# P5 row phase: interleaved row ownership (neighbouring waves on neighbouring rows at each step) instead of 16 consecutive rows per wave
# baseline (speedup 1.0000x reference)
.LBB0_569:
	s_or_b64 exec, exec, s[2:3]
	s_waitcnt lgkmcnt(0)
	v_mov_b32_e32 v0, v208
	s_barrier
	v_lshrrev_b32_e32 v168, 6, v208
	v_and_b32_e32 v169, 63, v208
	v_readfirstlane_b32 s42, v168
	v_lshlrev_b32_e32 v176, 4, v169
	v_lshlrev_b32_e32 v177, 3, v169
	s_nop 1
	s_add_u32 s1, s60, s42
	s_lshr_b32 s42, s1, 7
	s_lshl_b32 s42, s42, 11
	s_and_b32 s43, s1, 127
	s_or_b32 s42, s42, s43
	s_lshl_b32 s42, s42, 12
	s_add_u32 s2, s52, s42
	s_addc_u32 s3, s53, 0
	s_add_u32 s8, s90, s42
	s_addc_u32 s9, s91, 0
	s_add_u32 s8, s8, 0xec00000
	s_addc_u32 s9, s9, 0
	s_lshr_b32 s42, s42, 1
	s_add_u32 s6, s90, s42
	s_addc_u32 s7, s91, 0
	s_add_u32 s12, s6, 0x2400000
	s_addc_u32 s13, s7, 0
	s_add_u32 s6, s6, 0x16c00000
	s_addc_u32 s7, s7, 0
	s_lshr_b32 s42, s1, 7
	s_mul_i32 s42, s42, 0x3000
	s_add_u32 s38, s90, s42
	s_addc_u32 s39, s91, 0
	s_add_u32 s38, s38, 0x21b3000
	s_addc_u32 s39, s39, 0
	s_add_u32 s40, s38, 0x1000
	s_addc_u32 s41, s39, 0
	global_load_dwordx4 v[0:3], v176, s[64:65] offset:0
	global_load_dwordx4 v[4:7], v176, s[64:65] offset:1024
	global_load_dwordx4 v[8:11], v176, s[64:65] offset:2048
	global_load_dwordx4 v[12:15], v176, s[64:65] offset:3072
	global_load_dwordx4 v[16:19], v176, s[66:67] offset:0
	global_load_dwordx4 v[20:23], v176, s[66:67] offset:1024
	global_load_dwordx4 v[24:27], v176, s[66:67] offset:2048
	global_load_dwordx4 v[28:31], v176, s[66:67] offset:3072
	global_load_dwordx4 v[32:35], v176, s[40:41] offset:0
	global_load_dwordx4 v[36:39], v176, s[40:41] offset:1024
	global_load_dwordx4 v[40:43], v176, s[40:41] offset:2048
	global_load_dwordx4 v[44:47], v176, s[40:41] offset:3072
	global_load_dwordx4 v[48:51], v176, s[38:39] offset:0
	global_load_dwordx4 v[52:55], v176, s[38:39] offset:1024
	global_load_dwordx4 v[56:59], v176, s[38:39] offset:2048
	global_load_dwordx4 v[60:63], v176, s[38:39] offset:3072
	v_mov_b32_e32 v172, 0xba800000
	v_mov_b32_e32 v173, 0xba800000
	v_mov_b32_e32 v178, 0x3a800000
	v_mov_b32_e32 v179, 0x358637bd
	s_mov_b32 s44, 0x3fb504f3
	s_mov_b32 s45, 0x3fb504f3
	global_load_dwordx4 v[64:67], v176, s[2:3] offset:0
	global_load_dwordx4 v[68:71], v176, s[2:3] offset:1024
	global_load_dwordx4 v[72:75], v176, s[2:3] offset:2048
	global_load_dwordx4 v[76:79], v176, s[2:3] offset:3072
	global_load_dwordx2 v[112:113], v177, s[6:7] offset:0
	global_load_dwordx2 v[114:115], v177, s[6:7] offset:512
	global_load_dwordx2 v[116:117], v177, s[6:7] offset:1024
	global_load_dwordx2 v[118:119], v177, s[6:7] offset:1536
	s_add_u32 s2, s2, 0x80000
	s_addc_u32 s3, s3, 0
	s_add_u32 s6, s6, 0x40000
	s_addc_u32 s7, s7, 0
	global_load_dwordx4 v[80:83], v176, s[2:3] offset:0
	global_load_dwordx4 v[84:87], v176, s[2:3] offset:1024
	global_load_dwordx4 v[88:91], v176, s[2:3] offset:2048
	global_load_dwordx4 v[92:95], v176, s[2:3] offset:3072
	global_load_dwordx2 v[120:121], v177, s[6:7] offset:0
	global_load_dwordx2 v[122:123], v177, s[6:7] offset:512
	global_load_dwordx2 v[124:125], v177, s[6:7] offset:1024
	global_load_dwordx2 v[126:127], v177, s[6:7] offset:1536
	s_add_u32 s2, s2, 0x80000
	s_addc_u32 s3, s3, 0
	s_add_u32 s6, s6, 0x40000
	s_addc_u32 s7, s7, 0
	global_load_dwordx4 v[96:99], v176, s[2:3] offset:0
	global_load_dwordx4 v[100:103], v176, s[2:3] offset:1024
	global_load_dwordx4 v[104:107], v176, s[2:3] offset:2048
	global_load_dwordx4 v[108:111], v176, s[2:3] offset:3072
	global_load_dwordx2 v[128:129], v177, s[6:7] offset:0
	global_load_dwordx2 v[130:131], v177, s[6:7] offset:512
	global_load_dwordx2 v[132:133], v177, s[6:7] offset:1024
	global_load_dwordx2 v[134:135], v177, s[6:7] offset:1536
	s_add_u32 s2, s2, 0x80000
	s_addc_u32 s3, s3, 0
	s_add_u32 s6, s6, 0x40000
	s_addc_u32 s7, s7, 0
	s_waitcnt vmcnt(16)
	v_pk_add_f32 v[32:33], v[32:33], 1.0 op_sel_hi:[1,0]
	v_pk_add_f32 v[34:35], v[34:35], 1.0 op_sel_hi:[1,0]
	v_pk_add_f32 v[36:37], v[36:37], 1.0 op_sel_hi:[1,0]
	v_pk_add_f32 v[38:39], v[38:39], 1.0 op_sel_hi:[1,0]
	v_pk_add_f32 v[40:41], v[40:41], 1.0 op_sel_hi:[1,0]
	v_pk_add_f32 v[42:43], v[42:43], 1.0 op_sel_hi:[1,0]
	v_pk_add_f32 v[44:45], v[44:45], 1.0 op_sel_hi:[1,0]
	v_pk_add_f32 v[46:47], v[46:47], 1.0 op_sel_hi:[1,0]
	v_lshlrev_b32_e32 v136, 16, v112
	v_and_b32_e32 v137, 0xffff0000, v112
	v_lshlrev_b32_e32 v138, 16, v113
	v_and_b32_e32 v139, 0xffff0000, v113
	v_lshlrev_b32_e32 v140, 16, v114
	v_and_b32_e32 v141, 0xffff0000, v114
	v_lshlrev_b32_e32 v142, 16, v115
	v_and_b32_e32 v143, 0xffff0000, v115
	v_lshlrev_b32_e32 v144, 16, v116
	v_and_b32_e32 v145, 0xffff0000, v116
	v_lshlrev_b32_e32 v146, 16, v117
	v_and_b32_e32 v147, 0xffff0000, v117
	v_lshlrev_b32_e32 v148, 16, v118
	v_and_b32_e32 v149, 0xffff0000, v118
	v_lshlrev_b32_e32 v150, 16, v119
	v_and_b32_e32 v151, 0xffff0000, v119
	v_pk_fma_f32 v[136:137], v[64:65], s[44:45], v[136:137]
	v_pk_fma_f32 v[138:139], v[66:67], s[44:45], v[138:139]
	v_pk_fma_f32 v[140:141], v[68:69], s[44:45], v[140:141]
	v_pk_fma_f32 v[142:143], v[70:71], s[44:45], v[142:143]
	v_pk_fma_f32 v[144:145], v[72:73], s[44:45], v[144:145]
	v_pk_fma_f32 v[146:147], v[74:75], s[44:45], v[146:147]
	v_pk_fma_f32 v[148:149], v[76:77], s[44:45], v[148:149]
	v_pk_fma_f32 v[150:151], v[78:79], s[44:45], v[150:151]
	v_pk_add_f32 v[152:153], v[136:137], v[138:139]
	v_pk_add_f32 v[152:153], v[152:153], v[140:141]
	v_pk_add_f32 v[152:153], v[152:153], v[142:143]
	v_pk_add_f32 v[152:153], v[152:153], v[144:145]
	v_pk_add_f32 v[152:153], v[152:153], v[146:147]
	v_pk_add_f32 v[152:153], v[152:153], v[148:149]
	v_pk_add_f32 v[152:153], v[152:153], v[150:151]
	v_add_f32_e32 v170, v152, v153
	s_nop 1
	v_add_f32_dpp v168, v170, v170 quad_perm:[1,0,3,2] row_mask:0xf bank_mask:0xf
	s_nop 1
	v_add_f32_dpp v168, v168, v168 quad_perm:[2,3,0,1] row_mask:0xf bank_mask:0xf
	s_nop 1
	v_add_f32_dpp v168, v168, v168 row_half_mirror row_mask:0xf bank_mask:0xf
	s_nop 1
	v_add_f32_dpp v168, v168, v168 row_mirror row_mask:0xf bank_mask:0xf
	s_nop 1
	v_add_f32_dpp v168, v168, v168 row_bcast:15 row_mask:0xa bank_mask:0xf
	s_nop 1
	v_add_f32_dpp v168, v168, v168 row_bcast:31 row_mask:0xc bank_mask:0xf
	s_nop 1
	v_readlane_b32 s42, v168, 63
	s_nop 3
	s_mov_b32 s43, s42
	v_pk_fma_f32 v[136:137], s[42:43], v[172:173], v[136:137]
	v_pk_fma_f32 v[138:139], s[42:43], v[172:173], v[138:139]
	v_pk_fma_f32 v[140:141], s[42:43], v[172:173], v[140:141]
	v_pk_fma_f32 v[142:143], s[42:43], v[172:173], v[142:143]
	v_pk_fma_f32 v[144:145], s[42:43], v[172:173], v[144:145]
	v_pk_fma_f32 v[146:147], s[42:43], v[172:173], v[146:147]
	v_pk_fma_f32 v[148:149], s[42:43], v[172:173], v[148:149]
	v_pk_fma_f32 v[150:151], s[42:43], v[172:173], v[150:151]
	v_pk_mul_f32 v[152:153], v[136:137], v[136:137]
	v_pk_fma_f32 v[152:153], v[138:139], v[138:139], v[152:153]
	v_pk_fma_f32 v[152:153], v[140:141], v[140:141], v[152:153]
	v_pk_fma_f32 v[152:153], v[142:143], v[142:143], v[152:153]
	v_pk_fma_f32 v[152:153], v[144:145], v[144:145], v[152:153]
	v_pk_fma_f32 v[152:153], v[146:147], v[146:147], v[152:153]
	v_pk_fma_f32 v[152:153], v[148:149], v[148:149], v[152:153]
	v_pk_fma_f32 v[152:153], v[150:151], v[150:151], v[152:153]
	v_add_f32_e32 v170, v152, v153
	s_nop 1
	v_add_f32_dpp v168, v170, v170 quad_perm:[1,0,3,2] row_mask:0xf bank_mask:0xf
	s_nop 1
	v_add_f32_dpp v168, v168, v168 quad_perm:[2,3,0,1] row_mask:0xf bank_mask:0xf
	s_nop 1
	v_add_f32_dpp v168, v168, v168 row_half_mirror row_mask:0xf bank_mask:0xf
	s_nop 1
	v_add_f32_dpp v168, v168, v168 row_mirror row_mask:0xf bank_mask:0xf
	s_nop 1
	v_add_f32_dpp v168, v168, v168 row_bcast:15 row_mask:0xa bank_mask:0xf
	s_nop 1
	v_add_f32_dpp v168, v168, v168 row_bcast:31 row_mask:0xc bank_mask:0xf
	s_nop 1
	v_readlane_b32 s42, v168, 63
	s_nop 3
	v_fma_f32 v174, s42, v178, v179
	v_rsq_f32_e32 v174, v174
	s_nop 0
	v_pk_mul_f32 v[136:137], v[136:137], v[174:175] op_sel_hi:[1,0]
	v_pk_mul_f32 v[138:139], v[138:139], v[174:175] op_sel_hi:[1,0]
	v_pk_mul_f32 v[140:141], v[140:141], v[174:175] op_sel_hi:[1,0]
	v_pk_mul_f32 v[142:143], v[142:143], v[174:175] op_sel_hi:[1,0]
	v_pk_mul_f32 v[144:145], v[144:145], v[174:175] op_sel_hi:[1,0]
	v_pk_mul_f32 v[146:147], v[146:147], v[174:175] op_sel_hi:[1,0]
	v_pk_mul_f32 v[148:149], v[148:149], v[174:175] op_sel_hi:[1,0]
	v_pk_mul_f32 v[150:151], v[150:151], v[174:175] op_sel_hi:[1,0]
	v_pk_fma_f32 v[136:137], v[136:137], v[0:1], v[16:17]
	v_pk_fma_f32 v[138:139], v[138:139], v[2:3], v[18:19]
	v_pk_fma_f32 v[140:141], v[140:141], v[4:5], v[20:21]
	v_pk_fma_f32 v[142:143], v[142:143], v[6:7], v[22:23]
	v_pk_fma_f32 v[144:145], v[144:145], v[8:9], v[24:25]
	v_pk_fma_f32 v[146:147], v[146:147], v[10:11], v[26:27]
	v_pk_fma_f32 v[148:149], v[148:149], v[12:13], v[28:29]
	v_pk_fma_f32 v[150:151], v[150:151], v[14:15], v[30:31]
	global_store_dwordx4 v176, v[136:139], s[8:9] offset:0
	global_store_dwordx4 v176, v[140:143], s[8:9] offset:1024
	global_store_dwordx4 v176, v[144:147], s[8:9] offset:2048
	global_store_dwordx4 v176, v[148:151], s[8:9] offset:3072
	v_pk_add_f32 v[152:153], v[136:137], v[138:139]
	v_pk_add_f32 v[152:153], v[152:153], v[140:141]
	v_pk_add_f32 v[152:153], v[152:153], v[142:143]
	v_pk_add_f32 v[152:153], v[152:153], v[144:145]
	v_pk_add_f32 v[152:153], v[152:153], v[146:147]
	v_pk_add_f32 v[152:153], v[152:153], v[148:149]
	v_pk_add_f32 v[152:153], v[152:153], v[150:151]
	v_add_f32_e32 v170, v152, v153
	s_nop 1
	v_add_f32_dpp v168, v170, v170 quad_perm:[1,0,3,2] row_mask:0xf bank_mask:0xf
	s_nop 1
	v_add_f32_dpp v168, v168, v168 quad_perm:[2,3,0,1] row_mask:0xf bank_mask:0xf
	s_nop 1
	v_add_f32_dpp v168, v168, v168 row_half_mirror row_mask:0xf bank_mask:0xf
	s_nop 1
	v_add_f32_dpp v168, v168, v168 row_mirror row_mask:0xf bank_mask:0xf
	s_nop 1
	v_add_f32_dpp v168, v168, v168 row_bcast:15 row_mask:0xa bank_mask:0xf
	s_nop 1
	v_add_f32_dpp v168, v168, v168 row_bcast:31 row_mask:0xc bank_mask:0xf
	s_nop 1
	v_readlane_b32 s42, v168, 63
	s_nop 3
	s_mov_b32 s43, s42
	v_pk_fma_f32 v[136:137], s[42:43], v[172:173], v[136:137]
	v_pk_fma_f32 v[138:139], s[42:43], v[172:173], v[138:139]
	v_pk_fma_f32 v[140:141], s[42:43], v[172:173], v[140:141]
	v_pk_fma_f32 v[142:143], s[42:43], v[172:173], v[142:143]
	v_pk_fma_f32 v[144:145], s[42:43], v[172:173], v[144:145]
	v_pk_fma_f32 v[146:147], s[42:43], v[172:173], v[146:147]
	v_pk_fma_f32 v[148:149], s[42:43], v[172:173], v[148:149]
	v_pk_fma_f32 v[150:151], s[42:43], v[172:173], v[150:151]
	v_pk_mul_f32 v[152:153], v[136:137], v[136:137]
	v_pk_fma_f32 v[152:153], v[138:139], v[138:139], v[152:153]
	v_pk_fma_f32 v[152:153], v[140:141], v[140:141], v[152:153]
	v_pk_fma_f32 v[152:153], v[142:143], v[142:143], v[152:153]
	v_pk_fma_f32 v[152:153], v[144:145], v[144:145], v[152:153]
	v_pk_fma_f32 v[152:153], v[146:147], v[146:147], v[152:153]
	v_pk_fma_f32 v[152:153], v[148:149], v[148:149], v[152:153]
	v_pk_fma_f32 v[152:153], v[150:151], v[150:151], v[152:153]
	v_add_f32_e32 v170, v152, v153
	s_nop 1
	v_add_f32_dpp v168, v170, v170 quad_perm:[1,0,3,2] row_mask:0xf bank_mask:0xf
	s_nop 1
	v_add_f32_dpp v168, v168, v168 quad_perm:[2,3,0,1] row_mask:0xf bank_mask:0xf
	s_nop 1
	v_add_f32_dpp v168, v168, v168 row_half_mirror row_mask:0xf bank_mask:0xf
	s_nop 1
	v_add_f32_dpp v168, v168, v168 row_mirror row_mask:0xf bank_mask:0xf
	s_nop 1
	v_add_f32_dpp v168, v168, v168 row_bcast:15 row_mask:0xa bank_mask:0xf
	s_nop 1
	v_add_f32_dpp v168, v168, v168 row_bcast:31 row_mask:0xc bank_mask:0xf
	s_nop 1
	v_readlane_b32 s42, v168, 63
	s_nop 3
	v_fma_f32 v174, s42, v178, v179
	v_rsq_f32_e32 v174, v174
	s_nop 0
	v_pk_mul_f32 v[136:137], v[136:137], v[174:175] op_sel_hi:[1,0]
	v_pk_mul_f32 v[138:139], v[138:139], v[174:175] op_sel_hi:[1,0]
	v_pk_mul_f32 v[140:141], v[140:141], v[174:175] op_sel_hi:[1,0]
	v_pk_mul_f32 v[142:143], v[142:143], v[174:175] op_sel_hi:[1,0]
	v_pk_mul_f32 v[144:145], v[144:145], v[174:175] op_sel_hi:[1,0]
	v_pk_mul_f32 v[146:147], v[146:147], v[174:175] op_sel_hi:[1,0]
	v_pk_mul_f32 v[148:149], v[148:149], v[174:175] op_sel_hi:[1,0]
	v_pk_mul_f32 v[150:151], v[150:151], v[174:175] op_sel_hi:[1,0]
	v_pk_fma_f32 v[136:137], v[136:137], v[32:33], v[48:49]
	v_pk_fma_f32 v[138:139], v[138:139], v[34:35], v[50:51]
	v_pk_fma_f32 v[140:141], v[140:141], v[36:37], v[52:53]
	v_pk_fma_f32 v[142:143], v[142:143], v[38:39], v[54:55]
	v_pk_fma_f32 v[144:145], v[144:145], v[40:41], v[56:57]
	v_pk_fma_f32 v[146:147], v[146:147], v[42:43], v[58:59]
	v_pk_fma_f32 v[148:149], v[148:149], v[44:45], v[60:61]
	v_pk_fma_f32 v[150:151], v[150:151], v[46:47], v[62:63]
	v_cvt_pk_bf16_f32 v152, v136, v137
	v_cvt_pk_bf16_f32 v153, v138, v139
	v_cvt_pk_bf16_f32 v154, v140, v141
	v_cvt_pk_bf16_f32 v155, v142, v143
	v_cvt_pk_bf16_f32 v156, v144, v145
	v_cvt_pk_bf16_f32 v157, v146, v147
	v_cvt_pk_bf16_f32 v158, v148, v149
	v_cvt_pk_bf16_f32 v159, v150, v151
	global_store_dwordx2 v177, v[152:153], s[12:13] offset:0
	global_store_dwordx2 v177, v[154:155], s[12:13] offset:512
	global_store_dwordx2 v177, v[156:157], s[12:13] offset:1024
	global_store_dwordx2 v177, v[158:159], s[12:13] offset:1536
	s_add_u32 s8, s8, 0x80000
	s_addc_u32 s9, s9, 0
	s_add_u32 s12, s12, 0x40000
	s_addc_u32 s13, s13, 0
	global_load_dwordx4 v[64:67], v176, s[2:3] offset:0
	global_load_dwordx4 v[68:71], v176, s[2:3] offset:1024
	global_load_dwordx4 v[72:75], v176, s[2:3] offset:2048
	global_load_dwordx4 v[76:79], v176, s[2:3] offset:3072
	global_load_dwordx2 v[112:113], v177, s[6:7] offset:0
	global_load_dwordx2 v[114:115], v177, s[6:7] offset:512
	global_load_dwordx2 v[116:117], v177, s[6:7] offset:1024
	global_load_dwordx2 v[118:119], v177, s[6:7] offset:1536
	s_add_u32 s2, s2, 0x80000
	s_addc_u32 s3, s3, 0
	s_add_u32 s6, s6, 0x40000
	s_addc_u32 s7, s7, 0
	s_waitcnt vmcnt(24)
	v_lshlrev_b32_e32 v136, 16, v120
	v_and_b32_e32 v137, 0xffff0000, v120
	v_lshlrev_b32_e32 v138, 16, v121
	v_and_b32_e32 v139, 0xffff0000, v121
	v_lshlrev_b32_e32 v140, 16, v122
	v_and_b32_e32 v141, 0xffff0000, v122
	v_lshlrev_b32_e32 v142, 16, v123
	v_and_b32_e32 v143, 0xffff0000, v123
	v_lshlrev_b32_e32 v144, 16, v124
	v_and_b32_e32 v145, 0xffff0000, v124
	v_lshlrev_b32_e32 v146, 16, v125
	v_and_b32_e32 v147, 0xffff0000, v125
	v_lshlrev_b32_e32 v148, 16, v126
	v_and_b32_e32 v149, 0xffff0000, v126
	v_lshlrev_b32_e32 v150, 16, v127
	v_and_b32_e32 v151, 0xffff0000, v127
	v_pk_fma_f32 v[136:137], v[80:81], s[44:45], v[136:137]
	v_pk_fma_f32 v[138:139], v[82:83], s[44:45], v[138:139]
	v_pk_fma_f32 v[140:141], v[84:85], s[44:45], v[140:141]
	v_pk_fma_f32 v[142:143], v[86:87], s[44:45], v[142:143]
	v_pk_fma_f32 v[144:145], v[88:89], s[44:45], v[144:145]
	v_pk_fma_f32 v[146:147], v[90:91], s[44:45], v[146:147]
	v_pk_fma_f32 v[148:149], v[92:93], s[44:45], v[148:149]
	v_pk_fma_f32 v[150:151], v[94:95], s[44:45], v[150:151]
	v_pk_add_f32 v[152:153], v[136:137], v[138:139]
	v_pk_add_f32 v[152:153], v[152:153], v[140:141]
	v_pk_add_f32 v[152:153], v[152:153], v[142:143]
	v_pk_add_f32 v[152:153], v[152:153], v[144:145]
	v_pk_add_f32 v[152:153], v[152:153], v[146:147]
	v_pk_add_f32 v[152:153], v[152:153], v[148:149]
	v_pk_add_f32 v[152:153], v[152:153], v[150:151]
	v_add_f32_e32 v170, v152, v153
	s_nop 1
	v_add_f32_dpp v168, v170, v170 quad_perm:[1,0,3,2] row_mask:0xf bank_mask:0xf
	s_nop 1
	v_add_f32_dpp v168, v168, v168 quad_perm:[2,3,0,1] row_mask:0xf bank_mask:0xf
	s_nop 1
	v_add_f32_dpp v168, v168, v168 row_half_mirror row_mask:0xf bank_mask:0xf
	s_nop 1
	v_add_f32_dpp v168, v168, v168 row_mirror row_mask:0xf bank_mask:0xf
	s_nop 1
	v_add_f32_dpp v168, v168, v168 row_bcast:15 row_mask:0xa bank_mask:0xf
	s_nop 1
	v_add_f32_dpp v168, v168, v168 row_bcast:31 row_mask:0xc bank_mask:0xf
	s_nop 1
	v_readlane_b32 s42, v168, 63
	s_nop 3
	s_mov_b32 s43, s42
	v_pk_fma_f32 v[136:137], s[42:43], v[172:173], v[136:137]
	v_pk_fma_f32 v[138:139], s[42:43], v[172:173], v[138:139]
	v_pk_fma_f32 v[140:141], s[42:43], v[172:173], v[140:141]
	v_pk_fma_f32 v[142:143], s[42:43], v[172:173], v[142:143]
	v_pk_fma_f32 v[144:145], s[42:43], v[172:173], v[144:145]
	v_pk_fma_f32 v[146:147], s[42:43], v[172:173], v[146:147]
	v_pk_fma_f32 v[148:149], s[42:43], v[172:173], v[148:149]
	v_pk_fma_f32 v[150:151], s[42:43], v[172:173], v[150:151]
	v_pk_mul_f32 v[152:153], v[136:137], v[136:137]
	v_pk_fma_f32 v[152:153], v[138:139], v[138:139], v[152:153]
	v_pk_fma_f32 v[152:153], v[140:141], v[140:141], v[152:153]
	v_pk_fma_f32 v[152:153], v[142:143], v[142:143], v[152:153]
	v_pk_fma_f32 v[152:153], v[144:145], v[144:145], v[152:153]
	v_pk_fma_f32 v[152:153], v[146:147], v[146:147], v[152:153]
	v_pk_fma_f32 v[152:153], v[148:149], v[148:149], v[152:153]
	v_pk_fma_f32 v[152:153], v[150:151], v[150:151], v[152:153]
	v_add_f32_e32 v170, v152, v153
	s_nop 1
	v_add_f32_dpp v168, v170, v170 quad_perm:[1,0,3,2] row_mask:0xf bank_mask:0xf
	s_nop 1
	v_add_f32_dpp v168, v168, v168 quad_perm:[2,3,0,1] row_mask:0xf bank_mask:0xf
	s_nop 1
	v_add_f32_dpp v168, v168, v168 row_half_mirror row_mask:0xf bank_mask:0xf
	s_nop 1
	v_add_f32_dpp v168, v168, v168 row_mirror row_mask:0xf bank_mask:0xf
	s_nop 1
	v_add_f32_dpp v168, v168, v168 row_bcast:15 row_mask:0xa bank_mask:0xf
	s_nop 1
	v_add_f32_dpp v168, v168, v168 row_bcast:31 row_mask:0xc bank_mask:0xf
	s_nop 1
	v_readlane_b32 s42, v168, 63
	s_nop 3
	v_fma_f32 v174, s42, v178, v179
	v_rsq_f32_e32 v174, v174
	s_nop 0
	v_pk_mul_f32 v[136:137], v[136:137], v[174:175] op_sel_hi:[1,0]
	v_pk_mul_f32 v[138:139], v[138:139], v[174:175] op_sel_hi:[1,0]
	v_pk_mul_f32 v[140:141], v[140:141], v[174:175] op_sel_hi:[1,0]
	v_pk_mul_f32 v[142:143], v[142:143], v[174:175] op_sel_hi:[1,0]
	v_pk_mul_f32 v[144:145], v[144:145], v[174:175] op_sel_hi:[1,0]
	v_pk_mul_f32 v[146:147], v[146:147], v[174:175] op_sel_hi:[1,0]
	v_pk_mul_f32 v[148:149], v[148:149], v[174:175] op_sel_hi:[1,0]
	v_pk_mul_f32 v[150:151], v[150:151], v[174:175] op_sel_hi:[1,0]
	v_pk_fma_f32 v[136:137], v[136:137], v[0:1], v[16:17]
	v_pk_fma_f32 v[138:139], v[138:139], v[2:3], v[18:19]
	v_pk_fma_f32 v[140:141], v[140:141], v[4:5], v[20:21]
	v_pk_fma_f32 v[142:143], v[142:143], v[6:7], v[22:23]
	v_pk_fma_f32 v[144:145], v[144:145], v[8:9], v[24:25]
	v_pk_fma_f32 v[146:147], v[146:147], v[10:11], v[26:27]
	v_pk_fma_f32 v[148:149], v[148:149], v[12:13], v[28:29]
	v_pk_fma_f32 v[150:151], v[150:151], v[14:15], v[30:31]
	global_store_dwordx4 v176, v[136:139], s[8:9] offset:0
	global_store_dwordx4 v176, v[140:143], s[8:9] offset:1024
	global_store_dwordx4 v176, v[144:147], s[8:9] offset:2048
	global_store_dwordx4 v176, v[148:151], s[8:9] offset:3072
	v_pk_add_f32 v[152:153], v[136:137], v[138:139]
	v_pk_add_f32 v[152:153], v[152:153], v[140:141]
	v_pk_add_f32 v[152:153], v[152:153], v[142:143]
	v_pk_add_f32 v[152:153], v[152:153], v[144:145]
	v_pk_add_f32 v[152:153], v[152:153], v[146:147]
	v_pk_add_f32 v[152:153], v[152:153], v[148:149]
	v_pk_add_f32 v[152:153], v[152:153], v[150:151]
	v_add_f32_e32 v170, v152, v153
	s_nop 1
	v_add_f32_dpp v168, v170, v170 quad_perm:[1,0,3,2] row_mask:0xf bank_mask:0xf
	s_nop 1
	v_add_f32_dpp v168, v168, v168 quad_perm:[2,3,0,1] row_mask:0xf bank_mask:0xf
	s_nop 1
	v_add_f32_dpp v168, v168, v168 row_half_mirror row_mask:0xf bank_mask:0xf
	s_nop 1
	v_add_f32_dpp v168, v168, v168 row_mirror row_mask:0xf bank_mask:0xf
	s_nop 1
	v_add_f32_dpp v168, v168, v168 row_bcast:15 row_mask:0xa bank_mask:0xf
	s_nop 1
	v_add_f32_dpp v168, v168, v168 row_bcast:31 row_mask:0xc bank_mask:0xf
	s_nop 1
	v_readlane_b32 s42, v168, 63
	s_nop 3
	s_mov_b32 s43, s42
	v_pk_fma_f32 v[136:137], s[42:43], v[172:173], v[136:137]
	v_pk_fma_f32 v[138:139], s[42:43], v[172:173], v[138:139]
	v_pk_fma_f32 v[140:141], s[42:43], v[172:173], v[140:141]
	v_pk_fma_f32 v[142:143], s[42:43], v[172:173], v[142:143]
	v_pk_fma_f32 v[144:145], s[42:43], v[172:173], v[144:145]
	v_pk_fma_f32 v[146:147], s[42:43], v[172:173], v[146:147]
	v_pk_fma_f32 v[148:149], s[42:43], v[172:173], v[148:149]
	v_pk_fma_f32 v[150:151], s[42:43], v[172:173], v[150:151]
	v_pk_mul_f32 v[152:153], v[136:137], v[136:137]
	v_pk_fma_f32 v[152:153], v[138:139], v[138:139], v[152:153]
	v_pk_fma_f32 v[152:153], v[140:141], v[140:141], v[152:153]
	v_pk_fma_f32 v[152:153], v[142:143], v[142:143], v[152:153]
	v_pk_fma_f32 v[152:153], v[144:145], v[144:145], v[152:153]
	v_pk_fma_f32 v[152:153], v[146:147], v[146:147], v[152:153]
	v_pk_fma_f32 v[152:153], v[148:149], v[148:149], v[152:153]
	v_pk_fma_f32 v[152:153], v[150:151], v[150:151], v[152:153]
	v_add_f32_e32 v170, v152, v153
	s_nop 1
	v_add_f32_dpp v168, v170, v170 quad_perm:[1,0,3,2] row_mask:0xf bank_mask:0xf
	s_nop 1
	v_add_f32_dpp v168, v168, v168 quad_perm:[2,3,0,1] row_mask:0xf bank_mask:0xf
	s_nop 1
	v_add_f32_dpp v168, v168, v168 row_half_mirror row_mask:0xf bank_mask:0xf
	s_nop 1
	v_add_f32_dpp v168, v168, v168 row_mirror row_mask:0xf bank_mask:0xf
	s_nop 1
	v_add_f32_dpp v168, v168, v168 row_bcast:15 row_mask:0xa bank_mask:0xf
	s_nop 1
	v_add_f32_dpp v168, v168, v168 row_bcast:31 row_mask:0xc bank_mask:0xf
	s_nop 1
	v_readlane_b32 s42, v168, 63
	s_nop 3
	v_fma_f32 v174, s42, v178, v179
	v_rsq_f32_e32 v174, v174
	s_nop 0
	v_pk_mul_f32 v[136:137], v[136:137], v[174:175] op_sel_hi:[1,0]
	v_pk_mul_f32 v[138:139], v[138:139], v[174:175] op_sel_hi:[1,0]
	v_pk_mul_f32 v[140:141], v[140:141], v[174:175] op_sel_hi:[1,0]
	v_pk_mul_f32 v[142:143], v[142:143], v[174:175] op_sel_hi:[1,0]
	v_pk_mul_f32 v[144:145], v[144:145], v[174:175] op_sel_hi:[1,0]
	v_pk_mul_f32 v[146:147], v[146:147], v[174:175] op_sel_hi:[1,0]
	v_pk_mul_f32 v[148:149], v[148:149], v[174:175] op_sel_hi:[1,0]
	v_pk_mul_f32 v[150:151], v[150:151], v[174:175] op_sel_hi:[1,0]
	v_pk_fma_f32 v[136:137], v[136:137], v[32:33], v[48:49]
	v_pk_fma_f32 v[138:139], v[138:139], v[34:35], v[50:51]
	v_pk_fma_f32 v[140:141], v[140:141], v[36:37], v[52:53]
	v_pk_fma_f32 v[142:143], v[142:143], v[38:39], v[54:55]
	v_pk_fma_f32 v[144:145], v[144:145], v[40:41], v[56:57]
	v_pk_fma_f32 v[146:147], v[146:147], v[42:43], v[58:59]
	v_pk_fma_f32 v[148:149], v[148:149], v[44:45], v[60:61]
	v_pk_fma_f32 v[150:151], v[150:151], v[46:47], v[62:63]
	v_cvt_pk_bf16_f32 v152, v136, v137
	v_cvt_pk_bf16_f32 v153, v138, v139
	v_cvt_pk_bf16_f32 v154, v140, v141
	v_cvt_pk_bf16_f32 v155, v142, v143
	v_cvt_pk_bf16_f32 v156, v144, v145
	v_cvt_pk_bf16_f32 v157, v146, v147
	v_cvt_pk_bf16_f32 v158, v148, v149
	v_cvt_pk_bf16_f32 v159, v150, v151
	global_store_dwordx2 v177, v[152:153], s[12:13] offset:0
	global_store_dwordx2 v177, v[154:155], s[12:13] offset:512
	global_store_dwordx2 v177, v[156:157], s[12:13] offset:1024
	global_store_dwordx2 v177, v[158:159], s[12:13] offset:1536
	s_add_u32 s8, s8, 0x80000
	s_addc_u32 s9, s9, 0
	s_add_u32 s12, s12, 0x40000
	s_addc_u32 s13, s13, 0
	global_load_dwordx4 v[80:83], v176, s[2:3] offset:0
	global_load_dwordx4 v[84:87], v176, s[2:3] offset:1024
	global_load_dwordx4 v[88:91], v176, s[2:3] offset:2048
	global_load_dwordx4 v[92:95], v176, s[2:3] offset:3072
	global_load_dwordx2 v[120:121], v177, s[6:7] offset:0
	global_load_dwordx2 v[122:123], v177, s[6:7] offset:512
	global_load_dwordx2 v[124:125], v177, s[6:7] offset:1024
	global_load_dwordx2 v[126:127], v177, s[6:7] offset:1536
	s_add_u32 s2, s2, 0x80000
	s_addc_u32 s3, s3, 0
	s_add_u32 s6, s6, 0x40000
	s_addc_u32 s7, s7, 0
	s_waitcnt vmcnt(32)
	v_lshlrev_b32_e32 v136, 16, v128
	v_and_b32_e32 v137, 0xffff0000, v128
	v_lshlrev_b32_e32 v138, 16, v129
	v_and_b32_e32 v139, 0xffff0000, v129
	v_lshlrev_b32_e32 v140, 16, v130
	v_and_b32_e32 v141, 0xffff0000, v130
	v_lshlrev_b32_e32 v142, 16, v131
	v_and_b32_e32 v143, 0xffff0000, v131
	v_lshlrev_b32_e32 v144, 16, v132
	v_and_b32_e32 v145, 0xffff0000, v132
	v_lshlrev_b32_e32 v146, 16, v133
	v_and_b32_e32 v147, 0xffff0000, v133
	v_lshlrev_b32_e32 v148, 16, v134
	v_and_b32_e32 v149, 0xffff0000, v134
	v_lshlrev_b32_e32 v150, 16, v135
	v_and_b32_e32 v151, 0xffff0000, v135
	v_pk_fma_f32 v[136:137], v[96:97], s[44:45], v[136:137]
	v_pk_fma_f32 v[138:139], v[98:99], s[44:45], v[138:139]
	v_pk_fma_f32 v[140:141], v[100:101], s[44:45], v[140:141]
	v_pk_fma_f32 v[142:143], v[102:103], s[44:45], v[142:143]
	v_pk_fma_f32 v[144:145], v[104:105], s[44:45], v[144:145]
	v_pk_fma_f32 v[146:147], v[106:107], s[44:45], v[146:147]
	v_pk_fma_f32 v[148:149], v[108:109], s[44:45], v[148:149]
	v_pk_fma_f32 v[150:151], v[110:111], s[44:45], v[150:151]
	v_pk_add_f32 v[152:153], v[136:137], v[138:139]
	v_pk_add_f32 v[152:153], v[152:153], v[140:141]
	v_pk_add_f32 v[152:153], v[152:153], v[142:143]
	v_pk_add_f32 v[152:153], v[152:153], v[144:145]
	v_pk_add_f32 v[152:153], v[152:153], v[146:147]
	v_pk_add_f32 v[152:153], v[152:153], v[148:149]
	v_pk_add_f32 v[152:153], v[152:153], v[150:151]
	v_add_f32_e32 v170, v152, v153
	s_nop 1
	v_add_f32_dpp v168, v170, v170 quad_perm:[1,0,3,2] row_mask:0xf bank_mask:0xf
	s_nop 1
	v_add_f32_dpp v168, v168, v168 quad_perm:[2,3,0,1] row_mask:0xf bank_mask:0xf
	s_nop 1
	v_add_f32_dpp v168, v168, v168 row_half_mirror row_mask:0xf bank_mask:0xf
	s_nop 1
	v_add_f32_dpp v168, v168, v168 row_mirror row_mask:0xf bank_mask:0xf
	s_nop 1
	v_add_f32_dpp v168, v168, v168 row_bcast:15 row_mask:0xa bank_mask:0xf
	s_nop 1
	v_add_f32_dpp v168, v168, v168 row_bcast:31 row_mask:0xc bank_mask:0xf
	s_nop 1
	v_readlane_b32 s42, v168, 63
	s_nop 3
	s_mov_b32 s43, s42
	v_pk_fma_f32 v[136:137], s[42:43], v[172:173], v[136:137]
	v_pk_fma_f32 v[138:139], s[42:43], v[172:173], v[138:139]
	v_pk_fma_f32 v[140:141], s[42:43], v[172:173], v[140:141]
	v_pk_fma_f32 v[142:143], s[42:43], v[172:173], v[142:143]
	v_pk_fma_f32 v[144:145], s[42:43], v[172:173], v[144:145]
	v_pk_fma_f32 v[146:147], s[42:43], v[172:173], v[146:147]
	v_pk_fma_f32 v[148:149], s[42:43], v[172:173], v[148:149]
	v_pk_fma_f32 v[150:151], s[42:43], v[172:173], v[150:151]
	v_pk_mul_f32 v[152:153], v[136:137], v[136:137]
	v_pk_fma_f32 v[152:153], v[138:139], v[138:139], v[152:153]
	v_pk_fma_f32 v[152:153], v[140:141], v[140:141], v[152:153]
	v_pk_fma_f32 v[152:153], v[142:143], v[142:143], v[152:153]
	v_pk_fma_f32 v[152:153], v[144:145], v[144:145], v[152:153]
	v_pk_fma_f32 v[152:153], v[146:147], v[146:147], v[152:153]
	v_pk_fma_f32 v[152:153], v[148:149], v[148:149], v[152:153]
	v_pk_fma_f32 v[152:153], v[150:151], v[150:151], v[152:153]
	v_add_f32_e32 v170, v152, v153
	s_nop 1
	v_add_f32_dpp v168, v170, v170 quad_perm:[1,0,3,2] row_mask:0xf bank_mask:0xf
	s_nop 1
	v_add_f32_dpp v168, v168, v168 quad_perm:[2,3,0,1] row_mask:0xf bank_mask:0xf
	s_nop 1
	v_add_f32_dpp v168, v168, v168 row_half_mirror row_mask:0xf bank_mask:0xf
	s_nop 1
	v_add_f32_dpp v168, v168, v168 row_mirror row_mask:0xf bank_mask:0xf
	s_nop 1
	v_add_f32_dpp v168, v168, v168 row_bcast:15 row_mask:0xa bank_mask:0xf
	s_nop 1
	v_add_f32_dpp v168, v168, v168 row_bcast:31 row_mask:0xc bank_mask:0xf
	s_nop 1
	v_readlane_b32 s42, v168, 63
	s_nop 3
	v_fma_f32 v174, s42, v178, v179
	v_rsq_f32_e32 v174, v174
	s_nop 0
	v_pk_mul_f32 v[136:137], v[136:137], v[174:175] op_sel_hi:[1,0]
	v_pk_mul_f32 v[138:139], v[138:139], v[174:175] op_sel_hi:[1,0]
	v_pk_mul_f32 v[140:141], v[140:141], v[174:175] op_sel_hi:[1,0]
	v_pk_mul_f32 v[142:143], v[142:143], v[174:175] op_sel_hi:[1,0]
	v_pk_mul_f32 v[144:145], v[144:145], v[174:175] op_sel_hi:[1,0]
	v_pk_mul_f32 v[146:147], v[146:147], v[174:175] op_sel_hi:[1,0]
	v_pk_mul_f32 v[148:149], v[148:149], v[174:175] op_sel_hi:[1,0]
	v_pk_mul_f32 v[150:151], v[150:151], v[174:175] op_sel_hi:[1,0]
	v_pk_fma_f32 v[136:137], v[136:137], v[0:1], v[16:17]
	v_pk_fma_f32 v[138:139], v[138:139], v[2:3], v[18:19]
	v_pk_fma_f32 v[140:141], v[140:141], v[4:5], v[20:21]
	v_pk_fma_f32 v[142:143], v[142:143], v[6:7], v[22:23]
	v_pk_fma_f32 v[144:145], v[144:145], v[8:9], v[24:25]
	v_pk_fma_f32 v[146:147], v[146:147], v[10:11], v[26:27]
	v_pk_fma_f32 v[148:149], v[148:149], v[12:13], v[28:29]
	v_pk_fma_f32 v[150:151], v[150:151], v[14:15], v[30:31]
	global_store_dwordx4 v176, v[136:139], s[8:9] offset:0
	global_store_dwordx4 v176, v[140:143], s[8:9] offset:1024
	global_store_dwordx4 v176, v[144:147], s[8:9] offset:2048
	global_store_dwordx4 v176, v[148:151], s[8:9] offset:3072
	v_pk_add_f32 v[152:153], v[136:137], v[138:139]
	v_pk_add_f32 v[152:153], v[152:153], v[140:141]
	v_pk_add_f32 v[152:153], v[152:153], v[142:143]
	v_pk_add_f32 v[152:153], v[152:153], v[144:145]
	v_pk_add_f32 v[152:153], v[152:153], v[146:147]
	v_pk_add_f32 v[152:153], v[152:153], v[148:149]
	v_pk_add_f32 v[152:153], v[152:153], v[150:151]
	v_add_f32_e32 v170, v152, v153
	s_nop 1
	v_add_f32_dpp v168, v170, v170 quad_perm:[1,0,3,2] row_mask:0xf bank_mask:0xf
	s_nop 1
	v_add_f32_dpp v168, v168, v168 quad_perm:[2,3,0,1] row_mask:0xf bank_mask:0xf
	s_nop 1
	v_add_f32_dpp v168, v168, v168 row_half_mirror row_mask:0xf bank_mask:0xf
	s_nop 1
	v_add_f32_dpp v168, v168, v168 row_mirror row_mask:0xf bank_mask:0xf
	s_nop 1
	v_add_f32_dpp v168, v168, v168 row_bcast:15 row_mask:0xa bank_mask:0xf
	s_nop 1
	v_add_f32_dpp v168, v168, v168 row_bcast:31 row_mask:0xc bank_mask:0xf
	s_nop 1
	v_readlane_b32 s42, v168, 63
	s_nop 3
	s_mov_b32 s43, s42
	v_pk_fma_f32 v[136:137], s[42:43], v[172:173], v[136:137]
	v_pk_fma_f32 v[138:139], s[42:43], v[172:173], v[138:139]
	v_pk_fma_f32 v[140:141], s[42:43], v[172:173], v[140:141]
	v_pk_fma_f32 v[142:143], s[42:43], v[172:173], v[142:143]
	v_pk_fma_f32 v[144:145], s[42:43], v[172:173], v[144:145]
	v_pk_fma_f32 v[146:147], s[42:43], v[172:173], v[146:147]
	v_pk_fma_f32 v[148:149], s[42:43], v[172:173], v[148:149]
	v_pk_fma_f32 v[150:151], s[42:43], v[172:173], v[150:151]
	v_pk_mul_f32 v[152:153], v[136:137], v[136:137]
	v_pk_fma_f32 v[152:153], v[138:139], v[138:139], v[152:153]
	v_pk_fma_f32 v[152:153], v[140:141], v[140:141], v[152:153]
	v_pk_fma_f32 v[152:153], v[142:143], v[142:143], v[152:153]
	v_pk_fma_f32 v[152:153], v[144:145], v[144:145], v[152:153]
	v_pk_fma_f32 v[152:153], v[146:147], v[146:147], v[152:153]
	v_pk_fma_f32 v[152:153], v[148:149], v[148:149], v[152:153]
	v_pk_fma_f32 v[152:153], v[150:151], v[150:151], v[152:153]
	v_add_f32_e32 v170, v152, v153
	s_nop 1
	v_add_f32_dpp v168, v170, v170 quad_perm:[1,0,3,2] row_mask:0xf bank_mask:0xf
	s_nop 1
	v_add_f32_dpp v168, v168, v168 quad_perm:[2,3,0,1] row_mask:0xf bank_mask:0xf
	s_nop 1
	v_add_f32_dpp v168, v168, v168 row_half_mirror row_mask:0xf bank_mask:0xf
	s_nop 1
	v_add_f32_dpp v168, v168, v168 row_mirror row_mask:0xf bank_mask:0xf
	s_nop 1
	v_add_f32_dpp v168, v168, v168 row_bcast:15 row_mask:0xa bank_mask:0xf
	s_nop 1
	v_add_f32_dpp v168, v168, v168 row_bcast:31 row_mask:0xc bank_mask:0xf
	s_nop 1
	v_readlane_b32 s42, v168, 63
	s_nop 3
	v_fma_f32 v174, s42, v178, v179
	v_rsq_f32_e32 v174, v174
	s_nop 0
	v_pk_mul_f32 v[136:137], v[136:137], v[174:175] op_sel_hi:[1,0]
	v_pk_mul_f32 v[138:139], v[138:139], v[174:175] op_sel_hi:[1,0]
	v_pk_mul_f32 v[140:141], v[140:141], v[174:175] op_sel_hi:[1,0]
	v_pk_mul_f32 v[142:143], v[142:143], v[174:175] op_sel_hi:[1,0]
	v_pk_mul_f32 v[144:145], v[144:145], v[174:175] op_sel_hi:[1,0]
	v_pk_mul_f32 v[146:147], v[146:147], v[174:175] op_sel_hi:[1,0]
	v_pk_mul_f32 v[148:149], v[148:149], v[174:175] op_sel_hi:[1,0]
	v_pk_mul_f32 v[150:151], v[150:151], v[174:175] op_sel_hi:[1,0]
	v_pk_fma_f32 v[136:137], v[136:137], v[32:33], v[48:49]
	v_pk_fma_f32 v[138:139], v[138:139], v[34:35], v[50:51]
	v_pk_fma_f32 v[140:141], v[140:141], v[36:37], v[52:53]
	v_pk_fma_f32 v[142:143], v[142:143], v[38:39], v[54:55]
	v_pk_fma_f32 v[144:145], v[144:145], v[40:41], v[56:57]
	v_pk_fma_f32 v[146:147], v[146:147], v[42:43], v[58:59]
	v_pk_fma_f32 v[148:149], v[148:149], v[44:45], v[60:61]
	v_pk_fma_f32 v[150:151], v[150:151], v[46:47], v[62:63]
	v_cvt_pk_bf16_f32 v152, v136, v137
	v_cvt_pk_bf16_f32 v153, v138, v139
	v_cvt_pk_bf16_f32 v154, v140, v141
	v_cvt_pk_bf16_f32 v155, v142, v143
	v_cvt_pk_bf16_f32 v156, v144, v145
	v_cvt_pk_bf16_f32 v157, v146, v147
	v_cvt_pk_bf16_f32 v158, v148, v149
	v_cvt_pk_bf16_f32 v159, v150, v151
	global_store_dwordx2 v177, v[152:153], s[12:13] offset:0
	global_store_dwordx2 v177, v[154:155], s[12:13] offset:512
	global_store_dwordx2 v177, v[156:157], s[12:13] offset:1024
	global_store_dwordx2 v177, v[158:159], s[12:13] offset:1536
	s_add_u32 s8, s8, 0x80000
	s_addc_u32 s9, s9, 0
	s_add_u32 s12, s12, 0x40000
	s_addc_u32 s13, s13, 0
	global_load_dwordx4 v[96:99], v176, s[2:3] offset:0
	global_load_dwordx4 v[100:103], v176, s[2:3] offset:1024
	global_load_dwordx4 v[104:107], v176, s[2:3] offset:2048
	global_load_dwordx4 v[108:111], v176, s[2:3] offset:3072
	global_load_dwordx2 v[128:129], v177, s[6:7] offset:0
	global_load_dwordx2 v[130:131], v177, s[6:7] offset:512
	global_load_dwordx2 v[132:133], v177, s[6:7] offset:1024
	global_load_dwordx2 v[134:135], v177, s[6:7] offset:1536
	s_add_u32 s2, s2, 0x80000
	s_addc_u32 s3, s3, 0
	s_add_u32 s6, s6, 0x40000
	s_addc_u32 s7, s7, 0
	s_waitcnt vmcnt(32)
	v_lshlrev_b32_e32 v136, 16, v112
	v_and_b32_e32 v137, 0xffff0000, v112
	v_lshlrev_b32_e32 v138, 16, v113
	v_and_b32_e32 v139, 0xffff0000, v113
	v_lshlrev_b32_e32 v140, 16, v114
	v_and_b32_e32 v141, 0xffff0000, v114
	v_lshlrev_b32_e32 v142, 16, v115
	v_and_b32_e32 v143, 0xffff0000, v115
	v_lshlrev_b32_e32 v144, 16, v116
	v_and_b32_e32 v145, 0xffff0000, v116
	v_lshlrev_b32_e32 v146, 16, v117
	v_and_b32_e32 v147, 0xffff0000, v117
	v_lshlrev_b32_e32 v148, 16, v118
	v_and_b32_e32 v149, 0xffff0000, v118
	v_lshlrev_b32_e32 v150, 16, v119
	v_and_b32_e32 v151, 0xffff0000, v119
	v_pk_fma_f32 v[136:137], v[64:65], s[44:45], v[136:137]
	v_pk_fma_f32 v[138:139], v[66:67], s[44:45], v[138:139]
	v_pk_fma_f32 v[140:141], v[68:69], s[44:45], v[140:141]
	v_pk_fma_f32 v[142:143], v[70:71], s[44:45], v[142:143]
	v_pk_fma_f32 v[144:145], v[72:73], s[44:45], v[144:145]
	v_pk_fma_f32 v[146:147], v[74:75], s[44:45], v[146:147]
	v_pk_fma_f32 v[148:149], v[76:77], s[44:45], v[148:149]
	v_pk_fma_f32 v[150:151], v[78:79], s[44:45], v[150:151]
	v_pk_add_f32 v[152:153], v[136:137], v[138:139]
	v_pk_add_f32 v[152:153], v[152:153], v[140:141]
	v_pk_add_f32 v[152:153], v[152:153], v[142:143]
	v_pk_add_f32 v[152:153], v[152:153], v[144:145]
	v_pk_add_f32 v[152:153], v[152:153], v[146:147]
	v_pk_add_f32 v[152:153], v[152:153], v[148:149]
	v_pk_add_f32 v[152:153], v[152:153], v[150:151]
	v_add_f32_e32 v170, v152, v153
	s_nop 1
	v_add_f32_dpp v168, v170, v170 quad_perm:[1,0,3,2] row_mask:0xf bank_mask:0xf
	s_nop 1
	v_add_f32_dpp v168, v168, v168 quad_perm:[2,3,0,1] row_mask:0xf bank_mask:0xf
	s_nop 1
	v_add_f32_dpp v168, v168, v168 row_half_mirror row_mask:0xf bank_mask:0xf
	s_nop 1
	v_add_f32_dpp v168, v168, v168 row_mirror row_mask:0xf bank_mask:0xf
	s_nop 1
	v_add_f32_dpp v168, v168, v168 row_bcast:15 row_mask:0xa bank_mask:0xf
	s_nop 1
	v_add_f32_dpp v168, v168, v168 row_bcast:31 row_mask:0xc bank_mask:0xf
	s_nop 1
	v_readlane_b32 s42, v168, 63
	s_nop 3
	s_mov_b32 s43, s42
	v_pk_fma_f32 v[136:137], s[42:43], v[172:173], v[136:137]
	v_pk_fma_f32 v[138:139], s[42:43], v[172:173], v[138:139]
	v_pk_fma_f32 v[140:141], s[42:43], v[172:173], v[140:141]
	v_pk_fma_f32 v[142:143], s[42:43], v[172:173], v[142:143]
	v_pk_fma_f32 v[144:145], s[42:43], v[172:173], v[144:145]
	v_pk_fma_f32 v[146:147], s[42:43], v[172:173], v[146:147]
	v_pk_fma_f32 v[148:149], s[42:43], v[172:173], v[148:149]
	v_pk_fma_f32 v[150:151], s[42:43], v[172:173], v[150:151]
	v_pk_mul_f32 v[152:153], v[136:137], v[136:137]
	v_pk_fma_f32 v[152:153], v[138:139], v[138:139], v[152:153]
	v_pk_fma_f32 v[152:153], v[140:141], v[140:141], v[152:153]
	v_pk_fma_f32 v[152:153], v[142:143], v[142:143], v[152:153]
	v_pk_fma_f32 v[152:153], v[144:145], v[144:145], v[152:153]
	v_pk_fma_f32 v[152:153], v[146:147], v[146:147], v[152:153]
	v_pk_fma_f32 v[152:153], v[148:149], v[148:149], v[152:153]
	v_pk_fma_f32 v[152:153], v[150:151], v[150:151], v[152:153]
	v_add_f32_e32 v170, v152, v153
	s_nop 1
	v_add_f32_dpp v168, v170, v170 quad_perm:[1,0,3,2] row_mask:0xf bank_mask:0xf
	s_nop 1
	v_add_f32_dpp v168, v168, v168 quad_perm:[2,3,0,1] row_mask:0xf bank_mask:0xf
	s_nop 1
	v_add_f32_dpp v168, v168, v168 row_half_mirror row_mask:0xf bank_mask:0xf
	s_nop 1
	v_add_f32_dpp v168, v168, v168 row_mirror row_mask:0xf bank_mask:0xf
	s_nop 1
	v_add_f32_dpp v168, v168, v168 row_bcast:15 row_mask:0xa bank_mask:0xf
	s_nop 1
	v_add_f32_dpp v168, v168, v168 row_bcast:31 row_mask:0xc bank_mask:0xf
	s_nop 1
	v_readlane_b32 s42, v168, 63
	s_nop 3
	v_fma_f32 v174, s42, v178, v179
	v_rsq_f32_e32 v174, v174
	s_nop 0
	v_pk_mul_f32 v[136:137], v[136:137], v[174:175] op_sel_hi:[1,0]
	v_pk_mul_f32 v[138:139], v[138:139], v[174:175] op_sel_hi:[1,0]
	v_pk_mul_f32 v[140:141], v[140:141], v[174:175] op_sel_hi:[1,0]
	v_pk_mul_f32 v[142:143], v[142:143], v[174:175] op_sel_hi:[1,0]
	v_pk_mul_f32 v[144:145], v[144:145], v[174:175] op_sel_hi:[1,0]
	v_pk_mul_f32 v[146:147], v[146:147], v[174:175] op_sel_hi:[1,0]
	v_pk_mul_f32 v[148:149], v[148:149], v[174:175] op_sel_hi:[1,0]
	v_pk_mul_f32 v[150:151], v[150:151], v[174:175] op_sel_hi:[1,0]
	v_pk_fma_f32 v[136:137], v[136:137], v[0:1], v[16:17]
	v_pk_fma_f32 v[138:139], v[138:139], v[2:3], v[18:19]
	v_pk_fma_f32 v[140:141], v[140:141], v[4:5], v[20:21]
	v_pk_fma_f32 v[142:143], v[142:143], v[6:7], v[22:23]
	v_pk_fma_f32 v[144:145], v[144:145], v[8:9], v[24:25]
	v_pk_fma_f32 v[146:147], v[146:147], v[10:11], v[26:27]
	v_pk_fma_f32 v[148:149], v[148:149], v[12:13], v[28:29]
	v_pk_fma_f32 v[150:151], v[150:151], v[14:15], v[30:31]
	global_store_dwordx4 v176, v[136:139], s[8:9] offset:0
	global_store_dwordx4 v176, v[140:143], s[8:9] offset:1024
	global_store_dwordx4 v176, v[144:147], s[8:9] offset:2048
	global_store_dwordx4 v176, v[148:151], s[8:9] offset:3072
	v_pk_add_f32 v[152:153], v[136:137], v[138:139]
	v_pk_add_f32 v[152:153], v[152:153], v[140:141]
	v_pk_add_f32 v[152:153], v[152:153], v[142:143]
	v_pk_add_f32 v[152:153], v[152:153], v[144:145]
	v_pk_add_f32 v[152:153], v[152:153], v[146:147]
	v_pk_add_f32 v[152:153], v[152:153], v[148:149]
	v_pk_add_f32 v[152:153], v[152:153], v[150:151]
	v_add_f32_e32 v170, v152, v153
	s_nop 1
	v_add_f32_dpp v168, v170, v170 quad_perm:[1,0,3,2] row_mask:0xf bank_mask:0xf
	s_nop 1
	v_add_f32_dpp v168, v168, v168 quad_perm:[2,3,0,1] row_mask:0xf bank_mask:0xf
	s_nop 1
	v_add_f32_dpp v168, v168, v168 row_half_mirror row_mask:0xf bank_mask:0xf
	s_nop 1
	v_add_f32_dpp v168, v168, v168 row_mirror row_mask:0xf bank_mask:0xf
	s_nop 1
	v_add_f32_dpp v168, v168, v168 row_bcast:15 row_mask:0xa bank_mask:0xf
	s_nop 1
	v_add_f32_dpp v168, v168, v168 row_bcast:31 row_mask:0xc bank_mask:0xf
	s_nop 1
	v_readlane_b32 s42, v168, 63
	s_nop 3
	s_mov_b32 s43, s42
	v_pk_fma_f32 v[136:137], s[42:43], v[172:173], v[136:137]
	v_pk_fma_f32 v[138:139], s[42:43], v[172:173], v[138:139]
	v_pk_fma_f32 v[140:141], s[42:43], v[172:173], v[140:141]
	v_pk_fma_f32 v[142:143], s[42:43], v[172:173], v[142:143]
	v_pk_fma_f32 v[144:145], s[42:43], v[172:173], v[144:145]
	v_pk_fma_f32 v[146:147], s[42:43], v[172:173], v[146:147]
	v_pk_fma_f32 v[148:149], s[42:43], v[172:173], v[148:149]
	v_pk_fma_f32 v[150:151], s[42:43], v[172:173], v[150:151]
	v_pk_mul_f32 v[152:153], v[136:137], v[136:137]
	v_pk_fma_f32 v[152:153], v[138:139], v[138:139], v[152:153]
	v_pk_fma_f32 v[152:153], v[140:141], v[140:141], v[152:153]
	v_pk_fma_f32 v[152:153], v[142:143], v[142:143], v[152:153]
	v_pk_fma_f32 v[152:153], v[144:145], v[144:145], v[152:153]
	v_pk_fma_f32 v[152:153], v[146:147], v[146:147], v[152:153]
	v_pk_fma_f32 v[152:153], v[148:149], v[148:149], v[152:153]
	v_pk_fma_f32 v[152:153], v[150:151], v[150:151], v[152:153]
	v_add_f32_e32 v170, v152, v153
	s_nop 1
	v_add_f32_dpp v168, v170, v170 quad_perm:[1,0,3,2] row_mask:0xf bank_mask:0xf
	s_nop 1
	v_add_f32_dpp v168, v168, v168 quad_perm:[2,3,0,1] row_mask:0xf bank_mask:0xf
	s_nop 1
	v_add_f32_dpp v168, v168, v168 row_half_mirror row_mask:0xf bank_mask:0xf
	s_nop 1
	v_add_f32_dpp v168, v168, v168 row_mirror row_mask:0xf bank_mask:0xf
	s_nop 1
	v_add_f32_dpp v168, v168, v168 row_bcast:15 row_mask:0xa bank_mask:0xf
	s_nop 1
	v_add_f32_dpp v168, v168, v168 row_bcast:31 row_mask:0xc bank_mask:0xf
	s_nop 1
	v_readlane_b32 s42, v168, 63
	s_nop 3
	v_fma_f32 v174, s42, v178, v179
	v_rsq_f32_e32 v174, v174
	s_nop 0
	v_pk_mul_f32 v[136:137], v[136:137], v[174:175] op_sel_hi:[1,0]
	v_pk_mul_f32 v[138:139], v[138:139], v[174:175] op_sel_hi:[1,0]
	v_pk_mul_f32 v[140:141], v[140:141], v[174:175] op_sel_hi:[1,0]
	v_pk_mul_f32 v[142:143], v[142:143], v[174:175] op_sel_hi:[1,0]
	v_pk_mul_f32 v[144:145], v[144:145], v[174:175] op_sel_hi:[1,0]
	v_pk_mul_f32 v[146:147], v[146:147], v[174:175] op_sel_hi:[1,0]
	v_pk_mul_f32 v[148:149], v[148:149], v[174:175] op_sel_hi:[1,0]
	v_pk_mul_f32 v[150:151], v[150:151], v[174:175] op_sel_hi:[1,0]
	v_pk_fma_f32 v[136:137], v[136:137], v[32:33], v[48:49]
	v_pk_fma_f32 v[138:139], v[138:139], v[34:35], v[50:51]
	v_pk_fma_f32 v[140:141], v[140:141], v[36:37], v[52:53]
	v_pk_fma_f32 v[142:143], v[142:143], v[38:39], v[54:55]
	v_pk_fma_f32 v[144:145], v[144:145], v[40:41], v[56:57]
	v_pk_fma_f32 v[146:147], v[146:147], v[42:43], v[58:59]
	v_pk_fma_f32 v[148:149], v[148:149], v[44:45], v[60:61]
	v_pk_fma_f32 v[150:151], v[150:151], v[46:47], v[62:63]
	v_cvt_pk_bf16_f32 v152, v136, v137
	v_cvt_pk_bf16_f32 v153, v138, v139
	v_cvt_pk_bf16_f32 v154, v140, v141
	v_cvt_pk_bf16_f32 v155, v142, v143
	v_cvt_pk_bf16_f32 v156, v144, v145
	v_cvt_pk_bf16_f32 v157, v146, v147
	v_cvt_pk_bf16_f32 v158, v148, v149
	v_cvt_pk_bf16_f32 v159, v150, v151
	global_store_dwordx2 v177, v[152:153], s[12:13] offset:0
	global_store_dwordx2 v177, v[154:155], s[12:13] offset:512
	global_store_dwordx2 v177, v[156:157], s[12:13] offset:1024
	global_store_dwordx2 v177, v[158:159], s[12:13] offset:1536
	s_add_u32 s8, s8, 0x80000
	s_addc_u32 s9, s9, 0
	s_add_u32 s12, s12, 0x40000
	s_addc_u32 s13, s13, 0
	global_load_dwordx4 v[64:67], v176, s[2:3] offset:0
	global_load_dwordx4 v[68:71], v176, s[2:3] offset:1024
	global_load_dwordx4 v[72:75], v176, s[2:3] offset:2048
	global_load_dwordx4 v[76:79], v176, s[2:3] offset:3072
	global_load_dwordx2 v[112:113], v177, s[6:7] offset:0
	global_load_dwordx2 v[114:115], v177, s[6:7] offset:512
	global_load_dwordx2 v[116:117], v177, s[6:7] offset:1024
	global_load_dwordx2 v[118:119], v177, s[6:7] offset:1536
	s_add_u32 s2, s2, 0x80000
	s_addc_u32 s3, s3, 0
	s_add_u32 s6, s6, 0x40000
	s_addc_u32 s7, s7, 0
	s_waitcnt vmcnt(32)
	v_lshlrev_b32_e32 v136, 16, v120
	v_and_b32_e32 v137, 0xffff0000, v120
	v_lshlrev_b32_e32 v138, 16, v121
	v_and_b32_e32 v139, 0xffff0000, v121
	v_lshlrev_b32_e32 v140, 16, v122
	v_and_b32_e32 v141, 0xffff0000, v122
	v_lshlrev_b32_e32 v142, 16, v123
	v_and_b32_e32 v143, 0xffff0000, v123
	v_lshlrev_b32_e32 v144, 16, v124
	v_and_b32_e32 v145, 0xffff0000, v124
	v_lshlrev_b32_e32 v146, 16, v125
	v_and_b32_e32 v147, 0xffff0000, v125
	v_lshlrev_b32_e32 v148, 16, v126
	v_and_b32_e32 v149, 0xffff0000, v126
	v_lshlrev_b32_e32 v150, 16, v127
	v_and_b32_e32 v151, 0xffff0000, v127
	v_pk_fma_f32 v[136:137], v[80:81], s[44:45], v[136:137]
	v_pk_fma_f32 v[138:139], v[82:83], s[44:45], v[138:139]
	v_pk_fma_f32 v[140:141], v[84:85], s[44:45], v[140:141]
	v_pk_fma_f32 v[142:143], v[86:87], s[44:45], v[142:143]
	v_pk_fma_f32 v[144:145], v[88:89], s[44:45], v[144:145]
	v_pk_fma_f32 v[146:147], v[90:91], s[44:45], v[146:147]
	v_pk_fma_f32 v[148:149], v[92:93], s[44:45], v[148:149]
	v_pk_fma_f32 v[150:151], v[94:95], s[44:45], v[150:151]
	v_pk_add_f32 v[152:153], v[136:137], v[138:139]
	v_pk_add_f32 v[152:153], v[152:153], v[140:141]
	v_pk_add_f32 v[152:153], v[152:153], v[142:143]
	v_pk_add_f32 v[152:153], v[152:153], v[144:145]
	v_pk_add_f32 v[152:153], v[152:153], v[146:147]
	v_pk_add_f32 v[152:153], v[152:153], v[148:149]
	v_pk_add_f32 v[152:153], v[152:153], v[150:151]
	v_add_f32_e32 v170, v152, v153
	s_nop 1
	v_add_f32_dpp v168, v170, v170 quad_perm:[1,0,3,2] row_mask:0xf bank_mask:0xf
	s_nop 1
	v_add_f32_dpp v168, v168, v168 quad_perm:[2,3,0,1] row_mask:0xf bank_mask:0xf
	s_nop 1
	v_add_f32_dpp v168, v168, v168 row_half_mirror row_mask:0xf bank_mask:0xf
	s_nop 1
	v_add_f32_dpp v168, v168, v168 row_mirror row_mask:0xf bank_mask:0xf
	s_nop 1
	v_add_f32_dpp v168, v168, v168 row_bcast:15 row_mask:0xa bank_mask:0xf
	s_nop 1
	v_add_f32_dpp v168, v168, v168 row_bcast:31 row_mask:0xc bank_mask:0xf
	s_nop 1
	v_readlane_b32 s42, v168, 63
	s_nop 3
	s_mov_b32 s43, s42
	v_pk_fma_f32 v[136:137], s[42:43], v[172:173], v[136:137]
	v_pk_fma_f32 v[138:139], s[42:43], v[172:173], v[138:139]
	v_pk_fma_f32 v[140:141], s[42:43], v[172:173], v[140:141]
	v_pk_fma_f32 v[142:143], s[42:43], v[172:173], v[142:143]
	v_pk_fma_f32 v[144:145], s[42:43], v[172:173], v[144:145]
	v_pk_fma_f32 v[146:147], s[42:43], v[172:173], v[146:147]
	v_pk_fma_f32 v[148:149], s[42:43], v[172:173], v[148:149]
	v_pk_fma_f32 v[150:151], s[42:43], v[172:173], v[150:151]
	v_pk_mul_f32 v[152:153], v[136:137], v[136:137]
	v_pk_fma_f32 v[152:153], v[138:139], v[138:139], v[152:153]
	v_pk_fma_f32 v[152:153], v[140:141], v[140:141], v[152:153]
	v_pk_fma_f32 v[152:153], v[142:143], v[142:143], v[152:153]
	v_pk_fma_f32 v[152:153], v[144:145], v[144:145], v[152:153]
	v_pk_fma_f32 v[152:153], v[146:147], v[146:147], v[152:153]
	v_pk_fma_f32 v[152:153], v[148:149], v[148:149], v[152:153]
	v_pk_fma_f32 v[152:153], v[150:151], v[150:151], v[152:153]
	v_add_f32_e32 v170, v152, v153
	s_nop 1
	v_add_f32_dpp v168, v170, v170 quad_perm:[1,0,3,2] row_mask:0xf bank_mask:0xf
	s_nop 1
	v_add_f32_dpp v168, v168, v168 quad_perm:[2,3,0,1] row_mask:0xf bank_mask:0xf
	s_nop 1
	v_add_f32_dpp v168, v168, v168 row_half_mirror row_mask:0xf bank_mask:0xf
	s_nop 1
	v_add_f32_dpp v168, v168, v168 row_mirror row_mask:0xf bank_mask:0xf
	s_nop 1
	v_add_f32_dpp v168, v168, v168 row_bcast:15 row_mask:0xa bank_mask:0xf
	s_nop 1
	v_add_f32_dpp v168, v168, v168 row_bcast:31 row_mask:0xc bank_mask:0xf
	s_nop 1
	v_readlane_b32 s42, v168, 63
	s_nop 3
	v_fma_f32 v174, s42, v178, v179
	v_rsq_f32_e32 v174, v174
	s_nop 0
	v_pk_mul_f32 v[136:137], v[136:137], v[174:175] op_sel_hi:[1,0]
	v_pk_mul_f32 v[138:139], v[138:139], v[174:175] op_sel_hi:[1,0]
	v_pk_mul_f32 v[140:141], v[140:141], v[174:175] op_sel_hi:[1,0]
	v_pk_mul_f32 v[142:143], v[142:143], v[174:175] op_sel_hi:[1,0]
	v_pk_mul_f32 v[144:145], v[144:145], v[174:175] op_sel_hi:[1,0]
	v_pk_mul_f32 v[146:147], v[146:147], v[174:175] op_sel_hi:[1,0]
	v_pk_mul_f32 v[148:149], v[148:149], v[174:175] op_sel_hi:[1,0]
	v_pk_mul_f32 v[150:151], v[150:151], v[174:175] op_sel_hi:[1,0]
	v_pk_fma_f32 v[136:137], v[136:137], v[0:1], v[16:17]
	v_pk_fma_f32 v[138:139], v[138:139], v[2:3], v[18:19]
	v_pk_fma_f32 v[140:141], v[140:141], v[4:5], v[20:21]
	v_pk_fma_f32 v[142:143], v[142:143], v[6:7], v[22:23]
	v_pk_fma_f32 v[144:145], v[144:145], v[8:9], v[24:25]
	v_pk_fma_f32 v[146:147], v[146:147], v[10:11], v[26:27]
	v_pk_fma_f32 v[148:149], v[148:149], v[12:13], v[28:29]
	v_pk_fma_f32 v[150:151], v[150:151], v[14:15], v[30:31]
	global_store_dwordx4 v176, v[136:139], s[8:9] offset:0
	global_store_dwordx4 v176, v[140:143], s[8:9] offset:1024
	global_store_dwordx4 v176, v[144:147], s[8:9] offset:2048
	global_store_dwordx4 v176, v[148:151], s[8:9] offset:3072
	v_pk_add_f32 v[152:153], v[136:137], v[138:139]
	v_pk_add_f32 v[152:153], v[152:153], v[140:141]
	v_pk_add_f32 v[152:153], v[152:153], v[142:143]
	v_pk_add_f32 v[152:153], v[152:153], v[144:145]
	v_pk_add_f32 v[152:153], v[152:153], v[146:147]
	v_pk_add_f32 v[152:153], v[152:153], v[148:149]
	v_pk_add_f32 v[152:153], v[152:153], v[150:151]
	v_add_f32_e32 v170, v152, v153
	s_nop 1
	v_add_f32_dpp v168, v170, v170 quad_perm:[1,0,3,2] row_mask:0xf bank_mask:0xf
	s_nop 1
	v_add_f32_dpp v168, v168, v168 quad_perm:[2,3,0,1] row_mask:0xf bank_mask:0xf
	s_nop 1
	v_add_f32_dpp v168, v168, v168 row_half_mirror row_mask:0xf bank_mask:0xf
	s_nop 1
	v_add_f32_dpp v168, v168, v168 row_mirror row_mask:0xf bank_mask:0xf
	s_nop 1
	v_add_f32_dpp v168, v168, v168 row_bcast:15 row_mask:0xa bank_mask:0xf
	s_nop 1
	v_add_f32_dpp v168, v168, v168 row_bcast:31 row_mask:0xc bank_mask:0xf
	s_nop 1
	v_readlane_b32 s42, v168, 63
	s_nop 3
	s_mov_b32 s43, s42
	v_pk_fma_f32 v[136:137], s[42:43], v[172:173], v[136:137]
	v_pk_fma_f32 v[138:139], s[42:43], v[172:173], v[138:139]
	v_pk_fma_f32 v[140:141], s[42:43], v[172:173], v[140:141]
	v_pk_fma_f32 v[142:143], s[42:43], v[172:173], v[142:143]
	v_pk_fma_f32 v[144:145], s[42:43], v[172:173], v[144:145]
	v_pk_fma_f32 v[146:147], s[42:43], v[172:173], v[146:147]
	v_pk_fma_f32 v[148:149], s[42:43], v[172:173], v[148:149]
	v_pk_fma_f32 v[150:151], s[42:43], v[172:173], v[150:151]
	v_pk_mul_f32 v[152:153], v[136:137], v[136:137]
	v_pk_fma_f32 v[152:153], v[138:139], v[138:139], v[152:153]
	v_pk_fma_f32 v[152:153], v[140:141], v[140:141], v[152:153]
	v_pk_fma_f32 v[152:153], v[142:143], v[142:143], v[152:153]
	v_pk_fma_f32 v[152:153], v[144:145], v[144:145], v[152:153]
	v_pk_fma_f32 v[152:153], v[146:147], v[146:147], v[152:153]
	v_pk_fma_f32 v[152:153], v[148:149], v[148:149], v[152:153]
	v_pk_fma_f32 v[152:153], v[150:151], v[150:151], v[152:153]
	v_add_f32_e32 v170, v152, v153
	s_nop 1
	v_add_f32_dpp v168, v170, v170 quad_perm:[1,0,3,2] row_mask:0xf bank_mask:0xf
	s_nop 1
	v_add_f32_dpp v168, v168, v168 quad_perm:[2,3,0,1] row_mask:0xf bank_mask:0xf
	s_nop 1
	v_add_f32_dpp v168, v168, v168 row_half_mirror row_mask:0xf bank_mask:0xf
	s_nop 1
	v_add_f32_dpp v168, v168, v168 row_mirror row_mask:0xf bank_mask:0xf
	s_nop 1
	v_add_f32_dpp v168, v168, v168 row_bcast:15 row_mask:0xa bank_mask:0xf
	s_nop 1
	v_add_f32_dpp v168, v168, v168 row_bcast:31 row_mask:0xc bank_mask:0xf
	s_nop 1
	v_readlane_b32 s42, v168, 63
	s_nop 3
	v_fma_f32 v174, s42, v178, v179
	v_rsq_f32_e32 v174, v174
	s_nop 0
	v_pk_mul_f32 v[136:137], v[136:137], v[174:175] op_sel_hi:[1,0]
	v_pk_mul_f32 v[138:139], v[138:139], v[174:175] op_sel_hi:[1,0]
	v_pk_mul_f32 v[140:141], v[140:141], v[174:175] op_sel_hi:[1,0]
	v_pk_mul_f32 v[142:143], v[142:143], v[174:175] op_sel_hi:[1,0]
	v_pk_mul_f32 v[144:145], v[144:145], v[174:175] op_sel_hi:[1,0]
	v_pk_mul_f32 v[146:147], v[146:147], v[174:175] op_sel_hi:[1,0]
	v_pk_mul_f32 v[148:149], v[148:149], v[174:175] op_sel_hi:[1,0]
	v_pk_mul_f32 v[150:151], v[150:151], v[174:175] op_sel_hi:[1,0]
	v_pk_fma_f32 v[136:137], v[136:137], v[32:33], v[48:49]
	v_pk_fma_f32 v[138:139], v[138:139], v[34:35], v[50:51]
	v_pk_fma_f32 v[140:141], v[140:141], v[36:37], v[52:53]
	v_pk_fma_f32 v[142:143], v[142:143], v[38:39], v[54:55]
	v_pk_fma_f32 v[144:145], v[144:145], v[40:41], v[56:57]
	v_pk_fma_f32 v[146:147], v[146:147], v[42:43], v[58:59]
	v_pk_fma_f32 v[148:149], v[148:149], v[44:45], v[60:61]
	v_pk_fma_f32 v[150:151], v[150:151], v[46:47], v[62:63]
	v_cvt_pk_bf16_f32 v152, v136, v137
	v_cvt_pk_bf16_f32 v153, v138, v139
	v_cvt_pk_bf16_f32 v154, v140, v141
	v_cvt_pk_bf16_f32 v155, v142, v143
	v_cvt_pk_bf16_f32 v156, v144, v145
	v_cvt_pk_bf16_f32 v157, v146, v147
	v_cvt_pk_bf16_f32 v158, v148, v149
	v_cvt_pk_bf16_f32 v159, v150, v151
	global_store_dwordx2 v177, v[152:153], s[12:13] offset:0
	global_store_dwordx2 v177, v[154:155], s[12:13] offset:512
	global_store_dwordx2 v177, v[156:157], s[12:13] offset:1024
	global_store_dwordx2 v177, v[158:159], s[12:13] offset:1536
	s_add_u32 s8, s8, 0x80000
	s_addc_u32 s9, s9, 0
	s_add_u32 s12, s12, 0x40000
	s_addc_u32 s13, s13, 0
	global_load_dwordx4 v[80:83], v176, s[2:3] offset:0
	global_load_dwordx4 v[84:87], v176, s[2:3] offset:1024
	global_load_dwordx4 v[88:91], v176, s[2:3] offset:2048
	global_load_dwordx4 v[92:95], v176, s[2:3] offset:3072
	global_load_dwordx2 v[120:121], v177, s[6:7] offset:0
	global_load_dwordx2 v[122:123], v177, s[6:7] offset:512
	global_load_dwordx2 v[124:125], v177, s[6:7] offset:1024
	global_load_dwordx2 v[126:127], v177, s[6:7] offset:1536
	s_add_u32 s2, s2, 0x80000
	s_addc_u32 s3, s3, 0
	s_add_u32 s6, s6, 0x40000
	s_addc_u32 s7, s7, 0
	s_waitcnt vmcnt(32)
	v_lshlrev_b32_e32 v136, 16, v128
	v_and_b32_e32 v137, 0xffff0000, v128
	v_lshlrev_b32_e32 v138, 16, v129
	v_and_b32_e32 v139, 0xffff0000, v129
	v_lshlrev_b32_e32 v140, 16, v130
	v_and_b32_e32 v141, 0xffff0000, v130
	v_lshlrev_b32_e32 v142, 16, v131
	v_and_b32_e32 v143, 0xffff0000, v131
	v_lshlrev_b32_e32 v144, 16, v132
	v_and_b32_e32 v145, 0xffff0000, v132
	v_lshlrev_b32_e32 v146, 16, v133
	v_and_b32_e32 v147, 0xffff0000, v133
	v_lshlrev_b32_e32 v148, 16, v134
	v_and_b32_e32 v149, 0xffff0000, v134
	v_lshlrev_b32_e32 v150, 16, v135
	v_and_b32_e32 v151, 0xffff0000, v135
	v_pk_fma_f32 v[136:137], v[96:97], s[44:45], v[136:137]
	v_pk_fma_f32 v[138:139], v[98:99], s[44:45], v[138:139]
	v_pk_fma_f32 v[140:141], v[100:101], s[44:45], v[140:141]
	v_pk_fma_f32 v[142:143], v[102:103], s[44:45], v[142:143]
	v_pk_fma_f32 v[144:145], v[104:105], s[44:45], v[144:145]
	v_pk_fma_f32 v[146:147], v[106:107], s[44:45], v[146:147]
	v_pk_fma_f32 v[148:149], v[108:109], s[44:45], v[148:149]
	v_pk_fma_f32 v[150:151], v[110:111], s[44:45], v[150:151]
	v_pk_add_f32 v[152:153], v[136:137], v[138:139]
	v_pk_add_f32 v[152:153], v[152:153], v[140:141]
	v_pk_add_f32 v[152:153], v[152:153], v[142:143]
	v_pk_add_f32 v[152:153], v[152:153], v[144:145]
	v_pk_add_f32 v[152:153], v[152:153], v[146:147]
	v_pk_add_f32 v[152:153], v[152:153], v[148:149]
	v_pk_add_f32 v[152:153], v[152:153], v[150:151]
	v_add_f32_e32 v170, v152, v153
	s_nop 1
	v_add_f32_dpp v168, v170, v170 quad_perm:[1,0,3,2] row_mask:0xf bank_mask:0xf
	s_nop 1
	v_add_f32_dpp v168, v168, v168 quad_perm:[2,3,0,1] row_mask:0xf bank_mask:0xf
	s_nop 1
	v_add_f32_dpp v168, v168, v168 row_half_mirror row_mask:0xf bank_mask:0xf
	s_nop 1
	v_add_f32_dpp v168, v168, v168 row_mirror row_mask:0xf bank_mask:0xf
	s_nop 1
	v_add_f32_dpp v168, v168, v168 row_bcast:15 row_mask:0xa bank_mask:0xf
	s_nop 1
	v_add_f32_dpp v168, v168, v168 row_bcast:31 row_mask:0xc bank_mask:0xf
	s_nop 1
	v_readlane_b32 s42, v168, 63
	s_nop 3
	s_mov_b32 s43, s42
	v_pk_fma_f32 v[136:137], s[42:43], v[172:173], v[136:137]
	v_pk_fma_f32 v[138:139], s[42:43], v[172:173], v[138:139]
	v_pk_fma_f32 v[140:141], s[42:43], v[172:173], v[140:141]
	v_pk_fma_f32 v[142:143], s[42:43], v[172:173], v[142:143]
	v_pk_fma_f32 v[144:145], s[42:43], v[172:173], v[144:145]
	v_pk_fma_f32 v[146:147], s[42:43], v[172:173], v[146:147]
	v_pk_fma_f32 v[148:149], s[42:43], v[172:173], v[148:149]
	v_pk_fma_f32 v[150:151], s[42:43], v[172:173], v[150:151]
	v_pk_mul_f32 v[152:153], v[136:137], v[136:137]
	v_pk_fma_f32 v[152:153], v[138:139], v[138:139], v[152:153]
	v_pk_fma_f32 v[152:153], v[140:141], v[140:141], v[152:153]
	v_pk_fma_f32 v[152:153], v[142:143], v[142:143], v[152:153]
	v_pk_fma_f32 v[152:153], v[144:145], v[144:145], v[152:153]
	v_pk_fma_f32 v[152:153], v[146:147], v[146:147], v[152:153]
	v_pk_fma_f32 v[152:153], v[148:149], v[148:149], v[152:153]
	v_pk_fma_f32 v[152:153], v[150:151], v[150:151], v[152:153]
	v_add_f32_e32 v170, v152, v153
	s_nop 1
	v_add_f32_dpp v168, v170, v170 quad_perm:[1,0,3,2] row_mask:0xf bank_mask:0xf
	s_nop 1
	v_add_f32_dpp v168, v168, v168 quad_perm:[2,3,0,1] row_mask:0xf bank_mask:0xf
	s_nop 1
	v_add_f32_dpp v168, v168, v168 row_half_mirror row_mask:0xf bank_mask:0xf
	s_nop 1
	v_add_f32_dpp v168, v168, v168 row_mirror row_mask:0xf bank_mask:0xf
	s_nop 1
	v_add_f32_dpp v168, v168, v168 row_bcast:15 row_mask:0xa bank_mask:0xf
	s_nop 1
	v_add_f32_dpp v168, v168, v168 row_bcast:31 row_mask:0xc bank_mask:0xf
	s_nop 1
	v_readlane_b32 s42, v168, 63
	s_nop 3
	v_fma_f32 v174, s42, v178, v179
	v_rsq_f32_e32 v174, v174
	s_nop 0
	v_pk_mul_f32 v[136:137], v[136:137], v[174:175] op_sel_hi:[1,0]
	v_pk_mul_f32 v[138:139], v[138:139], v[174:175] op_sel_hi:[1,0]
	v_pk_mul_f32 v[140:141], v[140:141], v[174:175] op_sel_hi:[1,0]
	v_pk_mul_f32 v[142:143], v[142:143], v[174:175] op_sel_hi:[1,0]
	v_pk_mul_f32 v[144:145], v[144:145], v[174:175] op_sel_hi:[1,0]
	v_pk_mul_f32 v[146:147], v[146:147], v[174:175] op_sel_hi:[1,0]
	v_pk_mul_f32 v[148:149], v[148:149], v[174:175] op_sel_hi:[1,0]
	v_pk_mul_f32 v[150:151], v[150:151], v[174:175] op_sel_hi:[1,0]
	v_pk_fma_f32 v[136:137], v[136:137], v[0:1], v[16:17]
	v_pk_fma_f32 v[138:139], v[138:139], v[2:3], v[18:19]
	v_pk_fma_f32 v[140:141], v[140:141], v[4:5], v[20:21]
	v_pk_fma_f32 v[142:143], v[142:143], v[6:7], v[22:23]
	v_pk_fma_f32 v[144:145], v[144:145], v[8:9], v[24:25]
	v_pk_fma_f32 v[146:147], v[146:147], v[10:11], v[26:27]
	v_pk_fma_f32 v[148:149], v[148:149], v[12:13], v[28:29]
	v_pk_fma_f32 v[150:151], v[150:151], v[14:15], v[30:31]
	global_store_dwordx4 v176, v[136:139], s[8:9] offset:0
	global_store_dwordx4 v176, v[140:143], s[8:9] offset:1024
	global_store_dwordx4 v176, v[144:147], s[8:9] offset:2048
	global_store_dwordx4 v176, v[148:151], s[8:9] offset:3072
	v_pk_add_f32 v[152:153], v[136:137], v[138:139]
	v_pk_add_f32 v[152:153], v[152:153], v[140:141]
	v_pk_add_f32 v[152:153], v[152:153], v[142:143]
	v_pk_add_f32 v[152:153], v[152:153], v[144:145]
	v_pk_add_f32 v[152:153], v[152:153], v[146:147]
	v_pk_add_f32 v[152:153], v[152:153], v[148:149]
	v_pk_add_f32 v[152:153], v[152:153], v[150:151]
	v_add_f32_e32 v170, v152, v153
	s_nop 1
	v_add_f32_dpp v168, v170, v170 quad_perm:[1,0,3,2] row_mask:0xf bank_mask:0xf
	s_nop 1
	v_add_f32_dpp v168, v168, v168 quad_perm:[2,3,0,1] row_mask:0xf bank_mask:0xf
	s_nop 1
	v_add_f32_dpp v168, v168, v168 row_half_mirror row_mask:0xf bank_mask:0xf
	s_nop 1
	v_add_f32_dpp v168, v168, v168 row_mirror row_mask:0xf bank_mask:0xf
	s_nop 1
	v_add_f32_dpp v168, v168, v168 row_bcast:15 row_mask:0xa bank_mask:0xf
	s_nop 1
	v_add_f32_dpp v168, v168, v168 row_bcast:31 row_mask:0xc bank_mask:0xf
	s_nop 1
	v_readlane_b32 s42, v168, 63
	s_nop 3
	s_mov_b32 s43, s42
	v_pk_fma_f32 v[136:137], s[42:43], v[172:173], v[136:137]
	v_pk_fma_f32 v[138:139], s[42:43], v[172:173], v[138:139]
	v_pk_fma_f32 v[140:141], s[42:43], v[172:173], v[140:141]
	v_pk_fma_f32 v[142:143], s[42:43], v[172:173], v[142:143]
	v_pk_fma_f32 v[144:145], s[42:43], v[172:173], v[144:145]
	v_pk_fma_f32 v[146:147], s[42:43], v[172:173], v[146:147]
	v_pk_fma_f32 v[148:149], s[42:43], v[172:173], v[148:149]
	v_pk_fma_f32 v[150:151], s[42:43], v[172:173], v[150:151]
	v_pk_mul_f32 v[152:153], v[136:137], v[136:137]
	v_pk_fma_f32 v[152:153], v[138:139], v[138:139], v[152:153]
	v_pk_fma_f32 v[152:153], v[140:141], v[140:141], v[152:153]
	v_pk_fma_f32 v[152:153], v[142:143], v[142:143], v[152:153]
	v_pk_fma_f32 v[152:153], v[144:145], v[144:145], v[152:153]
	v_pk_fma_f32 v[152:153], v[146:147], v[146:147], v[152:153]
	v_pk_fma_f32 v[152:153], v[148:149], v[148:149], v[152:153]
	v_pk_fma_f32 v[152:153], v[150:151], v[150:151], v[152:153]
	v_add_f32_e32 v170, v152, v153
	s_nop 1
	v_add_f32_dpp v168, v170, v170 quad_perm:[1,0,3,2] row_mask:0xf bank_mask:0xf
	s_nop 1
	v_add_f32_dpp v168, v168, v168 quad_perm:[2,3,0,1] row_mask:0xf bank_mask:0xf
	s_nop 1
	v_add_f32_dpp v168, v168, v168 row_half_mirror row_mask:0xf bank_mask:0xf
	s_nop 1
	v_add_f32_dpp v168, v168, v168 row_mirror row_mask:0xf bank_mask:0xf
	s_nop 1
	v_add_f32_dpp v168, v168, v168 row_bcast:15 row_mask:0xa bank_mask:0xf
	s_nop 1
	v_add_f32_dpp v168, v168, v168 row_bcast:31 row_mask:0xc bank_mask:0xf
	s_nop 1
	v_readlane_b32 s42, v168, 63
	s_nop 3
	v_fma_f32 v174, s42, v178, v179
	v_rsq_f32_e32 v174, v174
	s_nop 0
	v_pk_mul_f32 v[136:137], v[136:137], v[174:175] op_sel_hi:[1,0]
	v_pk_mul_f32 v[138:139], v[138:139], v[174:175] op_sel_hi:[1,0]
	v_pk_mul_f32 v[140:141], v[140:141], v[174:175] op_sel_hi:[1,0]
	v_pk_mul_f32 v[142:143], v[142:143], v[174:175] op_sel_hi:[1,0]
	v_pk_mul_f32 v[144:145], v[144:145], v[174:175] op_sel_hi:[1,0]
	v_pk_mul_f32 v[146:147], v[146:147], v[174:175] op_sel_hi:[1,0]
	v_pk_mul_f32 v[148:149], v[148:149], v[174:175] op_sel_hi:[1,0]
	v_pk_mul_f32 v[150:151], v[150:151], v[174:175] op_sel_hi:[1,0]
	v_pk_fma_f32 v[136:137], v[136:137], v[32:33], v[48:49]
	v_pk_fma_f32 v[138:139], v[138:139], v[34:35], v[50:51]
	v_pk_fma_f32 v[140:141], v[140:141], v[36:37], v[52:53]
	v_pk_fma_f32 v[142:143], v[142:143], v[38:39], v[54:55]
	v_pk_fma_f32 v[144:145], v[144:145], v[40:41], v[56:57]
	v_pk_fma_f32 v[146:147], v[146:147], v[42:43], v[58:59]
	v_pk_fma_f32 v[148:149], v[148:149], v[44:45], v[60:61]
	v_pk_fma_f32 v[150:151], v[150:151], v[46:47], v[62:63]
	v_cvt_pk_bf16_f32 v152, v136, v137
	v_cvt_pk_bf16_f32 v153, v138, v139
	v_cvt_pk_bf16_f32 v154, v140, v141
	v_cvt_pk_bf16_f32 v155, v142, v143
	v_cvt_pk_bf16_f32 v156, v144, v145
	v_cvt_pk_bf16_f32 v157, v146, v147
	v_cvt_pk_bf16_f32 v158, v148, v149
	v_cvt_pk_bf16_f32 v159, v150, v151
	global_store_dwordx2 v177, v[152:153], s[12:13] offset:0
	global_store_dwordx2 v177, v[154:155], s[12:13] offset:512
	global_store_dwordx2 v177, v[156:157], s[12:13] offset:1024
	global_store_dwordx2 v177, v[158:159], s[12:13] offset:1536
	s_add_u32 s8, s8, 0x80000
	s_addc_u32 s9, s9, 0
	s_add_u32 s12, s12, 0x40000
	s_addc_u32 s13, s13, 0
	global_load_dwordx4 v[96:99], v176, s[2:3] offset:0
	global_load_dwordx4 v[100:103], v176, s[2:3] offset:1024
	global_load_dwordx4 v[104:107], v176, s[2:3] offset:2048
	global_load_dwordx4 v[108:111], v176, s[2:3] offset:3072
	global_load_dwordx2 v[128:129], v177, s[6:7] offset:0
	global_load_dwordx2 v[130:131], v177, s[6:7] offset:512
	global_load_dwordx2 v[132:133], v177, s[6:7] offset:1024
	global_load_dwordx2 v[134:135], v177, s[6:7] offset:1536
	s_add_u32 s2, s2, 0x80000
	s_addc_u32 s3, s3, 0
	s_add_u32 s6, s6, 0x40000
	s_addc_u32 s7, s7, 0
	s_waitcnt vmcnt(32)
	v_lshlrev_b32_e32 v136, 16, v112
	v_and_b32_e32 v137, 0xffff0000, v112
	v_lshlrev_b32_e32 v138, 16, v113
	v_and_b32_e32 v139, 0xffff0000, v113
	v_lshlrev_b32_e32 v140, 16, v114
	v_and_b32_e32 v141, 0xffff0000, v114
	v_lshlrev_b32_e32 v142, 16, v115
	v_and_b32_e32 v143, 0xffff0000, v115
	v_lshlrev_b32_e32 v144, 16, v116
	v_and_b32_e32 v145, 0xffff0000, v116
	v_lshlrev_b32_e32 v146, 16, v117
	v_and_b32_e32 v147, 0xffff0000, v117
	v_lshlrev_b32_e32 v148, 16, v118
	v_and_b32_e32 v149, 0xffff0000, v118
	v_lshlrev_b32_e32 v150, 16, v119
	v_and_b32_e32 v151, 0xffff0000, v119
	v_pk_fma_f32 v[136:137], v[64:65], s[44:45], v[136:137]
	v_pk_fma_f32 v[138:139], v[66:67], s[44:45], v[138:139]
	v_pk_fma_f32 v[140:141], v[68:69], s[44:45], v[140:141]
	v_pk_fma_f32 v[142:143], v[70:71], s[44:45], v[142:143]
	v_pk_fma_f32 v[144:145], v[72:73], s[44:45], v[144:145]
	v_pk_fma_f32 v[146:147], v[74:75], s[44:45], v[146:147]
	v_pk_fma_f32 v[148:149], v[76:77], s[44:45], v[148:149]
	v_pk_fma_f32 v[150:151], v[78:79], s[44:45], v[150:151]
	v_pk_add_f32 v[152:153], v[136:137], v[138:139]
	v_pk_add_f32 v[152:153], v[152:153], v[140:141]
	v_pk_add_f32 v[152:153], v[152:153], v[142:143]
	v_pk_add_f32 v[152:153], v[152:153], v[144:145]
	v_pk_add_f32 v[152:153], v[152:153], v[146:147]
	v_pk_add_f32 v[152:153], v[152:153], v[148:149]
	v_pk_add_f32 v[152:153], v[152:153], v[150:151]
	v_add_f32_e32 v170, v152, v153
	s_nop 1
	v_add_f32_dpp v168, v170, v170 quad_perm:[1,0,3,2] row_mask:0xf bank_mask:0xf
	s_nop 1
	v_add_f32_dpp v168, v168, v168 quad_perm:[2,3,0,1] row_mask:0xf bank_mask:0xf
	s_nop 1
	v_add_f32_dpp v168, v168, v168 row_half_mirror row_mask:0xf bank_mask:0xf
	s_nop 1
	v_add_f32_dpp v168, v168, v168 row_mirror row_mask:0xf bank_mask:0xf
	s_nop 1
	v_add_f32_dpp v168, v168, v168 row_bcast:15 row_mask:0xa bank_mask:0xf
	s_nop 1
	v_add_f32_dpp v168, v168, v168 row_bcast:31 row_mask:0xc bank_mask:0xf
	s_nop 1
	v_readlane_b32 s42, v168, 63
	s_nop 3
	s_mov_b32 s43, s42
	v_pk_fma_f32 v[136:137], s[42:43], v[172:173], v[136:137]
	v_pk_fma_f32 v[138:139], s[42:43], v[172:173], v[138:139]
	v_pk_fma_f32 v[140:141], s[42:43], v[172:173], v[140:141]
	v_pk_fma_f32 v[142:143], s[42:43], v[172:173], v[142:143]
	v_pk_fma_f32 v[144:145], s[42:43], v[172:173], v[144:145]
	v_pk_fma_f32 v[146:147], s[42:43], v[172:173], v[146:147]
	v_pk_fma_f32 v[148:149], s[42:43], v[172:173], v[148:149]
	v_pk_fma_f32 v[150:151], s[42:43], v[172:173], v[150:151]
	v_pk_mul_f32 v[152:153], v[136:137], v[136:137]
	v_pk_fma_f32 v[152:153], v[138:139], v[138:139], v[152:153]
	v_pk_fma_f32 v[152:153], v[140:141], v[140:141], v[152:153]
	v_pk_fma_f32 v[152:153], v[142:143], v[142:143], v[152:153]
	v_pk_fma_f32 v[152:153], v[144:145], v[144:145], v[152:153]
	v_pk_fma_f32 v[152:153], v[146:147], v[146:147], v[152:153]
	v_pk_fma_f32 v[152:153], v[148:149], v[148:149], v[152:153]
	v_pk_fma_f32 v[152:153], v[150:151], v[150:151], v[152:153]
	v_add_f32_e32 v170, v152, v153
	s_nop 1
	v_add_f32_dpp v168, v170, v170 quad_perm:[1,0,3,2] row_mask:0xf bank_mask:0xf
	s_nop 1
	v_add_f32_dpp v168, v168, v168 quad_perm:[2,3,0,1] row_mask:0xf bank_mask:0xf
	s_nop 1
	v_add_f32_dpp v168, v168, v168 row_half_mirror row_mask:0xf bank_mask:0xf
	s_nop 1
	v_add_f32_dpp v168, v168, v168 row_mirror row_mask:0xf bank_mask:0xf
	s_nop 1
	v_add_f32_dpp v168, v168, v168 row_bcast:15 row_mask:0xa bank_mask:0xf
	s_nop 1
	v_add_f32_dpp v168, v168, v168 row_bcast:31 row_mask:0xc bank_mask:0xf
	s_nop 1
	v_readlane_b32 s42, v168, 63
	s_nop 3
	v_fma_f32 v174, s42, v178, v179
	v_rsq_f32_e32 v174, v174
	s_nop 0
	v_pk_mul_f32 v[136:137], v[136:137], v[174:175] op_sel_hi:[1,0]
	v_pk_mul_f32 v[138:139], v[138:139], v[174:175] op_sel_hi:[1,0]
	v_pk_mul_f32 v[140:141], v[140:141], v[174:175] op_sel_hi:[1,0]
	v_pk_mul_f32 v[142:143], v[142:143], v[174:175] op_sel_hi:[1,0]
	v_pk_mul_f32 v[144:145], v[144:145], v[174:175] op_sel_hi:[1,0]
	v_pk_mul_f32 v[146:147], v[146:147], v[174:175] op_sel_hi:[1,0]
	v_pk_mul_f32 v[148:149], v[148:149], v[174:175] op_sel_hi:[1,0]
	v_pk_mul_f32 v[150:151], v[150:151], v[174:175] op_sel_hi:[1,0]
	v_pk_fma_f32 v[136:137], v[136:137], v[0:1], v[16:17]
	v_pk_fma_f32 v[138:139], v[138:139], v[2:3], v[18:19]
	v_pk_fma_f32 v[140:141], v[140:141], v[4:5], v[20:21]
	v_pk_fma_f32 v[142:143], v[142:143], v[6:7], v[22:23]
	v_pk_fma_f32 v[144:145], v[144:145], v[8:9], v[24:25]
	v_pk_fma_f32 v[146:147], v[146:147], v[10:11], v[26:27]
	v_pk_fma_f32 v[148:149], v[148:149], v[12:13], v[28:29]
	v_pk_fma_f32 v[150:151], v[150:151], v[14:15], v[30:31]
	global_store_dwordx4 v176, v[136:139], s[8:9] offset:0
	global_store_dwordx4 v176, v[140:143], s[8:9] offset:1024
	global_store_dwordx4 v176, v[144:147], s[8:9] offset:2048
	global_store_dwordx4 v176, v[148:151], s[8:9] offset:3072
	v_pk_add_f32 v[152:153], v[136:137], v[138:139]
	v_pk_add_f32 v[152:153], v[152:153], v[140:141]
	v_pk_add_f32 v[152:153], v[152:153], v[142:143]
	v_pk_add_f32 v[152:153], v[152:153], v[144:145]
	v_pk_add_f32 v[152:153], v[152:153], v[146:147]
	v_pk_add_f32 v[152:153], v[152:153], v[148:149]
	v_pk_add_f32 v[152:153], v[152:153], v[150:151]
	v_add_f32_e32 v170, v152, v153
	s_nop 1
	v_add_f32_dpp v168, v170, v170 quad_perm:[1,0,3,2] row_mask:0xf bank_mask:0xf
	s_nop 1
	v_add_f32_dpp v168, v168, v168 quad_perm:[2,3,0,1] row_mask:0xf bank_mask:0xf
	s_nop 1
	v_add_f32_dpp v168, v168, v168 row_half_mirror row_mask:0xf bank_mask:0xf
	s_nop 1
	v_add_f32_dpp v168, v168, v168 row_mirror row_mask:0xf bank_mask:0xf
	s_nop 1
	v_add_f32_dpp v168, v168, v168 row_bcast:15 row_mask:0xa bank_mask:0xf
	s_nop 1
	v_add_f32_dpp v168, v168, v168 row_bcast:31 row_mask:0xc bank_mask:0xf
	s_nop 1
	v_readlane_b32 s42, v168, 63
	s_nop 3
	s_mov_b32 s43, s42
	v_pk_fma_f32 v[136:137], s[42:43], v[172:173], v[136:137]
	v_pk_fma_f32 v[138:139], s[42:43], v[172:173], v[138:139]
	v_pk_fma_f32 v[140:141], s[42:43], v[172:173], v[140:141]
	v_pk_fma_f32 v[142:143], s[42:43], v[172:173], v[142:143]
	v_pk_fma_f32 v[144:145], s[42:43], v[172:173], v[144:145]
	v_pk_fma_f32 v[146:147], s[42:43], v[172:173], v[146:147]
	v_pk_fma_f32 v[148:149], s[42:43], v[172:173], v[148:149]
	v_pk_fma_f32 v[150:151], s[42:43], v[172:173], v[150:151]
	v_pk_mul_f32 v[152:153], v[136:137], v[136:137]
	v_pk_fma_f32 v[152:153], v[138:139], v[138:139], v[152:153]
	v_pk_fma_f32 v[152:153], v[140:141], v[140:141], v[152:153]
	v_pk_fma_f32 v[152:153], v[142:143], v[142:143], v[152:153]
	v_pk_fma_f32 v[152:153], v[144:145], v[144:145], v[152:153]
	v_pk_fma_f32 v[152:153], v[146:147], v[146:147], v[152:153]
	v_pk_fma_f32 v[152:153], v[148:149], v[148:149], v[152:153]
	v_pk_fma_f32 v[152:153], v[150:151], v[150:151], v[152:153]
	v_add_f32_e32 v170, v152, v153
	s_nop 1
	v_add_f32_dpp v168, v170, v170 quad_perm:[1,0,3,2] row_mask:0xf bank_mask:0xf
	s_nop 1
	v_add_f32_dpp v168, v168, v168 quad_perm:[2,3,0,1] row_mask:0xf bank_mask:0xf
	s_nop 1
	v_add_f32_dpp v168, v168, v168 row_half_mirror row_mask:0xf bank_mask:0xf
	s_nop 1
	v_add_f32_dpp v168, v168, v168 row_mirror row_mask:0xf bank_mask:0xf
	s_nop 1
	v_add_f32_dpp v168, v168, v168 row_bcast:15 row_mask:0xa bank_mask:0xf
	s_nop 1
	v_add_f32_dpp v168, v168, v168 row_bcast:31 row_mask:0xc bank_mask:0xf
	s_nop 1
	v_readlane_b32 s42, v168, 63
	s_nop 3
	v_fma_f32 v174, s42, v178, v179
	v_rsq_f32_e32 v174, v174
	s_nop 0
	v_pk_mul_f32 v[136:137], v[136:137], v[174:175] op_sel_hi:[1,0]
	v_pk_mul_f32 v[138:139], v[138:139], v[174:175] op_sel_hi:[1,0]
	v_pk_mul_f32 v[140:141], v[140:141], v[174:175] op_sel_hi:[1,0]
	v_pk_mul_f32 v[142:143], v[142:143], v[174:175] op_sel_hi:[1,0]
	v_pk_mul_f32 v[144:145], v[144:145], v[174:175] op_sel_hi:[1,0]
	v_pk_mul_f32 v[146:147], v[146:147], v[174:175] op_sel_hi:[1,0]
	v_pk_mul_f32 v[148:149], v[148:149], v[174:175] op_sel_hi:[1,0]
	v_pk_mul_f32 v[150:151], v[150:151], v[174:175] op_sel_hi:[1,0]
	v_pk_fma_f32 v[136:137], v[136:137], v[32:33], v[48:49]
	v_pk_fma_f32 v[138:139], v[138:139], v[34:35], v[50:51]
	v_pk_fma_f32 v[140:141], v[140:141], v[36:37], v[52:53]
	v_pk_fma_f32 v[142:143], v[142:143], v[38:39], v[54:55]
	v_pk_fma_f32 v[144:145], v[144:145], v[40:41], v[56:57]
	v_pk_fma_f32 v[146:147], v[146:147], v[42:43], v[58:59]
	v_pk_fma_f32 v[148:149], v[148:149], v[44:45], v[60:61]
	v_pk_fma_f32 v[150:151], v[150:151], v[46:47], v[62:63]
	v_cvt_pk_bf16_f32 v152, v136, v137
	v_cvt_pk_bf16_f32 v153, v138, v139
	v_cvt_pk_bf16_f32 v154, v140, v141
	v_cvt_pk_bf16_f32 v155, v142, v143
	v_cvt_pk_bf16_f32 v156, v144, v145
	v_cvt_pk_bf16_f32 v157, v146, v147
	v_cvt_pk_bf16_f32 v158, v148, v149
	v_cvt_pk_bf16_f32 v159, v150, v151
	global_store_dwordx2 v177, v[152:153], s[12:13] offset:0
	global_store_dwordx2 v177, v[154:155], s[12:13] offset:512
	global_store_dwordx2 v177, v[156:157], s[12:13] offset:1024
	global_store_dwordx2 v177, v[158:159], s[12:13] offset:1536
	s_add_u32 s8, s8, 0x80000
	s_addc_u32 s9, s9, 0
	s_add_u32 s12, s12, 0x40000
	s_addc_u32 s13, s13, 0
	global_load_dwordx4 v[64:67], v176, s[2:3] offset:0
	global_load_dwordx4 v[68:71], v176, s[2:3] offset:1024
	global_load_dwordx4 v[72:75], v176, s[2:3] offset:2048
	global_load_dwordx4 v[76:79], v176, s[2:3] offset:3072
	global_load_dwordx2 v[112:113], v177, s[6:7] offset:0
	global_load_dwordx2 v[114:115], v177, s[6:7] offset:512
	global_load_dwordx2 v[116:117], v177, s[6:7] offset:1024
	global_load_dwordx2 v[118:119], v177, s[6:7] offset:1536
	s_add_u32 s2, s2, 0x80000
	s_addc_u32 s3, s3, 0
	s_add_u32 s6, s6, 0x40000
	s_addc_u32 s7, s7, 0
	s_waitcnt vmcnt(32)
	v_lshlrev_b32_e32 v136, 16, v120
	v_and_b32_e32 v137, 0xffff0000, v120
	v_lshlrev_b32_e32 v138, 16, v121
	v_and_b32_e32 v139, 0xffff0000, v121
	v_lshlrev_b32_e32 v140, 16, v122
	v_and_b32_e32 v141, 0xffff0000, v122
	v_lshlrev_b32_e32 v142, 16, v123
	v_and_b32_e32 v143, 0xffff0000, v123
	v_lshlrev_b32_e32 v144, 16, v124
	v_and_b32_e32 v145, 0xffff0000, v124
	v_lshlrev_b32_e32 v146, 16, v125
	v_and_b32_e32 v147, 0xffff0000, v125
	v_lshlrev_b32_e32 v148, 16, v126
	v_and_b32_e32 v149, 0xffff0000, v126
	v_lshlrev_b32_e32 v150, 16, v127
	v_and_b32_e32 v151, 0xffff0000, v127
	v_pk_fma_f32 v[136:137], v[80:81], s[44:45], v[136:137]
	v_pk_fma_f32 v[138:139], v[82:83], s[44:45], v[138:139]
	v_pk_fma_f32 v[140:141], v[84:85], s[44:45], v[140:141]
	v_pk_fma_f32 v[142:143], v[86:87], s[44:45], v[142:143]
	v_pk_fma_f32 v[144:145], v[88:89], s[44:45], v[144:145]
	v_pk_fma_f32 v[146:147], v[90:91], s[44:45], v[146:147]
	v_pk_fma_f32 v[148:149], v[92:93], s[44:45], v[148:149]
	v_pk_fma_f32 v[150:151], v[94:95], s[44:45], v[150:151]
	v_pk_add_f32 v[152:153], v[136:137], v[138:139]
	v_pk_add_f32 v[152:153], v[152:153], v[140:141]
	v_pk_add_f32 v[152:153], v[152:153], v[142:143]
	v_pk_add_f32 v[152:153], v[152:153], v[144:145]
	v_pk_add_f32 v[152:153], v[152:153], v[146:147]
	v_pk_add_f32 v[152:153], v[152:153], v[148:149]
	v_pk_add_f32 v[152:153], v[152:153], v[150:151]
	v_add_f32_e32 v170, v152, v153
	s_nop 1
	v_add_f32_dpp v168, v170, v170 quad_perm:[1,0,3,2] row_mask:0xf bank_mask:0xf
	s_nop 1
	v_add_f32_dpp v168, v168, v168 quad_perm:[2,3,0,1] row_mask:0xf bank_mask:0xf
	s_nop 1
	v_add_f32_dpp v168, v168, v168 row_half_mirror row_mask:0xf bank_mask:0xf
	s_nop 1
	v_add_f32_dpp v168, v168, v168 row_mirror row_mask:0xf bank_mask:0xf
	s_nop 1
	v_add_f32_dpp v168, v168, v168 row_bcast:15 row_mask:0xa bank_mask:0xf
	s_nop 1
	v_add_f32_dpp v168, v168, v168 row_bcast:31 row_mask:0xc bank_mask:0xf
	s_nop 1
	v_readlane_b32 s42, v168, 63
	s_nop 3
	s_mov_b32 s43, s42
	v_pk_fma_f32 v[136:137], s[42:43], v[172:173], v[136:137]
	v_pk_fma_f32 v[138:139], s[42:43], v[172:173], v[138:139]
	v_pk_fma_f32 v[140:141], s[42:43], v[172:173], v[140:141]
	v_pk_fma_f32 v[142:143], s[42:43], v[172:173], v[142:143]
	v_pk_fma_f32 v[144:145], s[42:43], v[172:173], v[144:145]
	v_pk_fma_f32 v[146:147], s[42:43], v[172:173], v[146:147]
	v_pk_fma_f32 v[148:149], s[42:43], v[172:173], v[148:149]
	v_pk_fma_f32 v[150:151], s[42:43], v[172:173], v[150:151]
	v_pk_mul_f32 v[152:153], v[136:137], v[136:137]
	v_pk_fma_f32 v[152:153], v[138:139], v[138:139], v[152:153]
	v_pk_fma_f32 v[152:153], v[140:141], v[140:141], v[152:153]
	v_pk_fma_f32 v[152:153], v[142:143], v[142:143], v[152:153]
	v_pk_fma_f32 v[152:153], v[144:145], v[144:145], v[152:153]
	v_pk_fma_f32 v[152:153], v[146:147], v[146:147], v[152:153]
	v_pk_fma_f32 v[152:153], v[148:149], v[148:149], v[152:153]
	v_pk_fma_f32 v[152:153], v[150:151], v[150:151], v[152:153]
	v_add_f32_e32 v170, v152, v153
	s_nop 1
	v_add_f32_dpp v168, v170, v170 quad_perm:[1,0,3,2] row_mask:0xf bank_mask:0xf
	s_nop 1
	v_add_f32_dpp v168, v168, v168 quad_perm:[2,3,0,1] row_mask:0xf bank_mask:0xf
	s_nop 1
	v_add_f32_dpp v168, v168, v168 row_half_mirror row_mask:0xf bank_mask:0xf
	s_nop 1
	v_add_f32_dpp v168, v168, v168 row_mirror row_mask:0xf bank_mask:0xf
	s_nop 1
	v_add_f32_dpp v168, v168, v168 row_bcast:15 row_mask:0xa bank_mask:0xf
	s_nop 1
	v_add_f32_dpp v168, v168, v168 row_bcast:31 row_mask:0xc bank_mask:0xf
	s_nop 1
	v_readlane_b32 s42, v168, 63
	s_nop 3
	v_fma_f32 v174, s42, v178, v179
	v_rsq_f32_e32 v174, v174
	s_nop 0
	v_pk_mul_f32 v[136:137], v[136:137], v[174:175] op_sel_hi:[1,0]
	v_pk_mul_f32 v[138:139], v[138:139], v[174:175] op_sel_hi:[1,0]
	v_pk_mul_f32 v[140:141], v[140:141], v[174:175] op_sel_hi:[1,0]
	v_pk_mul_f32 v[142:143], v[142:143], v[174:175] op_sel_hi:[1,0]
	v_pk_mul_f32 v[144:145], v[144:145], v[174:175] op_sel_hi:[1,0]
	v_pk_mul_f32 v[146:147], v[146:147], v[174:175] op_sel_hi:[1,0]
	v_pk_mul_f32 v[148:149], v[148:149], v[174:175] op_sel_hi:[1,0]
	v_pk_mul_f32 v[150:151], v[150:151], v[174:175] op_sel_hi:[1,0]
	v_pk_fma_f32 v[136:137], v[136:137], v[0:1], v[16:17]
	v_pk_fma_f32 v[138:139], v[138:139], v[2:3], v[18:19]
	v_pk_fma_f32 v[140:141], v[140:141], v[4:5], v[20:21]
	v_pk_fma_f32 v[142:143], v[142:143], v[6:7], v[22:23]
	v_pk_fma_f32 v[144:145], v[144:145], v[8:9], v[24:25]
	v_pk_fma_f32 v[146:147], v[146:147], v[10:11], v[26:27]
	v_pk_fma_f32 v[148:149], v[148:149], v[12:13], v[28:29]
	v_pk_fma_f32 v[150:151], v[150:151], v[14:15], v[30:31]
	global_store_dwordx4 v176, v[136:139], s[8:9] offset:0
	global_store_dwordx4 v176, v[140:143], s[8:9] offset:1024
	global_store_dwordx4 v176, v[144:147], s[8:9] offset:2048
	global_store_dwordx4 v176, v[148:151], s[8:9] offset:3072
	v_pk_add_f32 v[152:153], v[136:137], v[138:139]
	v_pk_add_f32 v[152:153], v[152:153], v[140:141]
	v_pk_add_f32 v[152:153], v[152:153], v[142:143]
	v_pk_add_f32 v[152:153], v[152:153], v[144:145]
	v_pk_add_f32 v[152:153], v[152:153], v[146:147]
	v_pk_add_f32 v[152:153], v[152:153], v[148:149]
	v_pk_add_f32 v[152:153], v[152:153], v[150:151]
	v_add_f32_e32 v170, v152, v153
	s_nop 1
	v_add_f32_dpp v168, v170, v170 quad_perm:[1,0,3,2] row_mask:0xf bank_mask:0xf
	s_nop 1
	v_add_f32_dpp v168, v168, v168 quad_perm:[2,3,0,1] row_mask:0xf bank_mask:0xf
	s_nop 1
	v_add_f32_dpp v168, v168, v168 row_half_mirror row_mask:0xf bank_mask:0xf
	s_nop 1
	v_add_f32_dpp v168, v168, v168 row_mirror row_mask:0xf bank_mask:0xf
	s_nop 1
	v_add_f32_dpp v168, v168, v168 row_bcast:15 row_mask:0xa bank_mask:0xf
	s_nop 1
	v_add_f32_dpp v168, v168, v168 row_bcast:31 row_mask:0xc bank_mask:0xf
	s_nop 1
	v_readlane_b32 s42, v168, 63
	s_nop 3
	s_mov_b32 s43, s42
	v_pk_fma_f32 v[136:137], s[42:43], v[172:173], v[136:137]
	v_pk_fma_f32 v[138:139], s[42:43], v[172:173], v[138:139]
	v_pk_fma_f32 v[140:141], s[42:43], v[172:173], v[140:141]
	v_pk_fma_f32 v[142:143], s[42:43], v[172:173], v[142:143]
	v_pk_fma_f32 v[144:145], s[42:43], v[172:173], v[144:145]
	v_pk_fma_f32 v[146:147], s[42:43], v[172:173], v[146:147]
	v_pk_fma_f32 v[148:149], s[42:43], v[172:173], v[148:149]
	v_pk_fma_f32 v[150:151], s[42:43], v[172:173], v[150:151]
	v_pk_mul_f32 v[152:153], v[136:137], v[136:137]
	v_pk_fma_f32 v[152:153], v[138:139], v[138:139], v[152:153]
	v_pk_fma_f32 v[152:153], v[140:141], v[140:141], v[152:153]
	v_pk_fma_f32 v[152:153], v[142:143], v[142:143], v[152:153]
	v_pk_fma_f32 v[152:153], v[144:145], v[144:145], v[152:153]
	v_pk_fma_f32 v[152:153], v[146:147], v[146:147], v[152:153]
	v_pk_fma_f32 v[152:153], v[148:149], v[148:149], v[152:153]
	v_pk_fma_f32 v[152:153], v[150:151], v[150:151], v[152:153]
	v_add_f32_e32 v170, v152, v153
	s_nop 1
	v_add_f32_dpp v168, v170, v170 quad_perm:[1,0,3,2] row_mask:0xf bank_mask:0xf
	s_nop 1
	v_add_f32_dpp v168, v168, v168 quad_perm:[2,3,0,1] row_mask:0xf bank_mask:0xf
	s_nop 1
	v_add_f32_dpp v168, v168, v168 row_half_mirror row_mask:0xf bank_mask:0xf
	s_nop 1
	v_add_f32_dpp v168, v168, v168 row_mirror row_mask:0xf bank_mask:0xf
	s_nop 1
	v_add_f32_dpp v168, v168, v168 row_bcast:15 row_mask:0xa bank_mask:0xf
	s_nop 1
	v_add_f32_dpp v168, v168, v168 row_bcast:31 row_mask:0xc bank_mask:0xf
	s_nop 1
	v_readlane_b32 s42, v168, 63
	s_nop 3
	v_fma_f32 v174, s42, v178, v179
	v_rsq_f32_e32 v174, v174
	s_nop 0
	v_pk_mul_f32 v[136:137], v[136:137], v[174:175] op_sel_hi:[1,0]
	v_pk_mul_f32 v[138:139], v[138:139], v[174:175] op_sel_hi:[1,0]
	v_pk_mul_f32 v[140:141], v[140:141], v[174:175] op_sel_hi:[1,0]
	v_pk_mul_f32 v[142:143], v[142:143], v[174:175] op_sel_hi:[1,0]
	v_pk_mul_f32 v[144:145], v[144:145], v[174:175] op_sel_hi:[1,0]
	v_pk_mul_f32 v[146:147], v[146:147], v[174:175] op_sel_hi:[1,0]
	v_pk_mul_f32 v[148:149], v[148:149], v[174:175] op_sel_hi:[1,0]
	v_pk_mul_f32 v[150:151], v[150:151], v[174:175] op_sel_hi:[1,0]
	v_pk_fma_f32 v[136:137], v[136:137], v[32:33], v[48:49]
	v_pk_fma_f32 v[138:139], v[138:139], v[34:35], v[50:51]
	v_pk_fma_f32 v[140:141], v[140:141], v[36:37], v[52:53]
	v_pk_fma_f32 v[142:143], v[142:143], v[38:39], v[54:55]
	v_pk_fma_f32 v[144:145], v[144:145], v[40:41], v[56:57]
	v_pk_fma_f32 v[146:147], v[146:147], v[42:43], v[58:59]
	v_pk_fma_f32 v[148:149], v[148:149], v[44:45], v[60:61]
	v_pk_fma_f32 v[150:151], v[150:151], v[46:47], v[62:63]
	v_cvt_pk_bf16_f32 v152, v136, v137
	v_cvt_pk_bf16_f32 v153, v138, v139
	v_cvt_pk_bf16_f32 v154, v140, v141
	v_cvt_pk_bf16_f32 v155, v142, v143
	v_cvt_pk_bf16_f32 v156, v144, v145
	v_cvt_pk_bf16_f32 v157, v146, v147
	v_cvt_pk_bf16_f32 v158, v148, v149
	v_cvt_pk_bf16_f32 v159, v150, v151
	global_store_dwordx2 v177, v[152:153], s[12:13] offset:0
	global_store_dwordx2 v177, v[154:155], s[12:13] offset:512
	global_store_dwordx2 v177, v[156:157], s[12:13] offset:1024
	global_store_dwordx2 v177, v[158:159], s[12:13] offset:1536
	s_add_u32 s8, s8, 0x80000
	s_addc_u32 s9, s9, 0
	s_add_u32 s12, s12, 0x40000
	s_addc_u32 s13, s13, 0
	global_load_dwordx4 v[80:83], v176, s[2:3] offset:0
	global_load_dwordx4 v[84:87], v176, s[2:3] offset:1024
	global_load_dwordx4 v[88:91], v176, s[2:3] offset:2048
	global_load_dwordx4 v[92:95], v176, s[2:3] offset:3072
	global_load_dwordx2 v[120:121], v177, s[6:7] offset:0
	global_load_dwordx2 v[122:123], v177, s[6:7] offset:512
	global_load_dwordx2 v[124:125], v177, s[6:7] offset:1024
	global_load_dwordx2 v[126:127], v177, s[6:7] offset:1536
	s_add_u32 s2, s2, 0x80000
	s_addc_u32 s3, s3, 0
	s_add_u32 s6, s6, 0x40000
	s_addc_u32 s7, s7, 0
	s_waitcnt vmcnt(32)
	v_lshlrev_b32_e32 v136, 16, v128
	v_and_b32_e32 v137, 0xffff0000, v128
	v_lshlrev_b32_e32 v138, 16, v129
	v_and_b32_e32 v139, 0xffff0000, v129
	v_lshlrev_b32_e32 v140, 16, v130
	v_and_b32_e32 v141, 0xffff0000, v130
	v_lshlrev_b32_e32 v142, 16, v131
	v_and_b32_e32 v143, 0xffff0000, v131
	v_lshlrev_b32_e32 v144, 16, v132
	v_and_b32_e32 v145, 0xffff0000, v132
	v_lshlrev_b32_e32 v146, 16, v133
	v_and_b32_e32 v147, 0xffff0000, v133
	v_lshlrev_b32_e32 v148, 16, v134
	v_and_b32_e32 v149, 0xffff0000, v134
	v_lshlrev_b32_e32 v150, 16, v135
	v_and_b32_e32 v151, 0xffff0000, v135
	v_pk_fma_f32 v[136:137], v[96:97], s[44:45], v[136:137]
	v_pk_fma_f32 v[138:139], v[98:99], s[44:45], v[138:139]
	v_pk_fma_f32 v[140:141], v[100:101], s[44:45], v[140:141]
	v_pk_fma_f32 v[142:143], v[102:103], s[44:45], v[142:143]
	v_pk_fma_f32 v[144:145], v[104:105], s[44:45], v[144:145]
	v_pk_fma_f32 v[146:147], v[106:107], s[44:45], v[146:147]
	v_pk_fma_f32 v[148:149], v[108:109], s[44:45], v[148:149]
	v_pk_fma_f32 v[150:151], v[110:111], s[44:45], v[150:151]
	v_pk_add_f32 v[152:153], v[136:137], v[138:139]
	v_pk_add_f32 v[152:153], v[152:153], v[140:141]
	v_pk_add_f32 v[152:153], v[152:153], v[142:143]
	v_pk_add_f32 v[152:153], v[152:153], v[144:145]
	v_pk_add_f32 v[152:153], v[152:153], v[146:147]
	v_pk_add_f32 v[152:153], v[152:153], v[148:149]
	v_pk_add_f32 v[152:153], v[152:153], v[150:151]
	v_add_f32_e32 v170, v152, v153
	s_nop 1
	v_add_f32_dpp v168, v170, v170 quad_perm:[1,0,3,2] row_mask:0xf bank_mask:0xf
	s_nop 1
	v_add_f32_dpp v168, v168, v168 quad_perm:[2,3,0,1] row_mask:0xf bank_mask:0xf
	s_nop 1
	v_add_f32_dpp v168, v168, v168 row_half_mirror row_mask:0xf bank_mask:0xf
	s_nop 1
	v_add_f32_dpp v168, v168, v168 row_mirror row_mask:0xf bank_mask:0xf
	s_nop 1
	v_add_f32_dpp v168, v168, v168 row_bcast:15 row_mask:0xa bank_mask:0xf
	s_nop 1
	v_add_f32_dpp v168, v168, v168 row_bcast:31 row_mask:0xc bank_mask:0xf
	s_nop 1
	v_readlane_b32 s42, v168, 63
	s_nop 3
	s_mov_b32 s43, s42
	v_pk_fma_f32 v[136:137], s[42:43], v[172:173], v[136:137]
	v_pk_fma_f32 v[138:139], s[42:43], v[172:173], v[138:139]
	v_pk_fma_f32 v[140:141], s[42:43], v[172:173], v[140:141]
	v_pk_fma_f32 v[142:143], s[42:43], v[172:173], v[142:143]
	v_pk_fma_f32 v[144:145], s[42:43], v[172:173], v[144:145]
	v_pk_fma_f32 v[146:147], s[42:43], v[172:173], v[146:147]
	v_pk_fma_f32 v[148:149], s[42:43], v[172:173], v[148:149]
	v_pk_fma_f32 v[150:151], s[42:43], v[172:173], v[150:151]
	v_pk_mul_f32 v[152:153], v[136:137], v[136:137]
	v_pk_fma_f32 v[152:153], v[138:139], v[138:139], v[152:153]
	v_pk_fma_f32 v[152:153], v[140:141], v[140:141], v[152:153]
	v_pk_fma_f32 v[152:153], v[142:143], v[142:143], v[152:153]
	v_pk_fma_f32 v[152:153], v[144:145], v[144:145], v[152:153]
	v_pk_fma_f32 v[152:153], v[146:147], v[146:147], v[152:153]
	v_pk_fma_f32 v[152:153], v[148:149], v[148:149], v[152:153]
	v_pk_fma_f32 v[152:153], v[150:151], v[150:151], v[152:153]
	v_add_f32_e32 v170, v152, v153
	s_nop 1
	v_add_f32_dpp v168, v170, v170 quad_perm:[1,0,3,2] row_mask:0xf bank_mask:0xf
	s_nop 1
	v_add_f32_dpp v168, v168, v168 quad_perm:[2,3,0,1] row_mask:0xf bank_mask:0xf
	s_nop 1
	v_add_f32_dpp v168, v168, v168 row_half_mirror row_mask:0xf bank_mask:0xf
	s_nop 1
	v_add_f32_dpp v168, v168, v168 row_mirror row_mask:0xf bank_mask:0xf
	s_nop 1
	v_add_f32_dpp v168, v168, v168 row_bcast:15 row_mask:0xa bank_mask:0xf
	s_nop 1
	v_add_f32_dpp v168, v168, v168 row_bcast:31 row_mask:0xc bank_mask:0xf
	s_nop 1
	v_readlane_b32 s42, v168, 63
	s_nop 3
	v_fma_f32 v174, s42, v178, v179
	v_rsq_f32_e32 v174, v174
	s_nop 0
	v_pk_mul_f32 v[136:137], v[136:137], v[174:175] op_sel_hi:[1,0]
	v_pk_mul_f32 v[138:139], v[138:139], v[174:175] op_sel_hi:[1,0]
	v_pk_mul_f32 v[140:141], v[140:141], v[174:175] op_sel_hi:[1,0]
	v_pk_mul_f32 v[142:143], v[142:143], v[174:175] op_sel_hi:[1,0]
	v_pk_mul_f32 v[144:145], v[144:145], v[174:175] op_sel_hi:[1,0]
	v_pk_mul_f32 v[146:147], v[146:147], v[174:175] op_sel_hi:[1,0]
	v_pk_mul_f32 v[148:149], v[148:149], v[174:175] op_sel_hi:[1,0]
	v_pk_mul_f32 v[150:151], v[150:151], v[174:175] op_sel_hi:[1,0]
	v_pk_fma_f32 v[136:137], v[136:137], v[0:1], v[16:17]
	v_pk_fma_f32 v[138:139], v[138:139], v[2:3], v[18:19]
	v_pk_fma_f32 v[140:141], v[140:141], v[4:5], v[20:21]
	v_pk_fma_f32 v[142:143], v[142:143], v[6:7], v[22:23]
	v_pk_fma_f32 v[144:145], v[144:145], v[8:9], v[24:25]
	v_pk_fma_f32 v[146:147], v[146:147], v[10:11], v[26:27]
	v_pk_fma_f32 v[148:149], v[148:149], v[12:13], v[28:29]
	v_pk_fma_f32 v[150:151], v[150:151], v[14:15], v[30:31]
	global_store_dwordx4 v176, v[136:139], s[8:9] offset:0
	global_store_dwordx4 v176, v[140:143], s[8:9] offset:1024
	global_store_dwordx4 v176, v[144:147], s[8:9] offset:2048
	global_store_dwordx4 v176, v[148:151], s[8:9] offset:3072
	v_pk_add_f32 v[152:153], v[136:137], v[138:139]
	v_pk_add_f32 v[152:153], v[152:153], v[140:141]
	v_pk_add_f32 v[152:153], v[152:153], v[142:143]
	v_pk_add_f32 v[152:153], v[152:153], v[144:145]
	v_pk_add_f32 v[152:153], v[152:153], v[146:147]
	v_pk_add_f32 v[152:153], v[152:153], v[148:149]
	v_pk_add_f32 v[152:153], v[152:153], v[150:151]
	v_add_f32_e32 v170, v152, v153
	s_nop 1
	v_add_f32_dpp v168, v170, v170 quad_perm:[1,0,3,2] row_mask:0xf bank_mask:0xf
	s_nop 1
	v_add_f32_dpp v168, v168, v168 quad_perm:[2,3,0,1] row_mask:0xf bank_mask:0xf
	s_nop 1
	v_add_f32_dpp v168, v168, v168 row_half_mirror row_mask:0xf bank_mask:0xf
	s_nop 1
	v_add_f32_dpp v168, v168, v168 row_mirror row_mask:0xf bank_mask:0xf
	s_nop 1
	v_add_f32_dpp v168, v168, v168 row_bcast:15 row_mask:0xa bank_mask:0xf
	s_nop 1
	v_add_f32_dpp v168, v168, v168 row_bcast:31 row_mask:0xc bank_mask:0xf
	s_nop 1
	v_readlane_b32 s42, v168, 63
	s_nop 3
	s_mov_b32 s43, s42
	v_pk_fma_f32 v[136:137], s[42:43], v[172:173], v[136:137]
	v_pk_fma_f32 v[138:139], s[42:43], v[172:173], v[138:139]
	v_pk_fma_f32 v[140:141], s[42:43], v[172:173], v[140:141]
	v_pk_fma_f32 v[142:143], s[42:43], v[172:173], v[142:143]
	v_pk_fma_f32 v[144:145], s[42:43], v[172:173], v[144:145]
	v_pk_fma_f32 v[146:147], s[42:43], v[172:173], v[146:147]
	v_pk_fma_f32 v[148:149], s[42:43], v[172:173], v[148:149]
	v_pk_fma_f32 v[150:151], s[42:43], v[172:173], v[150:151]
	v_pk_mul_f32 v[152:153], v[136:137], v[136:137]
	v_pk_fma_f32 v[152:153], v[138:139], v[138:139], v[152:153]
	v_pk_fma_f32 v[152:153], v[140:141], v[140:141], v[152:153]
	v_pk_fma_f32 v[152:153], v[142:143], v[142:143], v[152:153]
	v_pk_fma_f32 v[152:153], v[144:145], v[144:145], v[152:153]
	v_pk_fma_f32 v[152:153], v[146:147], v[146:147], v[152:153]
	v_pk_fma_f32 v[152:153], v[148:149], v[148:149], v[152:153]
	v_pk_fma_f32 v[152:153], v[150:151], v[150:151], v[152:153]
	v_add_f32_e32 v170, v152, v153
	s_nop 1
	v_add_f32_dpp v168, v170, v170 quad_perm:[1,0,3,2] row_mask:0xf bank_mask:0xf
	s_nop 1
	v_add_f32_dpp v168, v168, v168 quad_perm:[2,3,0,1] row_mask:0xf bank_mask:0xf
	s_nop 1
	v_add_f32_dpp v168, v168, v168 row_half_mirror row_mask:0xf bank_mask:0xf
	s_nop 1
	v_add_f32_dpp v168, v168, v168 row_mirror row_mask:0xf bank_mask:0xf
	s_nop 1
	v_add_f32_dpp v168, v168, v168 row_bcast:15 row_mask:0xa bank_mask:0xf
	s_nop 1
	v_add_f32_dpp v168, v168, v168 row_bcast:31 row_mask:0xc bank_mask:0xf
	s_nop 1
	v_readlane_b32 s42, v168, 63
	s_nop 3
	v_fma_f32 v174, s42, v178, v179
	v_rsq_f32_e32 v174, v174
	s_nop 0
	v_pk_mul_f32 v[136:137], v[136:137], v[174:175] op_sel_hi:[1,0]
	v_pk_mul_f32 v[138:139], v[138:139], v[174:175] op_sel_hi:[1,0]
	v_pk_mul_f32 v[140:141], v[140:141], v[174:175] op_sel_hi:[1,0]
	v_pk_mul_f32 v[142:143], v[142:143], v[174:175] op_sel_hi:[1,0]
	v_pk_mul_f32 v[144:145], v[144:145], v[174:175] op_sel_hi:[1,0]
	v_pk_mul_f32 v[146:147], v[146:147], v[174:175] op_sel_hi:[1,0]
	v_pk_mul_f32 v[148:149], v[148:149], v[174:175] op_sel_hi:[1,0]
	v_pk_mul_f32 v[150:151], v[150:151], v[174:175] op_sel_hi:[1,0]
	v_pk_fma_f32 v[136:137], v[136:137], v[32:33], v[48:49]
	v_pk_fma_f32 v[138:139], v[138:139], v[34:35], v[50:51]
	v_pk_fma_f32 v[140:141], v[140:141], v[36:37], v[52:53]
	v_pk_fma_f32 v[142:143], v[142:143], v[38:39], v[54:55]
	v_pk_fma_f32 v[144:145], v[144:145], v[40:41], v[56:57]
	v_pk_fma_f32 v[146:147], v[146:147], v[42:43], v[58:59]
	v_pk_fma_f32 v[148:149], v[148:149], v[44:45], v[60:61]
	v_pk_fma_f32 v[150:151], v[150:151], v[46:47], v[62:63]
	v_cvt_pk_bf16_f32 v152, v136, v137
	v_cvt_pk_bf16_f32 v153, v138, v139
	v_cvt_pk_bf16_f32 v154, v140, v141
	v_cvt_pk_bf16_f32 v155, v142, v143
	v_cvt_pk_bf16_f32 v156, v144, v145
	v_cvt_pk_bf16_f32 v157, v146, v147
	v_cvt_pk_bf16_f32 v158, v148, v149
	v_cvt_pk_bf16_f32 v159, v150, v151
	global_store_dwordx2 v177, v[152:153], s[12:13] offset:0
	global_store_dwordx2 v177, v[154:155], s[12:13] offset:512
	global_store_dwordx2 v177, v[156:157], s[12:13] offset:1024
	global_store_dwordx2 v177, v[158:159], s[12:13] offset:1536
	s_add_u32 s8, s8, 0x80000
	s_addc_u32 s9, s9, 0
	s_add_u32 s12, s12, 0x40000
	s_addc_u32 s13, s13, 0
	global_load_dwordx4 v[96:99], v176, s[2:3] offset:0
	global_load_dwordx4 v[100:103], v176, s[2:3] offset:1024
	global_load_dwordx4 v[104:107], v176, s[2:3] offset:2048
	global_load_dwordx4 v[108:111], v176, s[2:3] offset:3072
	global_load_dwordx2 v[128:129], v177, s[6:7] offset:0
	global_load_dwordx2 v[130:131], v177, s[6:7] offset:512
	global_load_dwordx2 v[132:133], v177, s[6:7] offset:1024
	global_load_dwordx2 v[134:135], v177, s[6:7] offset:1536
	s_add_u32 s2, s2, 0x80000
	s_addc_u32 s3, s3, 0
	s_add_u32 s6, s6, 0x40000
	s_addc_u32 s7, s7, 0
	s_waitcnt vmcnt(32)
	v_lshlrev_b32_e32 v136, 16, v112
	v_and_b32_e32 v137, 0xffff0000, v112
	v_lshlrev_b32_e32 v138, 16, v113
	v_and_b32_e32 v139, 0xffff0000, v113
	v_lshlrev_b32_e32 v140, 16, v114
	v_and_b32_e32 v141, 0xffff0000, v114
	v_lshlrev_b32_e32 v142, 16, v115
	v_and_b32_e32 v143, 0xffff0000, v115
	v_lshlrev_b32_e32 v144, 16, v116
	v_and_b32_e32 v145, 0xffff0000, v116
	v_lshlrev_b32_e32 v146, 16, v117
	v_and_b32_e32 v147, 0xffff0000, v117
	v_lshlrev_b32_e32 v148, 16, v118
	v_and_b32_e32 v149, 0xffff0000, v118
	v_lshlrev_b32_e32 v150, 16, v119
	v_and_b32_e32 v151, 0xffff0000, v119
	v_pk_fma_f32 v[136:137], v[64:65], s[44:45], v[136:137]
	v_pk_fma_f32 v[138:139], v[66:67], s[44:45], v[138:139]
	v_pk_fma_f32 v[140:141], v[68:69], s[44:45], v[140:141]
	v_pk_fma_f32 v[142:143], v[70:71], s[44:45], v[142:143]
	v_pk_fma_f32 v[144:145], v[72:73], s[44:45], v[144:145]
	v_pk_fma_f32 v[146:147], v[74:75], s[44:45], v[146:147]
	v_pk_fma_f32 v[148:149], v[76:77], s[44:45], v[148:149]
	v_pk_fma_f32 v[150:151], v[78:79], s[44:45], v[150:151]
	v_pk_add_f32 v[152:153], v[136:137], v[138:139]
	v_pk_add_f32 v[152:153], v[152:153], v[140:141]
	v_pk_add_f32 v[152:153], v[152:153], v[142:143]
	v_pk_add_f32 v[152:153], v[152:153], v[144:145]
	v_pk_add_f32 v[152:153], v[152:153], v[146:147]
	v_pk_add_f32 v[152:153], v[152:153], v[148:149]
	v_pk_add_f32 v[152:153], v[152:153], v[150:151]
	v_add_f32_e32 v170, v152, v153
	s_nop 1
	v_add_f32_dpp v168, v170, v170 quad_perm:[1,0,3,2] row_mask:0xf bank_mask:0xf
	s_nop 1
	v_add_f32_dpp v168, v168, v168 quad_perm:[2,3,0,1] row_mask:0xf bank_mask:0xf
	s_nop 1
	v_add_f32_dpp v168, v168, v168 row_half_mirror row_mask:0xf bank_mask:0xf
	s_nop 1
	v_add_f32_dpp v168, v168, v168 row_mirror row_mask:0xf bank_mask:0xf
	s_nop 1
	v_add_f32_dpp v168, v168, v168 row_bcast:15 row_mask:0xa bank_mask:0xf
	s_nop 1
	v_add_f32_dpp v168, v168, v168 row_bcast:31 row_mask:0xc bank_mask:0xf
	s_nop 1
	v_readlane_b32 s42, v168, 63
	s_nop 3
	s_mov_b32 s43, s42
	v_pk_fma_f32 v[136:137], s[42:43], v[172:173], v[136:137]
	v_pk_fma_f32 v[138:139], s[42:43], v[172:173], v[138:139]
	v_pk_fma_f32 v[140:141], s[42:43], v[172:173], v[140:141]
	v_pk_fma_f32 v[142:143], s[42:43], v[172:173], v[142:143]
	v_pk_fma_f32 v[144:145], s[42:43], v[172:173], v[144:145]
	v_pk_fma_f32 v[146:147], s[42:43], v[172:173], v[146:147]
	v_pk_fma_f32 v[148:149], s[42:43], v[172:173], v[148:149]
	v_pk_fma_f32 v[150:151], s[42:43], v[172:173], v[150:151]
	v_pk_mul_f32 v[152:153], v[136:137], v[136:137]
	v_pk_fma_f32 v[152:153], v[138:139], v[138:139], v[152:153]
	v_pk_fma_f32 v[152:153], v[140:141], v[140:141], v[152:153]
	v_pk_fma_f32 v[152:153], v[142:143], v[142:143], v[152:153]
	v_pk_fma_f32 v[152:153], v[144:145], v[144:145], v[152:153]
	v_pk_fma_f32 v[152:153], v[146:147], v[146:147], v[152:153]
	v_pk_fma_f32 v[152:153], v[148:149], v[148:149], v[152:153]
	v_pk_fma_f32 v[152:153], v[150:151], v[150:151], v[152:153]
	v_add_f32_e32 v170, v152, v153
	s_nop 1
	v_add_f32_dpp v168, v170, v170 quad_perm:[1,0,3,2] row_mask:0xf bank_mask:0xf
	s_nop 1
	v_add_f32_dpp v168, v168, v168 quad_perm:[2,3,0,1] row_mask:0xf bank_mask:0xf
	s_nop 1
	v_add_f32_dpp v168, v168, v168 row_half_mirror row_mask:0xf bank_mask:0xf
	s_nop 1
	v_add_f32_dpp v168, v168, v168 row_mirror row_mask:0xf bank_mask:0xf
	s_nop 1
	v_add_f32_dpp v168, v168, v168 row_bcast:15 row_mask:0xa bank_mask:0xf
	s_nop 1
	v_add_f32_dpp v168, v168, v168 row_bcast:31 row_mask:0xc bank_mask:0xf
	s_nop 1
	v_readlane_b32 s42, v168, 63
	s_nop 3
	v_fma_f32 v174, s42, v178, v179
	v_rsq_f32_e32 v174, v174
	s_nop 0
	v_pk_mul_f32 v[136:137], v[136:137], v[174:175] op_sel_hi:[1,0]
	v_pk_mul_f32 v[138:139], v[138:139], v[174:175] op_sel_hi:[1,0]
	v_pk_mul_f32 v[140:141], v[140:141], v[174:175] op_sel_hi:[1,0]
	v_pk_mul_f32 v[142:143], v[142:143], v[174:175] op_sel_hi:[1,0]
	v_pk_mul_f32 v[144:145], v[144:145], v[174:175] op_sel_hi:[1,0]
	v_pk_mul_f32 v[146:147], v[146:147], v[174:175] op_sel_hi:[1,0]
	v_pk_mul_f32 v[148:149], v[148:149], v[174:175] op_sel_hi:[1,0]
	v_pk_mul_f32 v[150:151], v[150:151], v[174:175] op_sel_hi:[1,0]
	v_pk_fma_f32 v[136:137], v[136:137], v[0:1], v[16:17]
	v_pk_fma_f32 v[138:139], v[138:139], v[2:3], v[18:19]
	v_pk_fma_f32 v[140:141], v[140:141], v[4:5], v[20:21]
	v_pk_fma_f32 v[142:143], v[142:143], v[6:7], v[22:23]
	v_pk_fma_f32 v[144:145], v[144:145], v[8:9], v[24:25]
	v_pk_fma_f32 v[146:147], v[146:147], v[10:11], v[26:27]
	v_pk_fma_f32 v[148:149], v[148:149], v[12:13], v[28:29]
	v_pk_fma_f32 v[150:151], v[150:151], v[14:15], v[30:31]
	global_store_dwordx4 v176, v[136:139], s[8:9] offset:0
	global_store_dwordx4 v176, v[140:143], s[8:9] offset:1024
	global_store_dwordx4 v176, v[144:147], s[8:9] offset:2048
	global_store_dwordx4 v176, v[148:151], s[8:9] offset:3072
	v_pk_add_f32 v[152:153], v[136:137], v[138:139]
	v_pk_add_f32 v[152:153], v[152:153], v[140:141]
	v_pk_add_f32 v[152:153], v[152:153], v[142:143]
	v_pk_add_f32 v[152:153], v[152:153], v[144:145]
	v_pk_add_f32 v[152:153], v[152:153], v[146:147]
	v_pk_add_f32 v[152:153], v[152:153], v[148:149]
	v_pk_add_f32 v[152:153], v[152:153], v[150:151]
	v_add_f32_e32 v170, v152, v153
	s_nop 1
	v_add_f32_dpp v168, v170, v170 quad_perm:[1,0,3,2] row_mask:0xf bank_mask:0xf
	s_nop 1
	v_add_f32_dpp v168, v168, v168 quad_perm:[2,3,0,1] row_mask:0xf bank_mask:0xf
	s_nop 1
	v_add_f32_dpp v168, v168, v168 row_half_mirror row_mask:0xf bank_mask:0xf
	s_nop 1
	v_add_f32_dpp v168, v168, v168 row_mirror row_mask:0xf bank_mask:0xf
	s_nop 1
	v_add_f32_dpp v168, v168, v168 row_bcast:15 row_mask:0xa bank_mask:0xf
	s_nop 1
	v_add_f32_dpp v168, v168, v168 row_bcast:31 row_mask:0xc bank_mask:0xf
	s_nop 1
	v_readlane_b32 s42, v168, 63
	s_nop 3
	s_mov_b32 s43, s42
	v_pk_fma_f32 v[136:137], s[42:43], v[172:173], v[136:137]
	v_pk_fma_f32 v[138:139], s[42:43], v[172:173], v[138:139]
	v_pk_fma_f32 v[140:141], s[42:43], v[172:173], v[140:141]
	v_pk_fma_f32 v[142:143], s[42:43], v[172:173], v[142:143]
	v_pk_fma_f32 v[144:145], s[42:43], v[172:173], v[144:145]
	v_pk_fma_f32 v[146:147], s[42:43], v[172:173], v[146:147]
	v_pk_fma_f32 v[148:149], s[42:43], v[172:173], v[148:149]
	v_pk_fma_f32 v[150:151], s[42:43], v[172:173], v[150:151]
	v_pk_mul_f32 v[152:153], v[136:137], v[136:137]
	v_pk_fma_f32 v[152:153], v[138:139], v[138:139], v[152:153]
	v_pk_fma_f32 v[152:153], v[140:141], v[140:141], v[152:153]
	v_pk_fma_f32 v[152:153], v[142:143], v[142:143], v[152:153]
	v_pk_fma_f32 v[152:153], v[144:145], v[144:145], v[152:153]
	v_pk_fma_f32 v[152:153], v[146:147], v[146:147], v[152:153]
	v_pk_fma_f32 v[152:153], v[148:149], v[148:149], v[152:153]
	v_pk_fma_f32 v[152:153], v[150:151], v[150:151], v[152:153]
	v_add_f32_e32 v170, v152, v153
	s_nop 1
	v_add_f32_dpp v168, v170, v170 quad_perm:[1,0,3,2] row_mask:0xf bank_mask:0xf
	s_nop 1
	v_add_f32_dpp v168, v168, v168 quad_perm:[2,3,0,1] row_mask:0xf bank_mask:0xf
	s_nop 1
	v_add_f32_dpp v168, v168, v168 row_half_mirror row_mask:0xf bank_mask:0xf
	s_nop 1
	v_add_f32_dpp v168, v168, v168 row_mirror row_mask:0xf bank_mask:0xf
	s_nop 1
	v_add_f32_dpp v168, v168, v168 row_bcast:15 row_mask:0xa bank_mask:0xf
	s_nop 1
	v_add_f32_dpp v168, v168, v168 row_bcast:31 row_mask:0xc bank_mask:0xf
	s_nop 1
	v_readlane_b32 s42, v168, 63
	s_nop 3
	v_fma_f32 v174, s42, v178, v179
	v_rsq_f32_e32 v174, v174
	s_nop 0
	v_pk_mul_f32 v[136:137], v[136:137], v[174:175] op_sel_hi:[1,0]
	v_pk_mul_f32 v[138:139], v[138:139], v[174:175] op_sel_hi:[1,0]
	v_pk_mul_f32 v[140:141], v[140:141], v[174:175] op_sel_hi:[1,0]
	v_pk_mul_f32 v[142:143], v[142:143], v[174:175] op_sel_hi:[1,0]
	v_pk_mul_f32 v[144:145], v[144:145], v[174:175] op_sel_hi:[1,0]
	v_pk_mul_f32 v[146:147], v[146:147], v[174:175] op_sel_hi:[1,0]
	v_pk_mul_f32 v[148:149], v[148:149], v[174:175] op_sel_hi:[1,0]
	v_pk_mul_f32 v[150:151], v[150:151], v[174:175] op_sel_hi:[1,0]
	v_pk_fma_f32 v[136:137], v[136:137], v[32:33], v[48:49]
	v_pk_fma_f32 v[138:139], v[138:139], v[34:35], v[50:51]
	v_pk_fma_f32 v[140:141], v[140:141], v[36:37], v[52:53]
	v_pk_fma_f32 v[142:143], v[142:143], v[38:39], v[54:55]
	v_pk_fma_f32 v[144:145], v[144:145], v[40:41], v[56:57]
	v_pk_fma_f32 v[146:147], v[146:147], v[42:43], v[58:59]
	v_pk_fma_f32 v[148:149], v[148:149], v[44:45], v[60:61]
	v_pk_fma_f32 v[150:151], v[150:151], v[46:47], v[62:63]
	v_cvt_pk_bf16_f32 v152, v136, v137
	v_cvt_pk_bf16_f32 v153, v138, v139
	v_cvt_pk_bf16_f32 v154, v140, v141
	v_cvt_pk_bf16_f32 v155, v142, v143
	v_cvt_pk_bf16_f32 v156, v144, v145
	v_cvt_pk_bf16_f32 v157, v146, v147
	v_cvt_pk_bf16_f32 v158, v148, v149
	v_cvt_pk_bf16_f32 v159, v150, v151
	global_store_dwordx2 v177, v[152:153], s[12:13] offset:0
	global_store_dwordx2 v177, v[154:155], s[12:13] offset:512
	global_store_dwordx2 v177, v[156:157], s[12:13] offset:1024
	global_store_dwordx2 v177, v[158:159], s[12:13] offset:1536
	s_add_u32 s8, s8, 0x80000
	s_addc_u32 s9, s9, 0
	s_add_u32 s12, s12, 0x40000
	s_addc_u32 s13, s13, 0
	global_load_dwordx4 v[64:67], v176, s[2:3] offset:0
	global_load_dwordx4 v[68:71], v176, s[2:3] offset:1024
	global_load_dwordx4 v[72:75], v176, s[2:3] offset:2048
	global_load_dwordx4 v[76:79], v176, s[2:3] offset:3072
	global_load_dwordx2 v[112:113], v177, s[6:7] offset:0
	global_load_dwordx2 v[114:115], v177, s[6:7] offset:512
	global_load_dwordx2 v[116:117], v177, s[6:7] offset:1024
	global_load_dwordx2 v[118:119], v177, s[6:7] offset:1536
	s_add_u32 s2, s2, 0x80000
	s_addc_u32 s3, s3, 0
	s_add_u32 s6, s6, 0x40000
	s_addc_u32 s7, s7, 0
	s_waitcnt vmcnt(32)
	v_lshlrev_b32_e32 v136, 16, v120
	v_and_b32_e32 v137, 0xffff0000, v120
	v_lshlrev_b32_e32 v138, 16, v121
	v_and_b32_e32 v139, 0xffff0000, v121
	v_lshlrev_b32_e32 v140, 16, v122
	v_and_b32_e32 v141, 0xffff0000, v122
	v_lshlrev_b32_e32 v142, 16, v123
	v_and_b32_e32 v143, 0xffff0000, v123
	v_lshlrev_b32_e32 v144, 16, v124
	v_and_b32_e32 v145, 0xffff0000, v124
	v_lshlrev_b32_e32 v146, 16, v125
	v_and_b32_e32 v147, 0xffff0000, v125
	v_lshlrev_b32_e32 v148, 16, v126
	v_and_b32_e32 v149, 0xffff0000, v126
	v_lshlrev_b32_e32 v150, 16, v127
	v_and_b32_e32 v151, 0xffff0000, v127
	v_pk_fma_f32 v[136:137], v[80:81], s[44:45], v[136:137]
	v_pk_fma_f32 v[138:139], v[82:83], s[44:45], v[138:139]
	v_pk_fma_f32 v[140:141], v[84:85], s[44:45], v[140:141]
	v_pk_fma_f32 v[142:143], v[86:87], s[44:45], v[142:143]
	v_pk_fma_f32 v[144:145], v[88:89], s[44:45], v[144:145]
	v_pk_fma_f32 v[146:147], v[90:91], s[44:45], v[146:147]
	v_pk_fma_f32 v[148:149], v[92:93], s[44:45], v[148:149]
	v_pk_fma_f32 v[150:151], v[94:95], s[44:45], v[150:151]
	v_pk_add_f32 v[152:153], v[136:137], v[138:139]
	v_pk_add_f32 v[152:153], v[152:153], v[140:141]
	v_pk_add_f32 v[152:153], v[152:153], v[142:143]
	v_pk_add_f32 v[152:153], v[152:153], v[144:145]
	v_pk_add_f32 v[152:153], v[152:153], v[146:147]
	v_pk_add_f32 v[152:153], v[152:153], v[148:149]
	v_pk_add_f32 v[152:153], v[152:153], v[150:151]
	v_add_f32_e32 v170, v152, v153
	s_nop 1
	v_add_f32_dpp v168, v170, v170 quad_perm:[1,0,3,2] row_mask:0xf bank_mask:0xf
	s_nop 1
	v_add_f32_dpp v168, v168, v168 quad_perm:[2,3,0,1] row_mask:0xf bank_mask:0xf
	s_nop 1
	v_add_f32_dpp v168, v168, v168 row_half_mirror row_mask:0xf bank_mask:0xf
	s_nop 1
	v_add_f32_dpp v168, v168, v168 row_mirror row_mask:0xf bank_mask:0xf
	s_nop 1
	v_add_f32_dpp v168, v168, v168 row_bcast:15 row_mask:0xa bank_mask:0xf
	s_nop 1
	v_add_f32_dpp v168, v168, v168 row_bcast:31 row_mask:0xc bank_mask:0xf
	s_nop 1
	v_readlane_b32 s42, v168, 63
	s_nop 3
	s_mov_b32 s43, s42
	v_pk_fma_f32 v[136:137], s[42:43], v[172:173], v[136:137]
	v_pk_fma_f32 v[138:139], s[42:43], v[172:173], v[138:139]
	v_pk_fma_f32 v[140:141], s[42:43], v[172:173], v[140:141]
	v_pk_fma_f32 v[142:143], s[42:43], v[172:173], v[142:143]
	v_pk_fma_f32 v[144:145], s[42:43], v[172:173], v[144:145]
	v_pk_fma_f32 v[146:147], s[42:43], v[172:173], v[146:147]
	v_pk_fma_f32 v[148:149], s[42:43], v[172:173], v[148:149]
	v_pk_fma_f32 v[150:151], s[42:43], v[172:173], v[150:151]
	v_pk_mul_f32 v[152:153], v[136:137], v[136:137]
	v_pk_fma_f32 v[152:153], v[138:139], v[138:139], v[152:153]
	v_pk_fma_f32 v[152:153], v[140:141], v[140:141], v[152:153]
	v_pk_fma_f32 v[152:153], v[142:143], v[142:143], v[152:153]
	v_pk_fma_f32 v[152:153], v[144:145], v[144:145], v[152:153]
	v_pk_fma_f32 v[152:153], v[146:147], v[146:147], v[152:153]
	v_pk_fma_f32 v[152:153], v[148:149], v[148:149], v[152:153]
	v_pk_fma_f32 v[152:153], v[150:151], v[150:151], v[152:153]
	v_add_f32_e32 v170, v152, v153
	s_nop 1
	v_add_f32_dpp v168, v170, v170 quad_perm:[1,0,3,2] row_mask:0xf bank_mask:0xf
	s_nop 1
	v_add_f32_dpp v168, v168, v168 quad_perm:[2,3,0,1] row_mask:0xf bank_mask:0xf
	s_nop 1
	v_add_f32_dpp v168, v168, v168 row_half_mirror row_mask:0xf bank_mask:0xf
	s_nop 1
	v_add_f32_dpp v168, v168, v168 row_mirror row_mask:0xf bank_mask:0xf
	s_nop 1
	v_add_f32_dpp v168, v168, v168 row_bcast:15 row_mask:0xa bank_mask:0xf
	s_nop 1
	v_add_f32_dpp v168, v168, v168 row_bcast:31 row_mask:0xc bank_mask:0xf
	s_nop 1
	v_readlane_b32 s42, v168, 63
	s_nop 3
	v_fma_f32 v174, s42, v178, v179
	v_rsq_f32_e32 v174, v174
	s_nop 0
	v_pk_mul_f32 v[136:137], v[136:137], v[174:175] op_sel_hi:[1,0]
	v_pk_mul_f32 v[138:139], v[138:139], v[174:175] op_sel_hi:[1,0]
	v_pk_mul_f32 v[140:141], v[140:141], v[174:175] op_sel_hi:[1,0]
	v_pk_mul_f32 v[142:143], v[142:143], v[174:175] op_sel_hi:[1,0]
	v_pk_mul_f32 v[144:145], v[144:145], v[174:175] op_sel_hi:[1,0]
	v_pk_mul_f32 v[146:147], v[146:147], v[174:175] op_sel_hi:[1,0]
	v_pk_mul_f32 v[148:149], v[148:149], v[174:175] op_sel_hi:[1,0]
	v_pk_mul_f32 v[150:151], v[150:151], v[174:175] op_sel_hi:[1,0]
	v_pk_fma_f32 v[136:137], v[136:137], v[0:1], v[16:17]
	v_pk_fma_f32 v[138:139], v[138:139], v[2:3], v[18:19]
	v_pk_fma_f32 v[140:141], v[140:141], v[4:5], v[20:21]
	v_pk_fma_f32 v[142:143], v[142:143], v[6:7], v[22:23]
	v_pk_fma_f32 v[144:145], v[144:145], v[8:9], v[24:25]
	v_pk_fma_f32 v[146:147], v[146:147], v[10:11], v[26:27]
	v_pk_fma_f32 v[148:149], v[148:149], v[12:13], v[28:29]
	v_pk_fma_f32 v[150:151], v[150:151], v[14:15], v[30:31]
	global_store_dwordx4 v176, v[136:139], s[8:9] offset:0
	global_store_dwordx4 v176, v[140:143], s[8:9] offset:1024
	global_store_dwordx4 v176, v[144:147], s[8:9] offset:2048
	global_store_dwordx4 v176, v[148:151], s[8:9] offset:3072
	v_pk_add_f32 v[152:153], v[136:137], v[138:139]
	v_pk_add_f32 v[152:153], v[152:153], v[140:141]
	v_pk_add_f32 v[152:153], v[152:153], v[142:143]
	v_pk_add_f32 v[152:153], v[152:153], v[144:145]
	v_pk_add_f32 v[152:153], v[152:153], v[146:147]
	v_pk_add_f32 v[152:153], v[152:153], v[148:149]
	v_pk_add_f32 v[152:153], v[152:153], v[150:151]
	v_add_f32_e32 v170, v152, v153
	s_nop 1
	v_add_f32_dpp v168, v170, v170 quad_perm:[1,0,3,2] row_mask:0xf bank_mask:0xf
	s_nop 1
	v_add_f32_dpp v168, v168, v168 quad_perm:[2,3,0,1] row_mask:0xf bank_mask:0xf
	s_nop 1
	v_add_f32_dpp v168, v168, v168 row_half_mirror row_mask:0xf bank_mask:0xf
	s_nop 1
	v_add_f32_dpp v168, v168, v168 row_mirror row_mask:0xf bank_mask:0xf
	s_nop 1
	v_add_f32_dpp v168, v168, v168 row_bcast:15 row_mask:0xa bank_mask:0xf
	s_nop 1
	v_add_f32_dpp v168, v168, v168 row_bcast:31 row_mask:0xc bank_mask:0xf
	s_nop 1
	v_readlane_b32 s42, v168, 63
	s_nop 3
	s_mov_b32 s43, s42
	v_pk_fma_f32 v[136:137], s[42:43], v[172:173], v[136:137]
	v_pk_fma_f32 v[138:139], s[42:43], v[172:173], v[138:139]
	v_pk_fma_f32 v[140:141], s[42:43], v[172:173], v[140:141]
	v_pk_fma_f32 v[142:143], s[42:43], v[172:173], v[142:143]
	v_pk_fma_f32 v[144:145], s[42:43], v[172:173], v[144:145]
	v_pk_fma_f32 v[146:147], s[42:43], v[172:173], v[146:147]
	v_pk_fma_f32 v[148:149], s[42:43], v[172:173], v[148:149]
	v_pk_fma_f32 v[150:151], s[42:43], v[172:173], v[150:151]
	v_pk_mul_f32 v[152:153], v[136:137], v[136:137]
	v_pk_fma_f32 v[152:153], v[138:139], v[138:139], v[152:153]
	v_pk_fma_f32 v[152:153], v[140:141], v[140:141], v[152:153]
	v_pk_fma_f32 v[152:153], v[142:143], v[142:143], v[152:153]
	v_pk_fma_f32 v[152:153], v[144:145], v[144:145], v[152:153]
	v_pk_fma_f32 v[152:153], v[146:147], v[146:147], v[152:153]
	v_pk_fma_f32 v[152:153], v[148:149], v[148:149], v[152:153]
	v_pk_fma_f32 v[152:153], v[150:151], v[150:151], v[152:153]
	v_add_f32_e32 v170, v152, v153
	s_nop 1
	v_add_f32_dpp v168, v170, v170 quad_perm:[1,0,3,2] row_mask:0xf bank_mask:0xf
	s_nop 1
	v_add_f32_dpp v168, v168, v168 quad_perm:[2,3,0,1] row_mask:0xf bank_mask:0xf
	s_nop 1
	v_add_f32_dpp v168, v168, v168 row_half_mirror row_mask:0xf bank_mask:0xf
	s_nop 1
	v_add_f32_dpp v168, v168, v168 row_mirror row_mask:0xf bank_mask:0xf
	s_nop 1
	v_add_f32_dpp v168, v168, v168 row_bcast:15 row_mask:0xa bank_mask:0xf
	s_nop 1
	v_add_f32_dpp v168, v168, v168 row_bcast:31 row_mask:0xc bank_mask:0xf
	s_nop 1
	v_readlane_b32 s42, v168, 63
	s_nop 3
	v_fma_f32 v174, s42, v178, v179
	v_rsq_f32_e32 v174, v174
	s_nop 0
	v_pk_mul_f32 v[136:137], v[136:137], v[174:175] op_sel_hi:[1,0]
	v_pk_mul_f32 v[138:139], v[138:139], v[174:175] op_sel_hi:[1,0]
	v_pk_mul_f32 v[140:141], v[140:141], v[174:175] op_sel_hi:[1,0]
	v_pk_mul_f32 v[142:143], v[142:143], v[174:175] op_sel_hi:[1,0]
	v_pk_mul_f32 v[144:145], v[144:145], v[174:175] op_sel_hi:[1,0]
	v_pk_mul_f32 v[146:147], v[146:147], v[174:175] op_sel_hi:[1,0]
	v_pk_mul_f32 v[148:149], v[148:149], v[174:175] op_sel_hi:[1,0]
	v_pk_mul_f32 v[150:151], v[150:151], v[174:175] op_sel_hi:[1,0]
	v_pk_fma_f32 v[136:137], v[136:137], v[32:33], v[48:49]
	v_pk_fma_f32 v[138:139], v[138:139], v[34:35], v[50:51]
	v_pk_fma_f32 v[140:141], v[140:141], v[36:37], v[52:53]
	v_pk_fma_f32 v[142:143], v[142:143], v[38:39], v[54:55]
	v_pk_fma_f32 v[144:145], v[144:145], v[40:41], v[56:57]
	v_pk_fma_f32 v[146:147], v[146:147], v[42:43], v[58:59]
	v_pk_fma_f32 v[148:149], v[148:149], v[44:45], v[60:61]
	v_pk_fma_f32 v[150:151], v[150:151], v[46:47], v[62:63]
	v_cvt_pk_bf16_f32 v152, v136, v137
	v_cvt_pk_bf16_f32 v153, v138, v139
	v_cvt_pk_bf16_f32 v154, v140, v141
	v_cvt_pk_bf16_f32 v155, v142, v143
	v_cvt_pk_bf16_f32 v156, v144, v145
	v_cvt_pk_bf16_f32 v157, v146, v147
	v_cvt_pk_bf16_f32 v158, v148, v149
	v_cvt_pk_bf16_f32 v159, v150, v151
	global_store_dwordx2 v177, v[152:153], s[12:13] offset:0
	global_store_dwordx2 v177, v[154:155], s[12:13] offset:512
	global_store_dwordx2 v177, v[156:157], s[12:13] offset:1024
	global_store_dwordx2 v177, v[158:159], s[12:13] offset:1536
	s_add_u32 s8, s8, 0x80000
	s_addc_u32 s9, s9, 0
	s_add_u32 s12, s12, 0x40000
	s_addc_u32 s13, s13, 0
	global_load_dwordx4 v[80:83], v176, s[2:3] offset:0
	global_load_dwordx4 v[84:87], v176, s[2:3] offset:1024
	global_load_dwordx4 v[88:91], v176, s[2:3] offset:2048
	global_load_dwordx4 v[92:95], v176, s[2:3] offset:3072
	global_load_dwordx2 v[120:121], v177, s[6:7] offset:0
	global_load_dwordx2 v[122:123], v177, s[6:7] offset:512
	global_load_dwordx2 v[124:125], v177, s[6:7] offset:1024
	global_load_dwordx2 v[126:127], v177, s[6:7] offset:1536
	s_add_u32 s2, s2, 0x80000
	s_addc_u32 s3, s3, 0
	s_add_u32 s6, s6, 0x40000
	s_addc_u32 s7, s7, 0
	s_waitcnt vmcnt(32)
	v_lshlrev_b32_e32 v136, 16, v128
	v_and_b32_e32 v137, 0xffff0000, v128
	v_lshlrev_b32_e32 v138, 16, v129
	v_and_b32_e32 v139, 0xffff0000, v129
	v_lshlrev_b32_e32 v140, 16, v130
	v_and_b32_e32 v141, 0xffff0000, v130
	v_lshlrev_b32_e32 v142, 16, v131
	v_and_b32_e32 v143, 0xffff0000, v131
	v_lshlrev_b32_e32 v144, 16, v132
	v_and_b32_e32 v145, 0xffff0000, v132
	v_lshlrev_b32_e32 v146, 16, v133
	v_and_b32_e32 v147, 0xffff0000, v133
	v_lshlrev_b32_e32 v148, 16, v134
	v_and_b32_e32 v149, 0xffff0000, v134
	v_lshlrev_b32_e32 v150, 16, v135
	v_and_b32_e32 v151, 0xffff0000, v135
	v_pk_fma_f32 v[136:137], v[96:97], s[44:45], v[136:137]
	v_pk_fma_f32 v[138:139], v[98:99], s[44:45], v[138:139]
	v_pk_fma_f32 v[140:141], v[100:101], s[44:45], v[140:141]
	v_pk_fma_f32 v[142:143], v[102:103], s[44:45], v[142:143]
	v_pk_fma_f32 v[144:145], v[104:105], s[44:45], v[144:145]
	v_pk_fma_f32 v[146:147], v[106:107], s[44:45], v[146:147]
	v_pk_fma_f32 v[148:149], v[108:109], s[44:45], v[148:149]
	v_pk_fma_f32 v[150:151], v[110:111], s[44:45], v[150:151]
	v_pk_add_f32 v[152:153], v[136:137], v[138:139]
	v_pk_add_f32 v[152:153], v[152:153], v[140:141]
	v_pk_add_f32 v[152:153], v[152:153], v[142:143]
	v_pk_add_f32 v[152:153], v[152:153], v[144:145]
	v_pk_add_f32 v[152:153], v[152:153], v[146:147]
	v_pk_add_f32 v[152:153], v[152:153], v[148:149]
	v_pk_add_f32 v[152:153], v[152:153], v[150:151]
	v_add_f32_e32 v170, v152, v153
	s_nop 1
	v_add_f32_dpp v168, v170, v170 quad_perm:[1,0,3,2] row_mask:0xf bank_mask:0xf
	s_nop 1
	v_add_f32_dpp v168, v168, v168 quad_perm:[2,3,0,1] row_mask:0xf bank_mask:0xf
	s_nop 1
	v_add_f32_dpp v168, v168, v168 row_half_mirror row_mask:0xf bank_mask:0xf
	s_nop 1
	v_add_f32_dpp v168, v168, v168 row_mirror row_mask:0xf bank_mask:0xf
	s_nop 1
	v_add_f32_dpp v168, v168, v168 row_bcast:15 row_mask:0xa bank_mask:0xf
	s_nop 1
	v_add_f32_dpp v168, v168, v168 row_bcast:31 row_mask:0xc bank_mask:0xf
	s_nop 1
	v_readlane_b32 s42, v168, 63
	s_nop 3
	s_mov_b32 s43, s42
	v_pk_fma_f32 v[136:137], s[42:43], v[172:173], v[136:137]
	v_pk_fma_f32 v[138:139], s[42:43], v[172:173], v[138:139]
	v_pk_fma_f32 v[140:141], s[42:43], v[172:173], v[140:141]
	v_pk_fma_f32 v[142:143], s[42:43], v[172:173], v[142:143]
	v_pk_fma_f32 v[144:145], s[42:43], v[172:173], v[144:145]
	v_pk_fma_f32 v[146:147], s[42:43], v[172:173], v[146:147]
	v_pk_fma_f32 v[148:149], s[42:43], v[172:173], v[148:149]
	v_pk_fma_f32 v[150:151], s[42:43], v[172:173], v[150:151]
	v_pk_mul_f32 v[152:153], v[136:137], v[136:137]
	v_pk_fma_f32 v[152:153], v[138:139], v[138:139], v[152:153]
	v_pk_fma_f32 v[152:153], v[140:141], v[140:141], v[152:153]
	v_pk_fma_f32 v[152:153], v[142:143], v[142:143], v[152:153]
	v_pk_fma_f32 v[152:153], v[144:145], v[144:145], v[152:153]
	v_pk_fma_f32 v[152:153], v[146:147], v[146:147], v[152:153]
	v_pk_fma_f32 v[152:153], v[148:149], v[148:149], v[152:153]
	v_pk_fma_f32 v[152:153], v[150:151], v[150:151], v[152:153]
	v_add_f32_e32 v170, v152, v153
	s_nop 1
	v_add_f32_dpp v168, v170, v170 quad_perm:[1,0,3,2] row_mask:0xf bank_mask:0xf
	s_nop 1
	v_add_f32_dpp v168, v168, v168 quad_perm:[2,3,0,1] row_mask:0xf bank_mask:0xf
	s_nop 1
	v_add_f32_dpp v168, v168, v168 row_half_mirror row_mask:0xf bank_mask:0xf
	s_nop 1
	v_add_f32_dpp v168, v168, v168 row_mirror row_mask:0xf bank_mask:0xf
	s_nop 1
	v_add_f32_dpp v168, v168, v168 row_bcast:15 row_mask:0xa bank_mask:0xf
	s_nop 1
	v_add_f32_dpp v168, v168, v168 row_bcast:31 row_mask:0xc bank_mask:0xf
	s_nop 1
	v_readlane_b32 s42, v168, 63
	s_nop 3
	v_fma_f32 v174, s42, v178, v179
	v_rsq_f32_e32 v174, v174
	s_nop 0
	v_pk_mul_f32 v[136:137], v[136:137], v[174:175] op_sel_hi:[1,0]
	v_pk_mul_f32 v[138:139], v[138:139], v[174:175] op_sel_hi:[1,0]
	v_pk_mul_f32 v[140:141], v[140:141], v[174:175] op_sel_hi:[1,0]
	v_pk_mul_f32 v[142:143], v[142:143], v[174:175] op_sel_hi:[1,0]
	v_pk_mul_f32 v[144:145], v[144:145], v[174:175] op_sel_hi:[1,0]
	v_pk_mul_f32 v[146:147], v[146:147], v[174:175] op_sel_hi:[1,0]
	v_pk_mul_f32 v[148:149], v[148:149], v[174:175] op_sel_hi:[1,0]
	v_pk_mul_f32 v[150:151], v[150:151], v[174:175] op_sel_hi:[1,0]
	v_pk_fma_f32 v[136:137], v[136:137], v[0:1], v[16:17]
	v_pk_fma_f32 v[138:139], v[138:139], v[2:3], v[18:19]
	v_pk_fma_f32 v[140:141], v[140:141], v[4:5], v[20:21]
	v_pk_fma_f32 v[142:143], v[142:143], v[6:7], v[22:23]
	v_pk_fma_f32 v[144:145], v[144:145], v[8:9], v[24:25]
	v_pk_fma_f32 v[146:147], v[146:147], v[10:11], v[26:27]
	v_pk_fma_f32 v[148:149], v[148:149], v[12:13], v[28:29]
	v_pk_fma_f32 v[150:151], v[150:151], v[14:15], v[30:31]
	global_store_dwordx4 v176, v[136:139], s[8:9] offset:0
	global_store_dwordx4 v176, v[140:143], s[8:9] offset:1024
	global_store_dwordx4 v176, v[144:147], s[8:9] offset:2048
	global_store_dwordx4 v176, v[148:151], s[8:9] offset:3072
	v_pk_add_f32 v[152:153], v[136:137], v[138:139]
	v_pk_add_f32 v[152:153], v[152:153], v[140:141]
	v_pk_add_f32 v[152:153], v[152:153], v[142:143]
	v_pk_add_f32 v[152:153], v[152:153], v[144:145]
	v_pk_add_f32 v[152:153], v[152:153], v[146:147]
	v_pk_add_f32 v[152:153], v[152:153], v[148:149]
	v_pk_add_f32 v[152:153], v[152:153], v[150:151]
	v_add_f32_e32 v170, v152, v153
	s_nop 1
	v_add_f32_dpp v168, v170, v170 quad_perm:[1,0,3,2] row_mask:0xf bank_mask:0xf
	s_nop 1
	v_add_f32_dpp v168, v168, v168 quad_perm:[2,3,0,1] row_mask:0xf bank_mask:0xf
	s_nop 1
	v_add_f32_dpp v168, v168, v168 row_half_mirror row_mask:0xf bank_mask:0xf
	s_nop 1
	v_add_f32_dpp v168, v168, v168 row_mirror row_mask:0xf bank_mask:0xf
	s_nop 1
	v_add_f32_dpp v168, v168, v168 row_bcast:15 row_mask:0xa bank_mask:0xf
	s_nop 1
	v_add_f32_dpp v168, v168, v168 row_bcast:31 row_mask:0xc bank_mask:0xf
	s_nop 1
	v_readlane_b32 s42, v168, 63
	s_nop 3
	s_mov_b32 s43, s42
	v_pk_fma_f32 v[136:137], s[42:43], v[172:173], v[136:137]
	v_pk_fma_f32 v[138:139], s[42:43], v[172:173], v[138:139]
	v_pk_fma_f32 v[140:141], s[42:43], v[172:173], v[140:141]
	v_pk_fma_f32 v[142:143], s[42:43], v[172:173], v[142:143]
	v_pk_fma_f32 v[144:145], s[42:43], v[172:173], v[144:145]
	v_pk_fma_f32 v[146:147], s[42:43], v[172:173], v[146:147]
	v_pk_fma_f32 v[148:149], s[42:43], v[172:173], v[148:149]
	v_pk_fma_f32 v[150:151], s[42:43], v[172:173], v[150:151]
	v_pk_mul_f32 v[152:153], v[136:137], v[136:137]
	v_pk_fma_f32 v[152:153], v[138:139], v[138:139], v[152:153]
	v_pk_fma_f32 v[152:153], v[140:141], v[140:141], v[152:153]
	v_pk_fma_f32 v[152:153], v[142:143], v[142:143], v[152:153]
	v_pk_fma_f32 v[152:153], v[144:145], v[144:145], v[152:153]
	v_pk_fma_f32 v[152:153], v[146:147], v[146:147], v[152:153]
	v_pk_fma_f32 v[152:153], v[148:149], v[148:149], v[152:153]
	v_pk_fma_f32 v[152:153], v[150:151], v[150:151], v[152:153]
	v_add_f32_e32 v170, v152, v153
	s_nop 1
	v_add_f32_dpp v168, v170, v170 quad_perm:[1,0,3,2] row_mask:0xf bank_mask:0xf
	s_nop 1
	v_add_f32_dpp v168, v168, v168 quad_perm:[2,3,0,1] row_mask:0xf bank_mask:0xf
	s_nop 1
	v_add_f32_dpp v168, v168, v168 row_half_mirror row_mask:0xf bank_mask:0xf
	s_nop 1
	v_add_f32_dpp v168, v168, v168 row_mirror row_mask:0xf bank_mask:0xf
	s_nop 1
	v_add_f32_dpp v168, v168, v168 row_bcast:15 row_mask:0xa bank_mask:0xf
	s_nop 1
	v_add_f32_dpp v168, v168, v168 row_bcast:31 row_mask:0xc bank_mask:0xf
	s_nop 1
	v_readlane_b32 s42, v168, 63
	s_nop 3
	v_fma_f32 v174, s42, v178, v179
	v_rsq_f32_e32 v174, v174
	s_nop 0
	v_pk_mul_f32 v[136:137], v[136:137], v[174:175] op_sel_hi:[1,0]
	v_pk_mul_f32 v[138:139], v[138:139], v[174:175] op_sel_hi:[1,0]
	v_pk_mul_f32 v[140:141], v[140:141], v[174:175] op_sel_hi:[1,0]
	v_pk_mul_f32 v[142:143], v[142:143], v[174:175] op_sel_hi:[1,0]
	v_pk_mul_f32 v[144:145], v[144:145], v[174:175] op_sel_hi:[1,0]
	v_pk_mul_f32 v[146:147], v[146:147], v[174:175] op_sel_hi:[1,0]
	v_pk_mul_f32 v[148:149], v[148:149], v[174:175] op_sel_hi:[1,0]
	v_pk_mul_f32 v[150:151], v[150:151], v[174:175] op_sel_hi:[1,0]
	v_pk_fma_f32 v[136:137], v[136:137], v[32:33], v[48:49]
	v_pk_fma_f32 v[138:139], v[138:139], v[34:35], v[50:51]
	v_pk_fma_f32 v[140:141], v[140:141], v[36:37], v[52:53]
	v_pk_fma_f32 v[142:143], v[142:143], v[38:39], v[54:55]
	v_pk_fma_f32 v[144:145], v[144:145], v[40:41], v[56:57]
	v_pk_fma_f32 v[146:147], v[146:147], v[42:43], v[58:59]
	v_pk_fma_f32 v[148:149], v[148:149], v[44:45], v[60:61]
	v_pk_fma_f32 v[150:151], v[150:151], v[46:47], v[62:63]
	v_cvt_pk_bf16_f32 v152, v136, v137
	v_cvt_pk_bf16_f32 v153, v138, v139
	v_cvt_pk_bf16_f32 v154, v140, v141
	v_cvt_pk_bf16_f32 v155, v142, v143
	v_cvt_pk_bf16_f32 v156, v144, v145
	v_cvt_pk_bf16_f32 v157, v146, v147
	v_cvt_pk_bf16_f32 v158, v148, v149
	v_cvt_pk_bf16_f32 v159, v150, v151
	global_store_dwordx2 v177, v[152:153], s[12:13] offset:0
	global_store_dwordx2 v177, v[154:155], s[12:13] offset:512
	global_store_dwordx2 v177, v[156:157], s[12:13] offset:1024
	global_store_dwordx2 v177, v[158:159], s[12:13] offset:1536
	s_add_u32 s8, s8, 0x80000
	s_addc_u32 s9, s9, 0
	s_add_u32 s12, s12, 0x40000
	s_addc_u32 s13, s13, 0
	global_load_dwordx4 v[96:99], v176, s[2:3] offset:0
	global_load_dwordx4 v[100:103], v176, s[2:3] offset:1024
	global_load_dwordx4 v[104:107], v176, s[2:3] offset:2048
	global_load_dwordx4 v[108:111], v176, s[2:3] offset:3072
	global_load_dwordx2 v[128:129], v177, s[6:7] offset:0
	global_load_dwordx2 v[130:131], v177, s[6:7] offset:512
	global_load_dwordx2 v[132:133], v177, s[6:7] offset:1024
	global_load_dwordx2 v[134:135], v177, s[6:7] offset:1536
	s_add_u32 s2, s2, 0x80000
	s_addc_u32 s3, s3, 0
	s_add_u32 s6, s6, 0x40000
	s_addc_u32 s7, s7, 0
	s_waitcnt vmcnt(32)
	v_lshlrev_b32_e32 v136, 16, v112
	v_and_b32_e32 v137, 0xffff0000, v112
	v_lshlrev_b32_e32 v138, 16, v113
	v_and_b32_e32 v139, 0xffff0000, v113
	v_lshlrev_b32_e32 v140, 16, v114
	v_and_b32_e32 v141, 0xffff0000, v114
	v_lshlrev_b32_e32 v142, 16, v115
	v_and_b32_e32 v143, 0xffff0000, v115
	v_lshlrev_b32_e32 v144, 16, v116
	v_and_b32_e32 v145, 0xffff0000, v116
	v_lshlrev_b32_e32 v146, 16, v117
	v_and_b32_e32 v147, 0xffff0000, v117
	v_lshlrev_b32_e32 v148, 16, v118
	v_and_b32_e32 v149, 0xffff0000, v118
	v_lshlrev_b32_e32 v150, 16, v119
	v_and_b32_e32 v151, 0xffff0000, v119
	v_pk_fma_f32 v[136:137], v[64:65], s[44:45], v[136:137]
	v_pk_fma_f32 v[138:139], v[66:67], s[44:45], v[138:139]
	v_pk_fma_f32 v[140:141], v[68:69], s[44:45], v[140:141]
	v_pk_fma_f32 v[142:143], v[70:71], s[44:45], v[142:143]
	v_pk_fma_f32 v[144:145], v[72:73], s[44:45], v[144:145]
	v_pk_fma_f32 v[146:147], v[74:75], s[44:45], v[146:147]
	v_pk_fma_f32 v[148:149], v[76:77], s[44:45], v[148:149]
	v_pk_fma_f32 v[150:151], v[78:79], s[44:45], v[150:151]
	v_pk_add_f32 v[152:153], v[136:137], v[138:139]
	v_pk_add_f32 v[152:153], v[152:153], v[140:141]
	v_pk_add_f32 v[152:153], v[152:153], v[142:143]
	v_pk_add_f32 v[152:153], v[152:153], v[144:145]
	v_pk_add_f32 v[152:153], v[152:153], v[146:147]
	v_pk_add_f32 v[152:153], v[152:153], v[148:149]
	v_pk_add_f32 v[152:153], v[152:153], v[150:151]
	v_add_f32_e32 v170, v152, v153
	s_nop 1
	v_add_f32_dpp v168, v170, v170 quad_perm:[1,0,3,2] row_mask:0xf bank_mask:0xf
	s_nop 1
	v_add_f32_dpp v168, v168, v168 quad_perm:[2,3,0,1] row_mask:0xf bank_mask:0xf
	s_nop 1
	v_add_f32_dpp v168, v168, v168 row_half_mirror row_mask:0xf bank_mask:0xf
	s_nop 1
	v_add_f32_dpp v168, v168, v168 row_mirror row_mask:0xf bank_mask:0xf
	s_nop 1
	v_add_f32_dpp v168, v168, v168 row_bcast:15 row_mask:0xa bank_mask:0xf
	s_nop 1
	v_add_f32_dpp v168, v168, v168 row_bcast:31 row_mask:0xc bank_mask:0xf
	s_nop 1
	v_readlane_b32 s42, v168, 63
	s_nop 3
	s_mov_b32 s43, s42
	v_pk_fma_f32 v[136:137], s[42:43], v[172:173], v[136:137]
	v_pk_fma_f32 v[138:139], s[42:43], v[172:173], v[138:139]
	v_pk_fma_f32 v[140:141], s[42:43], v[172:173], v[140:141]
	v_pk_fma_f32 v[142:143], s[42:43], v[172:173], v[142:143]
	v_pk_fma_f32 v[144:145], s[42:43], v[172:173], v[144:145]
	v_pk_fma_f32 v[146:147], s[42:43], v[172:173], v[146:147]
	v_pk_fma_f32 v[148:149], s[42:43], v[172:173], v[148:149]
	v_pk_fma_f32 v[150:151], s[42:43], v[172:173], v[150:151]
	v_pk_mul_f32 v[152:153], v[136:137], v[136:137]
	v_pk_fma_f32 v[152:153], v[138:139], v[138:139], v[152:153]
	v_pk_fma_f32 v[152:153], v[140:141], v[140:141], v[152:153]
	v_pk_fma_f32 v[152:153], v[142:143], v[142:143], v[152:153]
	v_pk_fma_f32 v[152:153], v[144:145], v[144:145], v[152:153]
	v_pk_fma_f32 v[152:153], v[146:147], v[146:147], v[152:153]
	v_pk_fma_f32 v[152:153], v[148:149], v[148:149], v[152:153]
	v_pk_fma_f32 v[152:153], v[150:151], v[150:151], v[152:153]
	v_add_f32_e32 v170, v152, v153
	s_nop 1
	v_add_f32_dpp v168, v170, v170 quad_perm:[1,0,3,2] row_mask:0xf bank_mask:0xf
	s_nop 1
	v_add_f32_dpp v168, v168, v168 quad_perm:[2,3,0,1] row_mask:0xf bank_mask:0xf
	s_nop 1
	v_add_f32_dpp v168, v168, v168 row_half_mirror row_mask:0xf bank_mask:0xf
	s_nop 1
	v_add_f32_dpp v168, v168, v168 row_mirror row_mask:0xf bank_mask:0xf
	s_nop 1
	v_add_f32_dpp v168, v168, v168 row_bcast:15 row_mask:0xa bank_mask:0xf
	s_nop 1
	v_add_f32_dpp v168, v168, v168 row_bcast:31 row_mask:0xc bank_mask:0xf
	s_nop 1
	v_readlane_b32 s42, v168, 63
	s_nop 3
	v_fma_f32 v174, s42, v178, v179
	v_rsq_f32_e32 v174, v174
	s_nop 0
	v_pk_mul_f32 v[136:137], v[136:137], v[174:175] op_sel_hi:[1,0]
	v_pk_mul_f32 v[138:139], v[138:139], v[174:175] op_sel_hi:[1,0]
	v_pk_mul_f32 v[140:141], v[140:141], v[174:175] op_sel_hi:[1,0]
	v_pk_mul_f32 v[142:143], v[142:143], v[174:175] op_sel_hi:[1,0]
	v_pk_mul_f32 v[144:145], v[144:145], v[174:175] op_sel_hi:[1,0]
	v_pk_mul_f32 v[146:147], v[146:147], v[174:175] op_sel_hi:[1,0]
	v_pk_mul_f32 v[148:149], v[148:149], v[174:175] op_sel_hi:[1,0]
	v_pk_mul_f32 v[150:151], v[150:151], v[174:175] op_sel_hi:[1,0]
	v_pk_fma_f32 v[136:137], v[136:137], v[0:1], v[16:17]
	v_pk_fma_f32 v[138:139], v[138:139], v[2:3], v[18:19]
	v_pk_fma_f32 v[140:141], v[140:141], v[4:5], v[20:21]
	v_pk_fma_f32 v[142:143], v[142:143], v[6:7], v[22:23]
	v_pk_fma_f32 v[144:145], v[144:145], v[8:9], v[24:25]
	v_pk_fma_f32 v[146:147], v[146:147], v[10:11], v[26:27]
	v_pk_fma_f32 v[148:149], v[148:149], v[12:13], v[28:29]
	v_pk_fma_f32 v[150:151], v[150:151], v[14:15], v[30:31]
	global_store_dwordx4 v176, v[136:139], s[8:9] offset:0
	global_store_dwordx4 v176, v[140:143], s[8:9] offset:1024
	global_store_dwordx4 v176, v[144:147], s[8:9] offset:2048
	global_store_dwordx4 v176, v[148:151], s[8:9] offset:3072
	v_pk_add_f32 v[152:153], v[136:137], v[138:139]
	v_pk_add_f32 v[152:153], v[152:153], v[140:141]
	v_pk_add_f32 v[152:153], v[152:153], v[142:143]
	v_pk_add_f32 v[152:153], v[152:153], v[144:145]
	v_pk_add_f32 v[152:153], v[152:153], v[146:147]
	v_pk_add_f32 v[152:153], v[152:153], v[148:149]
	v_pk_add_f32 v[152:153], v[152:153], v[150:151]
	v_add_f32_e32 v170, v152, v153
	s_nop 1
	v_add_f32_dpp v168, v170, v170 quad_perm:[1,0,3,2] row_mask:0xf bank_mask:0xf
	s_nop 1
	v_add_f32_dpp v168, v168, v168 quad_perm:[2,3,0,1] row_mask:0xf bank_mask:0xf
	s_nop 1
	v_add_f32_dpp v168, v168, v168 row_half_mirror row_mask:0xf bank_mask:0xf
	s_nop 1
	v_add_f32_dpp v168, v168, v168 row_mirror row_mask:0xf bank_mask:0xf
	s_nop 1
	v_add_f32_dpp v168, v168, v168 row_bcast:15 row_mask:0xa bank_mask:0xf
	s_nop 1
	v_add_f32_dpp v168, v168, v168 row_bcast:31 row_mask:0xc bank_mask:0xf
	s_nop 1
	v_readlane_b32 s42, v168, 63
	s_nop 3
	s_mov_b32 s43, s42
	v_pk_fma_f32 v[136:137], s[42:43], v[172:173], v[136:137]
	v_pk_fma_f32 v[138:139], s[42:43], v[172:173], v[138:139]
	v_pk_fma_f32 v[140:141], s[42:43], v[172:173], v[140:141]
	v_pk_fma_f32 v[142:143], s[42:43], v[172:173], v[142:143]
	v_pk_fma_f32 v[144:145], s[42:43], v[172:173], v[144:145]
	v_pk_fma_f32 v[146:147], s[42:43], v[172:173], v[146:147]
	v_pk_fma_f32 v[148:149], s[42:43], v[172:173], v[148:149]
	v_pk_fma_f32 v[150:151], s[42:43], v[172:173], v[150:151]
	v_pk_mul_f32 v[152:153], v[136:137], v[136:137]
	v_pk_fma_f32 v[152:153], v[138:139], v[138:139], v[152:153]
	v_pk_fma_f32 v[152:153], v[140:141], v[140:141], v[152:153]
	v_pk_fma_f32 v[152:153], v[142:143], v[142:143], v[152:153]
	v_pk_fma_f32 v[152:153], v[144:145], v[144:145], v[152:153]
	v_pk_fma_f32 v[152:153], v[146:147], v[146:147], v[152:153]
	v_pk_fma_f32 v[152:153], v[148:149], v[148:149], v[152:153]
	v_pk_fma_f32 v[152:153], v[150:151], v[150:151], v[152:153]
	v_add_f32_e32 v170, v152, v153
	s_nop 1
	v_add_f32_dpp v168, v170, v170 quad_perm:[1,0,3,2] row_mask:0xf bank_mask:0xf
	s_nop 1
	v_add_f32_dpp v168, v168, v168 quad_perm:[2,3,0,1] row_mask:0xf bank_mask:0xf
	s_nop 1
	v_add_f32_dpp v168, v168, v168 row_half_mirror row_mask:0xf bank_mask:0xf
	s_nop 1
	v_add_f32_dpp v168, v168, v168 row_mirror row_mask:0xf bank_mask:0xf
	s_nop 1
	v_add_f32_dpp v168, v168, v168 row_bcast:15 row_mask:0xa bank_mask:0xf
	s_nop 1
	v_add_f32_dpp v168, v168, v168 row_bcast:31 row_mask:0xc bank_mask:0xf
	s_nop 1
	v_readlane_b32 s42, v168, 63
	s_nop 3
	v_fma_f32 v174, s42, v178, v179
	v_rsq_f32_e32 v174, v174
	s_nop 0
	v_pk_mul_f32 v[136:137], v[136:137], v[174:175] op_sel_hi:[1,0]
	v_pk_mul_f32 v[138:139], v[138:139], v[174:175] op_sel_hi:[1,0]
	v_pk_mul_f32 v[140:141], v[140:141], v[174:175] op_sel_hi:[1,0]
	v_pk_mul_f32 v[142:143], v[142:143], v[174:175] op_sel_hi:[1,0]
	v_pk_mul_f32 v[144:145], v[144:145], v[174:175] op_sel_hi:[1,0]
	v_pk_mul_f32 v[146:147], v[146:147], v[174:175] op_sel_hi:[1,0]
	v_pk_mul_f32 v[148:149], v[148:149], v[174:175] op_sel_hi:[1,0]
	v_pk_mul_f32 v[150:151], v[150:151], v[174:175] op_sel_hi:[1,0]
	v_pk_fma_f32 v[136:137], v[136:137], v[32:33], v[48:49]
	v_pk_fma_f32 v[138:139], v[138:139], v[34:35], v[50:51]
	v_pk_fma_f32 v[140:141], v[140:141], v[36:37], v[52:53]
	v_pk_fma_f32 v[142:143], v[142:143], v[38:39], v[54:55]
	v_pk_fma_f32 v[144:145], v[144:145], v[40:41], v[56:57]
	v_pk_fma_f32 v[146:147], v[146:147], v[42:43], v[58:59]
	v_pk_fma_f32 v[148:149], v[148:149], v[44:45], v[60:61]
	v_pk_fma_f32 v[150:151], v[150:151], v[46:47], v[62:63]
	v_cvt_pk_bf16_f32 v152, v136, v137
	v_cvt_pk_bf16_f32 v153, v138, v139
	v_cvt_pk_bf16_f32 v154, v140, v141
	v_cvt_pk_bf16_f32 v155, v142, v143
	v_cvt_pk_bf16_f32 v156, v144, v145
	v_cvt_pk_bf16_f32 v157, v146, v147
	v_cvt_pk_bf16_f32 v158, v148, v149
	v_cvt_pk_bf16_f32 v159, v150, v151
	global_store_dwordx2 v177, v[152:153], s[12:13] offset:0
	global_store_dwordx2 v177, v[154:155], s[12:13] offset:512
	global_store_dwordx2 v177, v[156:157], s[12:13] offset:1024
	global_store_dwordx2 v177, v[158:159], s[12:13] offset:1536
	s_add_u32 s8, s8, 0x80000
	s_addc_u32 s9, s9, 0
	s_add_u32 s12, s12, 0x40000
	s_addc_u32 s13, s13, 0
	global_load_dwordx4 v[64:67], v176, s[2:3] offset:0
	global_load_dwordx4 v[68:71], v176, s[2:3] offset:1024
	global_load_dwordx4 v[72:75], v176, s[2:3] offset:2048
	global_load_dwordx4 v[76:79], v176, s[2:3] offset:3072
	global_load_dwordx2 v[112:113], v177, s[6:7] offset:0
	global_load_dwordx2 v[114:115], v177, s[6:7] offset:512
	global_load_dwordx2 v[116:117], v177, s[6:7] offset:1024
	global_load_dwordx2 v[118:119], v177, s[6:7] offset:1536
	s_add_u32 s2, s2, 0x80000
	s_addc_u32 s3, s3, 0
	s_add_u32 s6, s6, 0x40000
	s_addc_u32 s7, s7, 0
	s_waitcnt vmcnt(32)
	v_lshlrev_b32_e32 v136, 16, v120
	v_and_b32_e32 v137, 0xffff0000, v120
	v_lshlrev_b32_e32 v138, 16, v121
	v_and_b32_e32 v139, 0xffff0000, v121
	v_lshlrev_b32_e32 v140, 16, v122
	v_and_b32_e32 v141, 0xffff0000, v122
	v_lshlrev_b32_e32 v142, 16, v123
	v_and_b32_e32 v143, 0xffff0000, v123
	v_lshlrev_b32_e32 v144, 16, v124
	v_and_b32_e32 v145, 0xffff0000, v124
	v_lshlrev_b32_e32 v146, 16, v125
	v_and_b32_e32 v147, 0xffff0000, v125
	v_lshlrev_b32_e32 v148, 16, v126
	v_and_b32_e32 v149, 0xffff0000, v126
	v_lshlrev_b32_e32 v150, 16, v127
	v_and_b32_e32 v151, 0xffff0000, v127
	v_pk_fma_f32 v[136:137], v[80:81], s[44:45], v[136:137]
	v_pk_fma_f32 v[138:139], v[82:83], s[44:45], v[138:139]
	v_pk_fma_f32 v[140:141], v[84:85], s[44:45], v[140:141]
	v_pk_fma_f32 v[142:143], v[86:87], s[44:45], v[142:143]
	v_pk_fma_f32 v[144:145], v[88:89], s[44:45], v[144:145]
	v_pk_fma_f32 v[146:147], v[90:91], s[44:45], v[146:147]
	v_pk_fma_f32 v[148:149], v[92:93], s[44:45], v[148:149]
	v_pk_fma_f32 v[150:151], v[94:95], s[44:45], v[150:151]
	v_pk_add_f32 v[152:153], v[136:137], v[138:139]
	v_pk_add_f32 v[152:153], v[152:153], v[140:141]
	v_pk_add_f32 v[152:153], v[152:153], v[142:143]
	v_pk_add_f32 v[152:153], v[152:153], v[144:145]
	v_pk_add_f32 v[152:153], v[152:153], v[146:147]
	v_pk_add_f32 v[152:153], v[152:153], v[148:149]
	v_pk_add_f32 v[152:153], v[152:153], v[150:151]
	v_add_f32_e32 v170, v152, v153
	s_nop 1
	v_add_f32_dpp v168, v170, v170 quad_perm:[1,0,3,2] row_mask:0xf bank_mask:0xf
	s_nop 1
	v_add_f32_dpp v168, v168, v168 quad_perm:[2,3,0,1] row_mask:0xf bank_mask:0xf
	s_nop 1
	v_add_f32_dpp v168, v168, v168 row_half_mirror row_mask:0xf bank_mask:0xf
	s_nop 1
	v_add_f32_dpp v168, v168, v168 row_mirror row_mask:0xf bank_mask:0xf
	s_nop 1
	v_add_f32_dpp v168, v168, v168 row_bcast:15 row_mask:0xa bank_mask:0xf
	s_nop 1
	v_add_f32_dpp v168, v168, v168 row_bcast:31 row_mask:0xc bank_mask:0xf
	s_nop 1
	v_readlane_b32 s42, v168, 63
	s_nop 3
	s_mov_b32 s43, s42
	v_pk_fma_f32 v[136:137], s[42:43], v[172:173], v[136:137]
	v_pk_fma_f32 v[138:139], s[42:43], v[172:173], v[138:139]
	v_pk_fma_f32 v[140:141], s[42:43], v[172:173], v[140:141]
	v_pk_fma_f32 v[142:143], s[42:43], v[172:173], v[142:143]
	v_pk_fma_f32 v[144:145], s[42:43], v[172:173], v[144:145]
	v_pk_fma_f32 v[146:147], s[42:43], v[172:173], v[146:147]
	v_pk_fma_f32 v[148:149], s[42:43], v[172:173], v[148:149]
	v_pk_fma_f32 v[150:151], s[42:43], v[172:173], v[150:151]
	v_pk_mul_f32 v[152:153], v[136:137], v[136:137]
	v_pk_fma_f32 v[152:153], v[138:139], v[138:139], v[152:153]
	v_pk_fma_f32 v[152:153], v[140:141], v[140:141], v[152:153]
	v_pk_fma_f32 v[152:153], v[142:143], v[142:143], v[152:153]
	v_pk_fma_f32 v[152:153], v[144:145], v[144:145], v[152:153]
	v_pk_fma_f32 v[152:153], v[146:147], v[146:147], v[152:153]
	v_pk_fma_f32 v[152:153], v[148:149], v[148:149], v[152:153]
	v_pk_fma_f32 v[152:153], v[150:151], v[150:151], v[152:153]
	v_add_f32_e32 v170, v152, v153
	s_nop 1
	v_add_f32_dpp v168, v170, v170 quad_perm:[1,0,3,2] row_mask:0xf bank_mask:0xf
	s_nop 1
	v_add_f32_dpp v168, v168, v168 quad_perm:[2,3,0,1] row_mask:0xf bank_mask:0xf
	s_nop 1
	v_add_f32_dpp v168, v168, v168 row_half_mirror row_mask:0xf bank_mask:0xf
	s_nop 1
	v_add_f32_dpp v168, v168, v168 row_mirror row_mask:0xf bank_mask:0xf
	s_nop 1
	v_add_f32_dpp v168, v168, v168 row_bcast:15 row_mask:0xa bank_mask:0xf
	s_nop 1
	v_add_f32_dpp v168, v168, v168 row_bcast:31 row_mask:0xc bank_mask:0xf
	s_nop 1
	v_readlane_b32 s42, v168, 63
	s_nop 3
	v_fma_f32 v174, s42, v178, v179
	v_rsq_f32_e32 v174, v174
	s_nop 0
	v_pk_mul_f32 v[136:137], v[136:137], v[174:175] op_sel_hi:[1,0]
	v_pk_mul_f32 v[138:139], v[138:139], v[174:175] op_sel_hi:[1,0]
	v_pk_mul_f32 v[140:141], v[140:141], v[174:175] op_sel_hi:[1,0]
	v_pk_mul_f32 v[142:143], v[142:143], v[174:175] op_sel_hi:[1,0]
	v_pk_mul_f32 v[144:145], v[144:145], v[174:175] op_sel_hi:[1,0]
	v_pk_mul_f32 v[146:147], v[146:147], v[174:175] op_sel_hi:[1,0]
	v_pk_mul_f32 v[148:149], v[148:149], v[174:175] op_sel_hi:[1,0]
	v_pk_mul_f32 v[150:151], v[150:151], v[174:175] op_sel_hi:[1,0]
	v_pk_fma_f32 v[136:137], v[136:137], v[0:1], v[16:17]
	v_pk_fma_f32 v[138:139], v[138:139], v[2:3], v[18:19]
	v_pk_fma_f32 v[140:141], v[140:141], v[4:5], v[20:21]
	v_pk_fma_f32 v[142:143], v[142:143], v[6:7], v[22:23]
	v_pk_fma_f32 v[144:145], v[144:145], v[8:9], v[24:25]
	v_pk_fma_f32 v[146:147], v[146:147], v[10:11], v[26:27]
	v_pk_fma_f32 v[148:149], v[148:149], v[12:13], v[28:29]
	v_pk_fma_f32 v[150:151], v[150:151], v[14:15], v[30:31]
	global_store_dwordx4 v176, v[136:139], s[8:9] offset:0
	global_store_dwordx4 v176, v[140:143], s[8:9] offset:1024
	global_store_dwordx4 v176, v[144:147], s[8:9] offset:2048
	global_store_dwordx4 v176, v[148:151], s[8:9] offset:3072
	v_pk_add_f32 v[152:153], v[136:137], v[138:139]
	v_pk_add_f32 v[152:153], v[152:153], v[140:141]
	v_pk_add_f32 v[152:153], v[152:153], v[142:143]
	v_pk_add_f32 v[152:153], v[152:153], v[144:145]
	v_pk_add_f32 v[152:153], v[152:153], v[146:147]
	v_pk_add_f32 v[152:153], v[152:153], v[148:149]
	v_pk_add_f32 v[152:153], v[152:153], v[150:151]
	v_add_f32_e32 v170, v152, v153
	s_nop 1
	v_add_f32_dpp v168, v170, v170 quad_perm:[1,0,3,2] row_mask:0xf bank_mask:0xf
	s_nop 1
	v_add_f32_dpp v168, v168, v168 quad_perm:[2,3,0,1] row_mask:0xf bank_mask:0xf
	s_nop 1
	v_add_f32_dpp v168, v168, v168 row_half_mirror row_mask:0xf bank_mask:0xf
	s_nop 1
	v_add_f32_dpp v168, v168, v168 row_mirror row_mask:0xf bank_mask:0xf
	s_nop 1
	v_add_f32_dpp v168, v168, v168 row_bcast:15 row_mask:0xa bank_mask:0xf
	s_nop 1
	v_add_f32_dpp v168, v168, v168 row_bcast:31 row_mask:0xc bank_mask:0xf
	s_nop 1
	v_readlane_b32 s42, v168, 63
	s_nop 3
	s_mov_b32 s43, s42
	v_pk_fma_f32 v[136:137], s[42:43], v[172:173], v[136:137]
	v_pk_fma_f32 v[138:139], s[42:43], v[172:173], v[138:139]
	v_pk_fma_f32 v[140:141], s[42:43], v[172:173], v[140:141]
	v_pk_fma_f32 v[142:143], s[42:43], v[172:173], v[142:143]
	v_pk_fma_f32 v[144:145], s[42:43], v[172:173], v[144:145]
	v_pk_fma_f32 v[146:147], s[42:43], v[172:173], v[146:147]
	v_pk_fma_f32 v[148:149], s[42:43], v[172:173], v[148:149]
	v_pk_fma_f32 v[150:151], s[42:43], v[172:173], v[150:151]
	v_pk_mul_f32 v[152:153], v[136:137], v[136:137]
	v_pk_fma_f32 v[152:153], v[138:139], v[138:139], v[152:153]
	v_pk_fma_f32 v[152:153], v[140:141], v[140:141], v[152:153]
	v_pk_fma_f32 v[152:153], v[142:143], v[142:143], v[152:153]
	v_pk_fma_f32 v[152:153], v[144:145], v[144:145], v[152:153]
	v_pk_fma_f32 v[152:153], v[146:147], v[146:147], v[152:153]
	v_pk_fma_f32 v[152:153], v[148:149], v[148:149], v[152:153]
	v_pk_fma_f32 v[152:153], v[150:151], v[150:151], v[152:153]
	v_add_f32_e32 v170, v152, v153
	s_nop 1
	v_add_f32_dpp v168, v170, v170 quad_perm:[1,0,3,2] row_mask:0xf bank_mask:0xf
	s_nop 1
	v_add_f32_dpp v168, v168, v168 quad_perm:[2,3,0,1] row_mask:0xf bank_mask:0xf
	s_nop 1
	v_add_f32_dpp v168, v168, v168 row_half_mirror row_mask:0xf bank_mask:0xf
	s_nop 1
	v_add_f32_dpp v168, v168, v168 row_mirror row_mask:0xf bank_mask:0xf
	s_nop 1
	v_add_f32_dpp v168, v168, v168 row_bcast:15 row_mask:0xa bank_mask:0xf
	s_nop 1
	v_add_f32_dpp v168, v168, v168 row_bcast:31 row_mask:0xc bank_mask:0xf
	s_nop 1
	v_readlane_b32 s42, v168, 63
	s_nop 3
	v_fma_f32 v174, s42, v178, v179
	v_rsq_f32_e32 v174, v174
	s_nop 0
	v_pk_mul_f32 v[136:137], v[136:137], v[174:175] op_sel_hi:[1,0]
	v_pk_mul_f32 v[138:139], v[138:139], v[174:175] op_sel_hi:[1,0]
	v_pk_mul_f32 v[140:141], v[140:141], v[174:175] op_sel_hi:[1,0]
	v_pk_mul_f32 v[142:143], v[142:143], v[174:175] op_sel_hi:[1,0]
	v_pk_mul_f32 v[144:145], v[144:145], v[174:175] op_sel_hi:[1,0]
	v_pk_mul_f32 v[146:147], v[146:147], v[174:175] op_sel_hi:[1,0]
	v_pk_mul_f32 v[148:149], v[148:149], v[174:175] op_sel_hi:[1,0]
	v_pk_mul_f32 v[150:151], v[150:151], v[174:175] op_sel_hi:[1,0]
	v_pk_fma_f32 v[136:137], v[136:137], v[32:33], v[48:49]
	v_pk_fma_f32 v[138:139], v[138:139], v[34:35], v[50:51]
	v_pk_fma_f32 v[140:141], v[140:141], v[36:37], v[52:53]
	v_pk_fma_f32 v[142:143], v[142:143], v[38:39], v[54:55]
	v_pk_fma_f32 v[144:145], v[144:145], v[40:41], v[56:57]
	v_pk_fma_f32 v[146:147], v[146:147], v[42:43], v[58:59]
	v_pk_fma_f32 v[148:149], v[148:149], v[44:45], v[60:61]
	v_pk_fma_f32 v[150:151], v[150:151], v[46:47], v[62:63]
	v_cvt_pk_bf16_f32 v152, v136, v137
	v_cvt_pk_bf16_f32 v153, v138, v139
	v_cvt_pk_bf16_f32 v154, v140, v141
	v_cvt_pk_bf16_f32 v155, v142, v143
	v_cvt_pk_bf16_f32 v156, v144, v145
	v_cvt_pk_bf16_f32 v157, v146, v147
	v_cvt_pk_bf16_f32 v158, v148, v149
	v_cvt_pk_bf16_f32 v159, v150, v151
	global_store_dwordx2 v177, v[152:153], s[12:13] offset:0
	global_store_dwordx2 v177, v[154:155], s[12:13] offset:512
	global_store_dwordx2 v177, v[156:157], s[12:13] offset:1024
	global_store_dwordx2 v177, v[158:159], s[12:13] offset:1536
	s_add_u32 s8, s8, 0x80000
	s_addc_u32 s9, s9, 0
	s_add_u32 s12, s12, 0x40000
	s_addc_u32 s13, s13, 0
	s_waitcnt vmcnt(24)
	v_lshlrev_b32_e32 v136, 16, v128
	v_and_b32_e32 v137, 0xffff0000, v128
	v_lshlrev_b32_e32 v138, 16, v129
	v_and_b32_e32 v139, 0xffff0000, v129
	v_lshlrev_b32_e32 v140, 16, v130
	v_and_b32_e32 v141, 0xffff0000, v130
	v_lshlrev_b32_e32 v142, 16, v131
	v_and_b32_e32 v143, 0xffff0000, v131
	v_lshlrev_b32_e32 v144, 16, v132
	v_and_b32_e32 v145, 0xffff0000, v132
	v_lshlrev_b32_e32 v146, 16, v133
	v_and_b32_e32 v147, 0xffff0000, v133
	v_lshlrev_b32_e32 v148, 16, v134
	v_and_b32_e32 v149, 0xffff0000, v134
	v_lshlrev_b32_e32 v150, 16, v135
	v_and_b32_e32 v151, 0xffff0000, v135
	v_pk_fma_f32 v[136:137], v[96:97], s[44:45], v[136:137]
	v_pk_fma_f32 v[138:139], v[98:99], s[44:45], v[138:139]
	v_pk_fma_f32 v[140:141], v[100:101], s[44:45], v[140:141]
	v_pk_fma_f32 v[142:143], v[102:103], s[44:45], v[142:143]
	v_pk_fma_f32 v[144:145], v[104:105], s[44:45], v[144:145]
	v_pk_fma_f32 v[146:147], v[106:107], s[44:45], v[146:147]
	v_pk_fma_f32 v[148:149], v[108:109], s[44:45], v[148:149]
	v_pk_fma_f32 v[150:151], v[110:111], s[44:45], v[150:151]
	v_pk_add_f32 v[152:153], v[136:137], v[138:139]
	v_pk_add_f32 v[152:153], v[152:153], v[140:141]
	v_pk_add_f32 v[152:153], v[152:153], v[142:143]
	v_pk_add_f32 v[152:153], v[152:153], v[144:145]
	v_pk_add_f32 v[152:153], v[152:153], v[146:147]
	v_pk_add_f32 v[152:153], v[152:153], v[148:149]
	v_pk_add_f32 v[152:153], v[152:153], v[150:151]
	v_add_f32_e32 v170, v152, v153
	s_nop 1
	v_add_f32_dpp v168, v170, v170 quad_perm:[1,0,3,2] row_mask:0xf bank_mask:0xf
	s_nop 1
	v_add_f32_dpp v168, v168, v168 quad_perm:[2,3,0,1] row_mask:0xf bank_mask:0xf
	s_nop 1
	v_add_f32_dpp v168, v168, v168 row_half_mirror row_mask:0xf bank_mask:0xf
	s_nop 1
	v_add_f32_dpp v168, v168, v168 row_mirror row_mask:0xf bank_mask:0xf
	s_nop 1
	v_add_f32_dpp v168, v168, v168 row_bcast:15 row_mask:0xa bank_mask:0xf
	s_nop 1
	v_add_f32_dpp v168, v168, v168 row_bcast:31 row_mask:0xc bank_mask:0xf
	s_nop 1
	v_readlane_b32 s42, v168, 63
	s_nop 3
	s_mov_b32 s43, s42
	v_pk_fma_f32 v[136:137], s[42:43], v[172:173], v[136:137]
	v_pk_fma_f32 v[138:139], s[42:43], v[172:173], v[138:139]
	v_pk_fma_f32 v[140:141], s[42:43], v[172:173], v[140:141]
	v_pk_fma_f32 v[142:143], s[42:43], v[172:173], v[142:143]
	v_pk_fma_f32 v[144:145], s[42:43], v[172:173], v[144:145]
	v_pk_fma_f32 v[146:147], s[42:43], v[172:173], v[146:147]
	v_pk_fma_f32 v[148:149], s[42:43], v[172:173], v[148:149]
	v_pk_fma_f32 v[150:151], s[42:43], v[172:173], v[150:151]
	v_pk_mul_f32 v[152:153], v[136:137], v[136:137]
	v_pk_fma_f32 v[152:153], v[138:139], v[138:139], v[152:153]
	v_pk_fma_f32 v[152:153], v[140:141], v[140:141], v[152:153]
	v_pk_fma_f32 v[152:153], v[142:143], v[142:143], v[152:153]
	v_pk_fma_f32 v[152:153], v[144:145], v[144:145], v[152:153]
	v_pk_fma_f32 v[152:153], v[146:147], v[146:147], v[152:153]
	v_pk_fma_f32 v[152:153], v[148:149], v[148:149], v[152:153]
	v_pk_fma_f32 v[152:153], v[150:151], v[150:151], v[152:153]
	v_add_f32_e32 v170, v152, v153
	s_nop 1
	v_add_f32_dpp v168, v170, v170 quad_perm:[1,0,3,2] row_mask:0xf bank_mask:0xf
	s_nop 1
	v_add_f32_dpp v168, v168, v168 quad_perm:[2,3,0,1] row_mask:0xf bank_mask:0xf
	s_nop 1
	v_add_f32_dpp v168, v168, v168 row_half_mirror row_mask:0xf bank_mask:0xf
	s_nop 1
	v_add_f32_dpp v168, v168, v168 row_mirror row_mask:0xf bank_mask:0xf
	s_nop 1
	v_add_f32_dpp v168, v168, v168 row_bcast:15 row_mask:0xa bank_mask:0xf
	s_nop 1
	v_add_f32_dpp v168, v168, v168 row_bcast:31 row_mask:0xc bank_mask:0xf
	s_nop 1
	v_readlane_b32 s42, v168, 63
	s_nop 3
	v_fma_f32 v174, s42, v178, v179
	v_rsq_f32_e32 v174, v174
	s_nop 0
	v_pk_mul_f32 v[136:137], v[136:137], v[174:175] op_sel_hi:[1,0]
	v_pk_mul_f32 v[138:139], v[138:139], v[174:175] op_sel_hi:[1,0]
	v_pk_mul_f32 v[140:141], v[140:141], v[174:175] op_sel_hi:[1,0]
	v_pk_mul_f32 v[142:143], v[142:143], v[174:175] op_sel_hi:[1,0]
	v_pk_mul_f32 v[144:145], v[144:145], v[174:175] op_sel_hi:[1,0]
	v_pk_mul_f32 v[146:147], v[146:147], v[174:175] op_sel_hi:[1,0]
	v_pk_mul_f32 v[148:149], v[148:149], v[174:175] op_sel_hi:[1,0]
	v_pk_mul_f32 v[150:151], v[150:151], v[174:175] op_sel_hi:[1,0]
	v_pk_fma_f32 v[136:137], v[136:137], v[0:1], v[16:17]
	v_pk_fma_f32 v[138:139], v[138:139], v[2:3], v[18:19]
	v_pk_fma_f32 v[140:141], v[140:141], v[4:5], v[20:21]
	v_pk_fma_f32 v[142:143], v[142:143], v[6:7], v[22:23]
	v_pk_fma_f32 v[144:145], v[144:145], v[8:9], v[24:25]
	v_pk_fma_f32 v[146:147], v[146:147], v[10:11], v[26:27]
	v_pk_fma_f32 v[148:149], v[148:149], v[12:13], v[28:29]
	v_pk_fma_f32 v[150:151], v[150:151], v[14:15], v[30:31]
	global_store_dwordx4 v176, v[136:139], s[8:9] offset:0
	global_store_dwordx4 v176, v[140:143], s[8:9] offset:1024
	global_store_dwordx4 v176, v[144:147], s[8:9] offset:2048
	global_store_dwordx4 v176, v[148:151], s[8:9] offset:3072
	v_pk_add_f32 v[152:153], v[136:137], v[138:139]
	v_pk_add_f32 v[152:153], v[152:153], v[140:141]
	v_pk_add_f32 v[152:153], v[152:153], v[142:143]
	v_pk_add_f32 v[152:153], v[152:153], v[144:145]
	v_pk_add_f32 v[152:153], v[152:153], v[146:147]
	v_pk_add_f32 v[152:153], v[152:153], v[148:149]
	v_pk_add_f32 v[152:153], v[152:153], v[150:151]
	v_add_f32_e32 v170, v152, v153
	s_nop 1
	v_add_f32_dpp v168, v170, v170 quad_perm:[1,0,3,2] row_mask:0xf bank_mask:0xf
	s_nop 1
	v_add_f32_dpp v168, v168, v168 quad_perm:[2,3,0,1] row_mask:0xf bank_mask:0xf
	s_nop 1
	v_add_f32_dpp v168, v168, v168 row_half_mirror row_mask:0xf bank_mask:0xf
	s_nop 1
	v_add_f32_dpp v168, v168, v168 row_mirror row_mask:0xf bank_mask:0xf
	s_nop 1
	v_add_f32_dpp v168, v168, v168 row_bcast:15 row_mask:0xa bank_mask:0xf
	s_nop 1
	v_add_f32_dpp v168, v168, v168 row_bcast:31 row_mask:0xc bank_mask:0xf
	s_nop 1
	v_readlane_b32 s42, v168, 63
	s_nop 3
	s_mov_b32 s43, s42
	v_pk_fma_f32 v[136:137], s[42:43], v[172:173], v[136:137]
	v_pk_fma_f32 v[138:139], s[42:43], v[172:173], v[138:139]
	v_pk_fma_f32 v[140:141], s[42:43], v[172:173], v[140:141]
	v_pk_fma_f32 v[142:143], s[42:43], v[172:173], v[142:143]
	v_pk_fma_f32 v[144:145], s[42:43], v[172:173], v[144:145]
	v_pk_fma_f32 v[146:147], s[42:43], v[172:173], v[146:147]
	v_pk_fma_f32 v[148:149], s[42:43], v[172:173], v[148:149]
	v_pk_fma_f32 v[150:151], s[42:43], v[172:173], v[150:151]
	v_pk_mul_f32 v[152:153], v[136:137], v[136:137]
	v_pk_fma_f32 v[152:153], v[138:139], v[138:139], v[152:153]
	v_pk_fma_f32 v[152:153], v[140:141], v[140:141], v[152:153]
	v_pk_fma_f32 v[152:153], v[142:143], v[142:143], v[152:153]
	v_pk_fma_f32 v[152:153], v[144:145], v[144:145], v[152:153]
	v_pk_fma_f32 v[152:153], v[146:147], v[146:147], v[152:153]
	v_pk_fma_f32 v[152:153], v[148:149], v[148:149], v[152:153]
	v_pk_fma_f32 v[152:153], v[150:151], v[150:151], v[152:153]
	v_add_f32_e32 v170, v152, v153
	s_nop 1
	v_add_f32_dpp v168, v170, v170 quad_perm:[1,0,3,2] row_mask:0xf bank_mask:0xf
	s_nop 1
	v_add_f32_dpp v168, v168, v168 quad_perm:[2,3,0,1] row_mask:0xf bank_mask:0xf
	s_nop 1
	v_add_f32_dpp v168, v168, v168 row_half_mirror row_mask:0xf bank_mask:0xf
	s_nop 1
	v_add_f32_dpp v168, v168, v168 row_mirror row_mask:0xf bank_mask:0xf
	s_nop 1
	v_add_f32_dpp v168, v168, v168 row_bcast:15 row_mask:0xa bank_mask:0xf
	s_nop 1
	v_add_f32_dpp v168, v168, v168 row_bcast:31 row_mask:0xc bank_mask:0xf
	s_nop 1
	v_readlane_b32 s42, v168, 63
	s_nop 3
	v_fma_f32 v174, s42, v178, v179
	v_rsq_f32_e32 v174, v174
	s_nop 0
	v_pk_mul_f32 v[136:137], v[136:137], v[174:175] op_sel_hi:[1,0]
	v_pk_mul_f32 v[138:139], v[138:139], v[174:175] op_sel_hi:[1,0]
	v_pk_mul_f32 v[140:141], v[140:141], v[174:175] op_sel_hi:[1,0]
	v_pk_mul_f32 v[142:143], v[142:143], v[174:175] op_sel_hi:[1,0]
	v_pk_mul_f32 v[144:145], v[144:145], v[174:175] op_sel_hi:[1,0]
	v_pk_mul_f32 v[146:147], v[146:147], v[174:175] op_sel_hi:[1,0]
	v_pk_mul_f32 v[148:149], v[148:149], v[174:175] op_sel_hi:[1,0]
	v_pk_mul_f32 v[150:151], v[150:151], v[174:175] op_sel_hi:[1,0]
	v_pk_fma_f32 v[136:137], v[136:137], v[32:33], v[48:49]
	v_pk_fma_f32 v[138:139], v[138:139], v[34:35], v[50:51]
	v_pk_fma_f32 v[140:141], v[140:141], v[36:37], v[52:53]
	v_pk_fma_f32 v[142:143], v[142:143], v[38:39], v[54:55]
	v_pk_fma_f32 v[144:145], v[144:145], v[40:41], v[56:57]
	v_pk_fma_f32 v[146:147], v[146:147], v[42:43], v[58:59]
	v_pk_fma_f32 v[148:149], v[148:149], v[44:45], v[60:61]
	v_pk_fma_f32 v[150:151], v[150:151], v[46:47], v[62:63]
	v_cvt_pk_bf16_f32 v152, v136, v137
	v_cvt_pk_bf16_f32 v153, v138, v139
	v_cvt_pk_bf16_f32 v154, v140, v141
	v_cvt_pk_bf16_f32 v155, v142, v143
	v_cvt_pk_bf16_f32 v156, v144, v145
	v_cvt_pk_bf16_f32 v157, v146, v147
	v_cvt_pk_bf16_f32 v158, v148, v149
	v_cvt_pk_bf16_f32 v159, v150, v151
	global_store_dwordx2 v177, v[152:153], s[12:13] offset:0
	global_store_dwordx2 v177, v[154:155], s[12:13] offset:512
	global_store_dwordx2 v177, v[156:157], s[12:13] offset:1024
	global_store_dwordx2 v177, v[158:159], s[12:13] offset:1536
	s_add_u32 s8, s8, 0x80000
	s_addc_u32 s9, s9, 0
	s_add_u32 s12, s12, 0x40000
	s_addc_u32 s13, s13, 0
	s_waitcnt vmcnt(16)
	v_lshlrev_b32_e32 v136, 16, v112
	v_and_b32_e32 v137, 0xffff0000, v112
	v_lshlrev_b32_e32 v138, 16, v113
	v_and_b32_e32 v139, 0xffff0000, v113
	v_lshlrev_b32_e32 v140, 16, v114
	v_and_b32_e32 v141, 0xffff0000, v114
	v_lshlrev_b32_e32 v142, 16, v115
	v_and_b32_e32 v143, 0xffff0000, v115
	v_lshlrev_b32_e32 v144, 16, v116
	v_and_b32_e32 v145, 0xffff0000, v116
	v_lshlrev_b32_e32 v146, 16, v117
	v_and_b32_e32 v147, 0xffff0000, v117
	v_lshlrev_b32_e32 v148, 16, v118
	v_and_b32_e32 v149, 0xffff0000, v118
	v_lshlrev_b32_e32 v150, 16, v119
	v_and_b32_e32 v151, 0xffff0000, v119
	v_pk_fma_f32 v[136:137], v[64:65], s[44:45], v[136:137]
	v_pk_fma_f32 v[138:139], v[66:67], s[44:45], v[138:139]
	v_pk_fma_f32 v[140:141], v[68:69], s[44:45], v[140:141]
	v_pk_fma_f32 v[142:143], v[70:71], s[44:45], v[142:143]
	v_pk_fma_f32 v[144:145], v[72:73], s[44:45], v[144:145]
	v_pk_fma_f32 v[146:147], v[74:75], s[44:45], v[146:147]
	v_pk_fma_f32 v[148:149], v[76:77], s[44:45], v[148:149]
	v_pk_fma_f32 v[150:151], v[78:79], s[44:45], v[150:151]
	v_pk_add_f32 v[152:153], v[136:137], v[138:139]
	v_pk_add_f32 v[152:153], v[152:153], v[140:141]
	v_pk_add_f32 v[152:153], v[152:153], v[142:143]
	v_pk_add_f32 v[152:153], v[152:153], v[144:145]
	v_pk_add_f32 v[152:153], v[152:153], v[146:147]
	v_pk_add_f32 v[152:153], v[152:153], v[148:149]
	v_pk_add_f32 v[152:153], v[152:153], v[150:151]
	v_add_f32_e32 v170, v152, v153
	s_nop 1
	v_add_f32_dpp v168, v170, v170 quad_perm:[1,0,3,2] row_mask:0xf bank_mask:0xf
	s_nop 1
	v_add_f32_dpp v168, v168, v168 quad_perm:[2,3,0,1] row_mask:0xf bank_mask:0xf
	s_nop 1
	v_add_f32_dpp v168, v168, v168 row_half_mirror row_mask:0xf bank_mask:0xf
	s_nop 1
	v_add_f32_dpp v168, v168, v168 row_mirror row_mask:0xf bank_mask:0xf
	s_nop 1
	v_add_f32_dpp v168, v168, v168 row_bcast:15 row_mask:0xa bank_mask:0xf
	s_nop 1
	v_add_f32_dpp v168, v168, v168 row_bcast:31 row_mask:0xc bank_mask:0xf
	s_nop 1
	v_readlane_b32 s42, v168, 63
	s_nop 3
	s_mov_b32 s43, s42
	v_pk_fma_f32 v[136:137], s[42:43], v[172:173], v[136:137]
	v_pk_fma_f32 v[138:139], s[42:43], v[172:173], v[138:139]
	v_pk_fma_f32 v[140:141], s[42:43], v[172:173], v[140:141]
	v_pk_fma_f32 v[142:143], s[42:43], v[172:173], v[142:143]
	v_pk_fma_f32 v[144:145], s[42:43], v[172:173], v[144:145]
	v_pk_fma_f32 v[146:147], s[42:43], v[172:173], v[146:147]
	v_pk_fma_f32 v[148:149], s[42:43], v[172:173], v[148:149]
	v_pk_fma_f32 v[150:151], s[42:43], v[172:173], v[150:151]
	v_pk_mul_f32 v[152:153], v[136:137], v[136:137]
	v_pk_fma_f32 v[152:153], v[138:139], v[138:139], v[152:153]
	v_pk_fma_f32 v[152:153], v[140:141], v[140:141], v[152:153]
	v_pk_fma_f32 v[152:153], v[142:143], v[142:143], v[152:153]
	v_pk_fma_f32 v[152:153], v[144:145], v[144:145], v[152:153]
	v_pk_fma_f32 v[152:153], v[146:147], v[146:147], v[152:153]
	v_pk_fma_f32 v[152:153], v[148:149], v[148:149], v[152:153]
	v_pk_fma_f32 v[152:153], v[150:151], v[150:151], v[152:153]
	v_add_f32_e32 v170, v152, v153
	s_nop 1
	v_add_f32_dpp v168, v170, v170 quad_perm:[1,0,3,2] row_mask:0xf bank_mask:0xf
	s_nop 1
	v_add_f32_dpp v168, v168, v168 quad_perm:[2,3,0,1] row_mask:0xf bank_mask:0xf
	s_nop 1
	v_add_f32_dpp v168, v168, v168 row_half_mirror row_mask:0xf bank_mask:0xf
	s_nop 1
	v_add_f32_dpp v168, v168, v168 row_mirror row_mask:0xf bank_mask:0xf
	s_nop 1
	v_add_f32_dpp v168, v168, v168 row_bcast:15 row_mask:0xa bank_mask:0xf
	s_nop 1
	v_add_f32_dpp v168, v168, v168 row_bcast:31 row_mask:0xc bank_mask:0xf
	s_nop 1
	v_readlane_b32 s42, v168, 63
	s_nop 3
	v_fma_f32 v174, s42, v178, v179
	v_rsq_f32_e32 v174, v174
	s_nop 0
	v_pk_mul_f32 v[136:137], v[136:137], v[174:175] op_sel_hi:[1,0]
	v_pk_mul_f32 v[138:139], v[138:139], v[174:175] op_sel_hi:[1,0]
	v_pk_mul_f32 v[140:141], v[140:141], v[174:175] op_sel_hi:[1,0]
	v_pk_mul_f32 v[142:143], v[142:143], v[174:175] op_sel_hi:[1,0]
	v_pk_mul_f32 v[144:145], v[144:145], v[174:175] op_sel_hi:[1,0]
	v_pk_mul_f32 v[146:147], v[146:147], v[174:175] op_sel_hi:[1,0]
	v_pk_mul_f32 v[148:149], v[148:149], v[174:175] op_sel_hi:[1,0]
	v_pk_mul_f32 v[150:151], v[150:151], v[174:175] op_sel_hi:[1,0]
	v_pk_fma_f32 v[136:137], v[136:137], v[0:1], v[16:17]
	v_pk_fma_f32 v[138:139], v[138:139], v[2:3], v[18:19]
	v_pk_fma_f32 v[140:141], v[140:141], v[4:5], v[20:21]
	v_pk_fma_f32 v[142:143], v[142:143], v[6:7], v[22:23]
	v_pk_fma_f32 v[144:145], v[144:145], v[8:9], v[24:25]
	v_pk_fma_f32 v[146:147], v[146:147], v[10:11], v[26:27]
	v_pk_fma_f32 v[148:149], v[148:149], v[12:13], v[28:29]
	v_pk_fma_f32 v[150:151], v[150:151], v[14:15], v[30:31]
	global_store_dwordx4 v176, v[136:139], s[8:9] offset:0
	global_store_dwordx4 v176, v[140:143], s[8:9] offset:1024
	global_store_dwordx4 v176, v[144:147], s[8:9] offset:2048
	global_store_dwordx4 v176, v[148:151], s[8:9] offset:3072
	v_pk_add_f32 v[152:153], v[136:137], v[138:139]
	v_pk_add_f32 v[152:153], v[152:153], v[140:141]
	v_pk_add_f32 v[152:153], v[152:153], v[142:143]
	v_pk_add_f32 v[152:153], v[152:153], v[144:145]
	v_pk_add_f32 v[152:153], v[152:153], v[146:147]
	v_pk_add_f32 v[152:153], v[152:153], v[148:149]
	v_pk_add_f32 v[152:153], v[152:153], v[150:151]
	v_add_f32_e32 v170, v152, v153
	s_nop 1
	v_add_f32_dpp v168, v170, v170 quad_perm:[1,0,3,2] row_mask:0xf bank_mask:0xf
	s_nop 1
	v_add_f32_dpp v168, v168, v168 quad_perm:[2,3,0,1] row_mask:0xf bank_mask:0xf
	s_nop 1
	v_add_f32_dpp v168, v168, v168 row_half_mirror row_mask:0xf bank_mask:0xf
	s_nop 1
	v_add_f32_dpp v168, v168, v168 row_mirror row_mask:0xf bank_mask:0xf
	s_nop 1
	v_add_f32_dpp v168, v168, v168 row_bcast:15 row_mask:0xa bank_mask:0xf
	s_nop 1
	v_add_f32_dpp v168, v168, v168 row_bcast:31 row_mask:0xc bank_mask:0xf
	s_nop 1
	v_readlane_b32 s42, v168, 63
	s_nop 3
	s_mov_b32 s43, s42
	v_pk_fma_f32 v[136:137], s[42:43], v[172:173], v[136:137]
	v_pk_fma_f32 v[138:139], s[42:43], v[172:173], v[138:139]
	v_pk_fma_f32 v[140:141], s[42:43], v[172:173], v[140:141]
	v_pk_fma_f32 v[142:143], s[42:43], v[172:173], v[142:143]
	v_pk_fma_f32 v[144:145], s[42:43], v[172:173], v[144:145]
	v_pk_fma_f32 v[146:147], s[42:43], v[172:173], v[146:147]
	v_pk_fma_f32 v[148:149], s[42:43], v[172:173], v[148:149]
	v_pk_fma_f32 v[150:151], s[42:43], v[172:173], v[150:151]
	v_pk_mul_f32 v[152:153], v[136:137], v[136:137]
	v_pk_fma_f32 v[152:153], v[138:139], v[138:139], v[152:153]
	v_pk_fma_f32 v[152:153], v[140:141], v[140:141], v[152:153]
	v_pk_fma_f32 v[152:153], v[142:143], v[142:143], v[152:153]
	v_pk_fma_f32 v[152:153], v[144:145], v[144:145], v[152:153]
	v_pk_fma_f32 v[152:153], v[146:147], v[146:147], v[152:153]
	v_pk_fma_f32 v[152:153], v[148:149], v[148:149], v[152:153]
	v_pk_fma_f32 v[152:153], v[150:151], v[150:151], v[152:153]
	v_add_f32_e32 v170, v152, v153
	s_nop 1
	v_add_f32_dpp v168, v170, v170 quad_perm:[1,0,3,2] row_mask:0xf bank_mask:0xf
	s_nop 1
	v_add_f32_dpp v168, v168, v168 quad_perm:[2,3,0,1] row_mask:0xf bank_mask:0xf
	s_nop 1
	v_add_f32_dpp v168, v168, v168 row_half_mirror row_mask:0xf bank_mask:0xf
	s_nop 1
	v_add_f32_dpp v168, v168, v168 row_mirror row_mask:0xf bank_mask:0xf
	s_nop 1
	v_add_f32_dpp v168, v168, v168 row_bcast:15 row_mask:0xa bank_mask:0xf
	s_nop 1
	v_add_f32_dpp v168, v168, v168 row_bcast:31 row_mask:0xc bank_mask:0xf
	s_nop 1
	v_readlane_b32 s42, v168, 63
	s_nop 3
	v_fma_f32 v174, s42, v178, v179
	v_rsq_f32_e32 v174, v174
	s_nop 0
	v_pk_mul_f32 v[136:137], v[136:137], v[174:175] op_sel_hi:[1,0]
	v_pk_mul_f32 v[138:139], v[138:139], v[174:175] op_sel_hi:[1,0]
	v_pk_mul_f32 v[140:141], v[140:141], v[174:175] op_sel_hi:[1,0]
	v_pk_mul_f32 v[142:143], v[142:143], v[174:175] op_sel_hi:[1,0]
	v_pk_mul_f32 v[144:145], v[144:145], v[174:175] op_sel_hi:[1,0]
	v_pk_mul_f32 v[146:147], v[146:147], v[174:175] op_sel_hi:[1,0]
	v_pk_mul_f32 v[148:149], v[148:149], v[174:175] op_sel_hi:[1,0]
	v_pk_mul_f32 v[150:151], v[150:151], v[174:175] op_sel_hi:[1,0]
	v_pk_fma_f32 v[136:137], v[136:137], v[32:33], v[48:49]
	v_pk_fma_f32 v[138:139], v[138:139], v[34:35], v[50:51]
	v_pk_fma_f32 v[140:141], v[140:141], v[36:37], v[52:53]
	v_pk_fma_f32 v[142:143], v[142:143], v[38:39], v[54:55]
	v_pk_fma_f32 v[144:145], v[144:145], v[40:41], v[56:57]
	v_pk_fma_f32 v[146:147], v[146:147], v[42:43], v[58:59]
	v_pk_fma_f32 v[148:149], v[148:149], v[44:45], v[60:61]
	v_pk_fma_f32 v[150:151], v[150:151], v[46:47], v[62:63]
	v_cvt_pk_bf16_f32 v152, v136, v137
	v_cvt_pk_bf16_f32 v153, v138, v139
	v_cvt_pk_bf16_f32 v154, v140, v141
	v_cvt_pk_bf16_f32 v155, v142, v143
	v_cvt_pk_bf16_f32 v156, v144, v145
	v_cvt_pk_bf16_f32 v157, v146, v147
	v_cvt_pk_bf16_f32 v158, v148, v149
	v_cvt_pk_bf16_f32 v159, v150, v151
	global_store_dwordx2 v177, v[152:153], s[12:13] offset:0
	global_store_dwordx2 v177, v[154:155], s[12:13] offset:512
	global_store_dwordx2 v177, v[156:157], s[12:13] offset:1024
	global_store_dwordx2 v177, v[158:159], s[12:13] offset:1536
	s_add_u32 s8, s8, 0x80000
	s_addc_u32 s9, s9, 0
	s_add_u32 s12, s12, 0x40000
	s_addc_u32 s13, s13, 0
	s_mov_b64 s[16:17], 0x1000
	s_mov_b32 s18, 0x800000
	s_mov_b32 s19, 0xec00000
	s_mov_b32 s20, 0x2400000
	s_add_u32 s28, s90, 0x21b3000
	s_addc_u32 s29, s91, 0
	s_mov_b32 s15, 0x8000
	s_mov_b32 s14, 0x3fb504f3
